# attention-A loop priorities refined: MFMA segments (QK, PV) at s_setprio 1, the VALU-only exp block and the LDS write/barrier segment at 0
# speedup vs baseline: 1.0463x; 1.0200x over previous
; #define MFMA32(a, b, c) __builtin_amdgcn_mfma_f32_32x32x16_bf16((a), (b), (c), 0, 0, 0)
; __device__ __forceinline__ void attn_item_A(const Params& p, int layer, int head, int q0u, char* lds) {
;     ...
;   for (int t = 0; t < ntiles; ++t) {
;     const int buf = t & 1;
;     const bool more = (t + 1 < ntiles);
;     if (more) { ATT_LOADK(t + 1); ATT_LOADV(t + 1); }
;     const u16* kt_ = Ks + buf * 32 * KLD + r * KLD + 8 * h;
;     bf16x8 a0, a1, b0, b1;
;     {
;       f32x16 sx, sy;
; #pragma unroll
;       for (int e = 0; e < 16; ++e) { sx[e] = 0.f; sy[e] = 0.f; }
; #pragma unroll
;       for (int s = 0; s < 4; ++s) {
;         const bf16x8 kf = *(const bf16x8*)(kt_ + 16 * s);
;         const bf16x8 qf = *(const bf16x8*)(Qs + s * 1024);
;         sx = MFMA32(kf, qf, sx);
;       }
; #pragma unroll
;       for (int s = 4; s < 8; ++s) {
;         const bf16x8 kf = *(const bf16x8*)(kt_ + 16 * s);
;         const bf16x8 qf = *(const bf16x8*)(Qs + s * 1024);
;         sy = MFMA32(kf, qf, sy);
;       }
;       {
;         float w[16];
; #pragma unroll
;         for (int e = 0; e < 16; ++e) { w[e] = __builtin_amdgcn_exp2f(fmaf(sx[e], CS, -bA)); lA += w[e]; }
;         const u32x4 p0 = {pk2(w[0], w[1]), pk2(w[2], w[3]), pk2(w[4], w[5]), pk2(w[6], w[7])};
;         const u32x4 p1 = {pk2(w[8], w[9]), pk2(w[10], w[11]), pk2(w[12], w[13]), pk2(w[14], w[15])};
;         a0 = __builtin_bit_cast(bf16x8, p0); a1 = __builtin_bit_cast(bf16x8, p1);
;       }
;       {
;         float w[16];
; #pragma unroll
;         for (int e = 0; e < 16; ++e) { w[e] = __builtin_amdgcn_exp2f(fmaf(sy[e], CS, -bB)); lB += w[e]; }
;         const u32x4 p0 = {pk2(w[0], w[1]), pk2(w[2], w[3]), pk2(w[4], w[5]), pk2(w[6], w[7])};
;         const u32x4 p1 = {pk2(w[8], w[9]), pk2(w[10], w[11]), pk2(w[12], w[13]), pk2(w[14], w[15])};
;         b0 = __builtin_bit_cast(bf16x8, p0); b1 = __builtin_bit_cast(bf16x8, p1);
;       }
;     }
;     const u16* vt = Vt + buf * 128 * VLD + r * VLD + 4 * h;
; #pragma unroll
;     for (int d = 0; d < 4; d += 2) {
;       const s16x4 l0 = *(const s16x4*)(vt + d * 32 * VLD), h0 = *(const s16x4*)(vt + d * 32 * VLD + 8);
;       const s16x4 l1 = *(const s16x4*)(vt + d * 32 * VLD + 16), h1 = *(const s16x4*)(vt + d * 32 * VLD + 24);
;       const s16x4 m0 = *(const s16x4*)(vt + (d + 1) * 32 * VLD), n0 = *(const s16x4*)(vt + (d + 1) * 32 * VLD + 8);
.LBB0_1571:
	s_setprio 1
	s_and_b32 s1, s8, 1
	s_mul_i32 s7, s1, 0x2200
	v_add_u32_e32 v197, v193, v194
	v_add_u32_e32 v210, s7, v196
	ds_read_b128 v[128:131], v197 offset:37888
	ds_read_b128 v[160:163], v197 offset:38912
	ds_read_b128 v[144:147], v197 offset:41984
	ds_read_b128 v[178:181], v197 offset:43008
	ds_read_b128 v[132:135], v210
	ds_read_b128 v[198:201], v210 offset:32
	ds_read_b128 v[148:151], v210 offset:128
	ds_read_b128 v[202:205], v210 offset:160
	ds_read_b128 v[206:209], v210 offset:64
	ds_read_b128 v[216:219], v210 offset:96
	ds_read_b128 v[220:223], v210 offset:192
	ds_read_b128 v[224:227], v210 offset:224
	s_waitcnt lgkmcnt(7)
	v_mfma_f32_32x32x16_bf16 v[128:143], v[132:135], v[128:131], 0
	s_ashr_i32 s7, s6, 31
	s_add_i32 s8, s8, 1
	s_waitcnt lgkmcnt(5)
	v_mfma_f32_32x32x16_bf16 v[144:159], v[148:151], v[144:147], 0
	v_mfma_f32_32x32x16_bf16 v[128:143], v[198:201], v[160:163], v[128:143]
	s_waitcnt lgkmcnt(4)
	v_mfma_f32_32x32x16_bf16 v[144:159], v[202:205], v[178:181], v[144:159]
	s_waitcnt lgkmcnt(3)
	v_mfma_f32_32x32x16_bf16 v[128:143], v[206:209], v[240:243], v[128:143]
	v_lshl_add_u64 v[178:179], s[6:7], 1, v[170:171]
	s_mul_i32 s7, s1, 0x2400
	v_add_u32_e32 v210, s7, v175
	v_add_u32_e32 v212, 0x4000, v210
	v_add_u32_e32 v215, 0x4800, v210
	v_add_u32_e32 v238, 0x5000, v210
	s_waitcnt lgkmcnt(1)
	v_mfma_f32_32x32x16_bf16 v[144:159], v[220:223], v[248:251], v[144:159]
	v_add_u32_e32 v160, s6, v195
	v_mad_i64_i32 v[180:181], s[10:11], v160, s63, v[176:177]
	global_load_dwordx4 v[160:163], v[180:181], off offset:1040
	v_add_u32_e32 v210, 0x5800, v210
	s_xor_b32 s1, s1, 1
	s_add_i32 s6, s6, 32
	v_mfma_f32_32x32x16_bf16 v[128:143], v[216:219], v[244:247], v[128:143]
	ds_read2_b64 v[198:201], v212 offset0:128 offset1:130
	s_mul_i32 s7, s1, 0x2200
	s_mulk_i32 s1, 0x2400
	s_cmp_eq_u32 s0, s8
	s_waitcnt lgkmcnt(1)
	v_mfma_f32_32x32x16_bf16 v[144:159], v[224:227], v[252:255], v[144:159]
	s_setprio 0
	s_nop 5
	v_fmamk_f32 v128, v128, 0x3e38aa3b, v173
	v_fmamk_f32 v129, v129, 0x3e38aa3b, v173
	v_fmamk_f32 v130, v130, 0x3e38aa3b, v173
	v_fmamk_f32 v131, v131, 0x3e38aa3b, v173
	v_fmamk_f32 v132, v132, 0x3e38aa3b, v173
	v_fmamk_f32 v133, v133, 0x3e38aa3b, v173
	v_fmamk_f32 v202, v134, 0x3e38aa3b, v173
	v_fmamk_f32 v135, v135, 0x3e38aa3b, v173
	v_fmamk_f32 v203, v144, 0x3e38aa3b, v164
	v_fmamk_f32 v145, v145, 0x3e38aa3b, v164
	v_fmamk_f32 v204, v146, 0x3e38aa3b, v164
	v_fmamk_f32 v205, v147, 0x3e38aa3b, v164
	v_fmamk_f32 v206, v148, 0x3e38aa3b, v164
	v_fmamk_f32 v207, v149, 0x3e38aa3b, v164
	v_fmamk_f32 v208, v150, 0x3e38aa3b, v164
	v_fmamk_f32 v209, v151, 0x3e38aa3b, v164
	v_exp_f32_e32 v150, v128
	v_exp_f32_e32 v148, v129
	v_exp_f32_e32 v146, v130
	v_exp_f32_e32 v144, v131
	v_exp_f32_e32 v134, v132
	v_exp_f32_e32 v130, v133
	v_exp_f32_e32 v132, v202
	v_exp_f32_e32 v128, v135
	v_exp_f32_e32 v151, v203
	v_exp_f32_e32 v149, v145
	v_exp_f32_e32 v147, v204
	v_exp_f32_e32 v145, v205
	v_exp_f32_e32 v135, v206
	v_exp_f32_e32 v131, v207
	v_exp_f32_e32 v133, v208
	v_exp_f32_e32 v129, v209
	v_cvt_pk_bf16_f32 v202, v150, v148
	v_cvt_pk_bf16_f32 v203, v146, v144
	v_cvt_pk_bf16_f32 v204, v134, v130
	v_cvt_pk_bf16_f32 v205, v132, v128
	v_cvt_pk_bf16_f32 v206, v151, v149
	v_cvt_pk_bf16_f32 v207, v147, v145
	v_cvt_pk_bf16_f32 v208, v135, v131
	v_cvt_pk_bf16_f32 v209, v133, v129
	s_setprio 1
	s_waitcnt lgkmcnt(0)
	v_mfma_f32_32x32x16_bf16 v[64:79], v[202:205], v[198:201], v[64:79]
	v_fmamk_f32 v152, v152, 0x3e38aa3b, v164
	v_fmamk_f32 v153, v153, 0x3e38aa3b, v164
	v_fmamk_f32 v154, v154, 0x3e38aa3b, v164
	v_fmamk_f32 v155, v155, 0x3e38aa3b, v164
	v_fmamk_f32 v156, v156, 0x3e38aa3b, v164
	v_fmamk_f32 v157, v157, 0x3e38aa3b, v164
	v_fmamk_f32 v158, v158, 0x3e38aa3b, v164
	v_mfma_f32_32x32x16_bf16 v[48:63], v[206:209], v[198:201], v[48:63]
	ds_read2_b64 v[198:201], v215 offset0:160 offset1:162
	ds_read2_b64 v[216:219], v212 offset0:132 offset1:134
	ds_read2_b64 v[220:223], v238 offset0:192 offset1:194
	ds_read2_b64 v[224:227], v210 offset0:224 offset1:226
	v_fmamk_f32 v159, v159, 0x3e38aa3b, v164
	v_exp_f32_e32 v213, v152
	v_exp_f32_e32 v229, v153
	v_exp_f32_e32 v231, v154
	v_exp_f32_e32 v233, v157
	s_waitcnt lgkmcnt(1)
	v_mfma_f32_32x32x16_bf16 v[96:111], v[202:205], v[220:223], v[96:111]
	v_exp_f32_e32 v235, v158
	v_exp_f32_e32 v237, v159
	v_fmamk_f32 v136, v136, 0x3e38aa3b, v173
	v_fmamk_f32 v137, v137, 0x3e38aa3b, v173
	v_fmamk_f32 v138, v138, 0x3e38aa3b, v173
	v_fmamk_f32 v139, v139, 0x3e38aa3b, v173
	v_fmamk_f32 v140, v140, 0x3e38aa3b, v173
	v_mfma_f32_32x32x16_bf16 v[16:31], v[206:209], v[220:223], v[16:31]
	v_exp_f32_e32 v221, v155
	v_exp_f32_e32 v223, v156
	global_load_dwordx4 v[152:155], v[180:181], off offset:1024
	global_load_dwordx4 v[156:159], v[178:179], off
	v_fmamk_f32 v141, v141, 0x3e38aa3b, v173
	global_load_dwordx4 v[178:181], v[178:179], off offset:16
	v_fmamk_f32 v142, v142, 0x3e38aa3b, v173
	v_fmamk_f32 v143, v143, 0x3e38aa3b, v173
	v_exp_f32_e32 v212, v136
	v_exp_f32_e32 v228, v137
	v_exp_f32_e32 v230, v138
	v_exp_f32_e32 v220, v139
	v_exp_f32_e32 v222, v140
	v_exp_f32_e32 v232, v141
	v_exp_f32_e32 v234, v142
	v_exp_f32_e32 v236, v143
	v_mfma_f32_32x32x16_bf16 v[80:95], v[202:205], v[198:201], v[80:95]
	v_cvt_pk_bf16_f32 v136, v212, v228
	v_cvt_pk_bf16_f32 v137, v230, v220
	v_cvt_pk_bf16_f32 v138, v222, v232
	v_cvt_pk_bf16_f32 v139, v234, v236
	v_cvt_pk_bf16_f32 v140, v213, v229
	v_cvt_pk_bf16_f32 v141, v231, v221
	v_cvt_pk_bf16_f32 v142, v223, v233
	v_mfma_f32_32x32x16_bf16 v[32:47], v[206:209], v[198:201], v[32:47]
	v_cvt_pk_bf16_f32 v143, v235, v237
	ds_read2_b64 v[198:201], v215 offset0:164 offset1:166
	v_add_f32_e64 v150, v168, v150
	v_add_f32_e64 v151, v169, v151
	v_add_f32_e64 v148, v148, v150
	v_add_f32_e64 v149, v149, v151
	v_pk_add_f32 v[146:147], v[146:147], v[148:149]
	s_waitcnt lgkmcnt(1)
; #define MFMA32(a, b, c) __builtin_amdgcn_mfma_f32_32x32x16_bf16((a), (b), (c), 0, 0, 0)
; __device__ __forceinline__ void attn_item_A(const Params& p, int layer, int head, int q0u, char* lds) {
;     ...
;   for (int t = 0; t < ntiles; ++t) {
;     const int buf = t & 1;
;     const bool more = (t + 1 < ntiles);
;     if (more) { ATT_LOADK(t + 1); ATT_LOADV(t + 1); }
;     const u16* kt_ = Ks + buf * 32 * KLD + r * KLD + 8 * h;
;     bf16x8 a0, a1, b0, b1;
;     {
;       f32x16 sx, sy;
; #pragma unroll
;       for (int e = 0; e < 16; ++e) { sx[e] = 0.f; sy[e] = 0.f; }
; #pragma unroll
;       for (int s = 0; s < 4; ++s) {
;         const bf16x8 kf = *(const bf16x8*)(kt_ + 16 * s);
;         const bf16x8 qf = *(const bf16x8*)(Qs + s * 1024);
;         sx = MFMA32(kf, qf, sx);
;       }
; #pragma unroll
;       for (int s = 4; s < 8; ++s) {
;         const bf16x8 kf = *(const bf16x8*)(kt_ + 16 * s);
;         const bf16x8 qf = *(const bf16x8*)(Qs + s * 1024);
;         sy = MFMA32(kf, qf, sy);
;       }
;       {
;         float w[16];
; #pragma unroll
;         for (int e = 0; e < 16; ++e) { w[e] = __builtin_amdgcn_exp2f(fmaf(sx[e], CS, -bA)); lA += w[e]; }
;         const u32x4 p0 = {pk2(w[0], w[1]), pk2(w[2], w[3]), pk2(w[4], w[5]), pk2(w[6], w[7])};
;         const u32x4 p1 = {pk2(w[8], w[9]), pk2(w[10], w[11]), pk2(w[12], w[13]), pk2(w[14], w[15])};
;         a0 = __builtin_bit_cast(bf16x8, p0); a1 = __builtin_bit_cast(bf16x8, p1);
;       }
;       {
;         float w[16];
; #pragma unroll
;         for (int e = 0; e < 16; ++e) { w[e] = __builtin_amdgcn_exp2f(fmaf(sy[e], CS, -bB)); lB += w[e]; }
;         const u32x4 p0 = {pk2(w[0], w[1]), pk2(w[2], w[3]), pk2(w[4], w[5]), pk2(w[6], w[7])};
;         const u32x4 p1 = {pk2(w[8], w[9]), pk2(w[10], w[11]), pk2(w[12], w[13]), pk2(w[14], w[15])};
;         b0 = __builtin_bit_cast(bf16x8, p0); b1 = __builtin_bit_cast(bf16x8, p1);
;       }
;     }
;     const u16* vt = Vt + buf * 128 * VLD + r * VLD + 4 * h;
; #pragma unroll
;     for (int d = 0; d < 4; d += 2) {
;       const s16x4 l0 = *(const s16x4*)(vt + d * 32 * VLD), h0 = *(const s16x4*)(vt + d * 32 * VLD + 8);
;       const s16x4 l1 = *(const s16x4*)(vt + d * 32 * VLD + 16), h1 = *(const s16x4*)(vt + d * 32 * VLD + 24);
;       const s16x4 m0 = *(const s16x4*)(vt + (d + 1) * 32 * VLD), n0 = *(const s16x4*)(vt + (d + 1) * 32 * VLD + 8);
	v_mfma_f32_32x32x16_bf16 v[112:127], v[202:205], v[224:227], v[112:127]
	ds_read2_b64 v[202:205], v210 offset0:228 offset1:230
	v_add_f32_e64 v144, v144, v146
	v_add_f32_e64 v145, v145, v147
	v_add_f32_e64 v134, v134, v144
	v_add_f32_e64 v135, v135, v145
	v_pk_add_f32 v[130:131], v[130:131], v[134:135]
	v_mfma_f32_32x32x16_bf16 v[0:15], v[206:209], v[224:227], v[0:15]
	v_add_f32_e64 v130, v132, v130
	v_add_f32_e64 v131, v133, v131
	v_add_u32_e32 v206, s7, v172
	v_add_f32_e64 v128, v128, v130
	v_add_f32_e64 v129, v129, v131
	v_add_u32_e32 v207, s1, v174
	v_pk_add_f32 v[128:129], v[212:213], v[128:129]
	v_add_u32_e32 v208, 0x4400, v207
	v_pk_add_f32 v[128:129], v[228:229], v[128:129]
	s_waitcnt lgkmcnt(1)
	v_mfma_f32_32x32x16_bf16 v[80:95], v[136:139], v[198:201], v[80:95]
	v_add_f32_e64 v128, v230, v128
	v_add_f32_e64 v129, v231, v129
	v_add_u32_e32 v207, 0x4410, v207
	v_add_f32_e64 v128, v220, v128
	v_add_f32_e64 v129, v221, v129
	v_pk_add_f32 v[128:129], v[222:223], v[128:129]
	s_nop 0
	v_pk_add_f32 v[128:129], v[232:233], v[128:129]
	v_mfma_f32_32x32x16_bf16 v[32:47], v[140:143], v[198:201], v[32:47]
	ds_read2_b64 v[198:201], v238 offset0:196 offset1:198
	v_add_f32_e64 v128, v234, v128
	v_add_f32_e64 v129, v235, v129
	s_setprio 0
	s_waitcnt vmcnt(2)
	ds_write_b128 v206, v[152:155]
	ds_write_b128 v206, v[160:163] offset:16
	s_waitcnt vmcnt(1)
	ds_write2_b64 v208, v[156:157], v[158:159] offset1:1
	s_waitcnt vmcnt(0)
	ds_write2_b64 v207, v[178:179], v[180:181] offset1:1
	v_mfma_f32_32x32x16_bf16 v[64:79], v[136:139], v[216:219], v[64:79]
	v_add_f32_e64 v168, v236, v128
	v_add_f32_e64 v169, v237, v129
	s_waitcnt lgkmcnt(0)
	s_barrier
	v_mfma_f32_32x32x16_bf16 v[48:63], v[140:143], v[216:219], v[48:63]
	v_mfma_f32_32x32x16_bf16 v[96:111], v[136:139], v[198:201], v[96:111]
	v_mfma_f32_32x32x16_bf16 v[16:31], v[140:143], v[198:201], v[16:31]
	v_mfma_f32_32x32x16_bf16 v[112:127], v[136:139], v[202:205], v[112:127]
	v_mfma_f32_32x32x16_bf16 v[0:15], v[140:143], v[202:205], v[0:15]
	s_cbranch_scc0 .LBB0_1571
	s_and_b32 s0, s0, 1
	s_mul_i32 s1, s0, 0x2200
	v_add_u32_e32 v170, s1, v196
	ds_read_b128 v[128:131], v170
	ds_read_b128 v[132:135], v197 offset:37888
	ds_read_b128 v[136:139], v197 offset:38912
	ds_read_b128 v[140:143], v170 offset:32
	s_mulk_i32 s0, 0x2400
	s_waitcnt lgkmcnt(2)
	v_mfma_f32_32x32x16_bf16 v[144:159], v[128:131], v[132:135], 0
	ds_read_b128 v[128:131], v170 offset:64
	ds_read_b128 v[132:135], v197 offset:39936
	ds_read_b128 v[160:163], v197 offset:40960
	ds_read_b128 v[176:179], v170 offset:96
	s_waitcnt lgkmcnt(4)
	v_mfma_f32_32x32x16_bf16 v[144:159], v[140:143], v[136:139], v[144:159]
	s_waitcnt lgkmcnt(2)
	v_mfma_f32_32x32x16_bf16 v[144:159], v[128:131], v[132:135], v[144:159]
	ds_read_b128 v[128:131], v170 offset:128
	ds_read_b128 v[132:135], v197 offset:41984
	ds_read_b128 v[198:201], v197 offset:43008
	ds_read_b128 v[202:205], v170 offset:160
	ds_read_b128 v[206:209], v197 offset:44032
	ds_read_b128 v[194:197], v197 offset:45056
	ds_read_b128 v[216:219], v170 offset:192
	ds_read_b128 v[220:223], v170 offset:224
	s_waitcnt lgkmcnt(6)
	v_mfma_f32_32x32x16_bf16 v[128:143], v[128:131], v[132:135], 0
	s_waitcnt lgkmcnt(4)
	v_mfma_f32_32x32x16_bf16 v[128:143], v[202:205], v[198:201], v[128:143]
	s_waitcnt lgkmcnt(1)
	v_mfma_f32_32x32x16_bf16 v[128:143], v[216:219], v[206:209], v[128:143]
	s_waitcnt lgkmcnt(0)
	v_mfma_f32_32x32x16_bf16 v[128:143], v[220:223], v[194:197], v[128:143]
	v_mfma_f32_32x32x16_bf16 v[144:159], v[176:179], v[160:163], v[144:159]
	s_nop 10
	v_fmamk_f32 v128, v128, 0x3e38aa3b, v164
	v_exp_f32_e32 v194, v128
	v_fmamk_f32 v128, v129, 0x3e38aa3b, v164
	v_exp_f32_e32 v195, v128
	v_fmamk_f32 v128, v130, 0x3e38aa3b, v164
	v_exp_f32_e32 v196, v128
	v_fmamk_f32 v128, v131, 0x3e38aa3b, v164
	v_fmamk_f32 v144, v144, 0x3e38aa3b, v173
	v_exp_f32_e32 v160, v144
	v_fmamk_f32 v144, v155, 0x3e38aa3b, v173
	v_exp_f32_e32 v197, v128
	v_fmamk_f32 v128, v132, 0x3e38aa3b, v164
	v_fmamk_f32 v132, v134, 0x3e38aa3b, v164
	v_fmamk_f32 v145, v145, 0x3e38aa3b, v173
	v_fmamk_f32 v146, v146, 0x3e38aa3b, v173
	v_fmamk_f32 v147, v147, 0x3e38aa3b, v173
	v_fmamk_f32 v148, v148, 0x3e38aa3b, v173
	v_fmamk_f32 v149, v149, 0x3e38aa3b, v173
	v_fmamk_f32 v150, v150, 0x3e38aa3b, v173
	v_fmamk_f32 v151, v151, 0x3e38aa3b, v173
	v_exp_f32_e32 v179, v144
	v_fmamk_f32 v144, v156, 0x3e38aa3b, v173
	v_exp_f32_e32 v198, v128
	v_fmamk_f32 v128, v133, 0x3e38aa3b, v164
	v_add_u32_e32 v156, s0, v175
	v_exp_f32_e32 v175, v132
	v_fmamk_f32 v132, v135, 0x3e38aa3b, v164
	v_exp_f32_e32 v161, v145
	v_exp_f32_e32 v162, v146
	v_exp_f32_e32 v163, v147
	v_exp_f32_e32 v170, v148
	v_exp_f32_e32 v171, v149
	v_exp_f32_e32 v172, v150
	v_exp_f32_e32 v174, v151
	v_exp_f32_e32 v199, v128
	v_exp_f32_e32 v200, v132
	v_fmamk_f32 v152, v152, 0x3e38aa3b, v173
	v_exp_f32_e32 v180, v144
	v_fmamk_f32 v144, v157, 0x3e38aa3b, v173
	v_exp_f32_e32 v176, v152
	v_exp_f32_e32 v181, v144
	v_fmamk_f32 v144, v158, 0x3e38aa3b, v173
	v_add_u32_e32 v152, 0x4000, v156
	v_fmamk_f32 v136, v136, 0x3e38aa3b, v164
	v_exp_f32_e32 v193, v144
	v_cvt_pk_bf16_f32 v144, v160, v161
	v_cvt_pk_bf16_f32 v145, v162, v163
	v_cvt_pk_bf16_f32 v146, v170, v171
	v_cvt_pk_bf16_f32 v147, v172, v174
	ds_read2_b64 v[128:131], v152 offset0:128 offset1:130
	v_cvt_pk_bf16_f32 v132, v194, v195
	v_cvt_pk_bf16_f32 v133, v196, v197
	v_cvt_pk_bf16_f32 v134, v198, v199
	v_cvt_pk_bf16_f32 v135, v175, v200
	v_exp_f32_e32 v201, v136
	v_fmamk_f32 v136, v137, 0x3e38aa3b, v164
	v_exp_f32_e32 v202, v136
	v_fmamk_f32 v136, v138, 0x3e38aa3b, v164
	v_exp_f32_e32 v203, v136
	v_fmamk_f32 v136, v139, 0x3e38aa3b, v164
	v_fmamk_f32 v153, v153, 0x3e38aa3b, v173
	v_exp_f32_e32 v204, v136
	v_fmamk_f32 v136, v140, 0x3e38aa3b, v164
	v_exp_f32_e32 v177, v153
	v_add_u32_e32 v153, 0x4800, v156
	v_exp_f32_e32 v205, v136
	v_fmamk_f32 v136, v141, 0x3e38aa3b, v164
	v_fmamk_f32 v154, v154, 0x3e38aa3b, v173
	v_fmac_f32_e32 v173, 0x3e38aa3b, v159
	s_waitcnt lgkmcnt(0)
; __device__ __forceinline__ void attn_item_A(const Params& p, int layer, int head, int q0u, char* lds) {
;     ...
;     const u16* vt = Vt + buf * 128 * VLD + r * VLD + 4 * h;
; #pragma unroll
;     for (int d = 0; d < 4; d += 2) {
;       const s16x4 l0 = *(const s16x4*)(vt + d * 32 * VLD), h0 = *(const s16x4*)(vt + d * 32 * VLD + 8);
;       const s16x4 l1 = *(const s16x4*)(vt + d * 32 * VLD + 16), h1 = *(const s16x4*)(vt + d * 32 * VLD + 24);
;       const s16x4 m0 = *(const s16x4*)(vt + (d + 1) * 32 * VLD), n0 = *(const s16x4*)(vt + (d + 1) * 32 * VLD + 8);
;       const s16x4 m1 = *(const s16x4*)(vt + (d + 1) * 32 * VLD + 16), n1 = *(const s16x4*)(vt + (d + 1) * 32 * VLD + 24);
;       const bf16x8 v0 = {l0[0], l0[1], l0[2], l0[3], h0[0], h0[1], h0[2], h0[3]};
;       const bf16x8 v1 = {l1[0], l1[1], l1[2], l1[3], h1[0], h1[1], h1[2], h1[3]};
;       const bf16x8 u0 = {m0[0], m0[1], m0[2], m0[3], n0[0], n0[1], n0[2], n0[3]};
;       const bf16x8 u1 = {m1[0], m1[1], m1[2], m1[3], n1[0], n1[1], n1[2], n1[3]};
;       o1[d] = MFMA32(a0, v0, o1[d]);
;       o2[d] = MFMA32(b0, v0, o2[d]);
;       o1[d + 1] = MFMA32(a0, u0, o1[d + 1]);
;       o2[d + 1] = MFMA32(b0, u0, o2[d + 1]);
;       o1[d] = MFMA32(a1, v1, o1[d]);
;       o2[d] = MFMA32(b1, v1, o2[d]);
;       o1[d + 1] = MFMA32(a1, u1, o1[d + 1]);
;       o2[d + 1] = MFMA32(b1, u1, o2[d + 1]);
;     }
;     if (more) { ATT_STOREK(buf ^ 1); ATT_STOREV(buf ^ 1); }
;     __syncthreads();
;   }
;   int lane_e = lane; asm volatile("" : "+v"(lane_e));
;   const int r_e = lane_e & 31, h_e = lane_e >> 5;
;   lA += __shfl_xor(lA, 32); lB += __shfl_xor(lB, 32);
;   const float lam = ((const float*)(p.ws + OFF_LAM))[layer];
;   const float iA = 1.f / lA, iB = lam / lB;
;   u16* Mx = (u16*)(p.ws + OFF_M);
;   const int orow0 = q0u + wid * 32;
;   const float lam_init = 0.8f - 0.6f * expf(-0.3f * (float)layer);
;   float sw[4];
; #pragma unroll
;   for (int d = 0; d < 4; ++d) sw[d] = p.subln[layer * 128 + d * 32 + r_e] * (1.f - lam_init);
; #pragma unroll
;   for (int e = 0; e < 16; ++e) {
;     const int qq = crow(e, h_e);
;     const float ia = __shfl(iA, qq), ib = __shfl(iB, qq);
;     float ov[4];
;     float ss = 0.f;
; #pragma unroll
;     for (int d = 0; d < 4; ++d) { ov[d] = o1[d][e] * ia - o2[d][e] * ib; ss += ov[d] * ov[d]; }
; #pragma unroll
;     for (int x = 16; x >= 1; x >>= 1) ss += __shfl_xor(ss, x);
	v_mfma_f32_32x32x16_bf16 v[64:79], v[144:147], v[128:131], v[64:79]
	v_exp_f32_e32 v206, v136
	v_fmamk_f32 v136, v142, 0x3e38aa3b, v164
	v_fmac_f32_e32 v164, 0x3e38aa3b, v143
	v_exp_f32_e32 v178, v154
	v_exp_f32_e32 v173, v173
	v_exp_f32_e32 v207, v136
	v_exp_f32_e32 v164, v164
	v_mfma_f32_32x32x16_bf16 v[48:63], v[132:135], v[128:131], v[48:63]
	ds_read2_b64 v[128:131], v153 offset0:160 offset1:162
	v_cvt_pk_bf16_f32 v148, v176, v177
	v_cvt_pk_bf16_f32 v149, v178, v179
	v_cvt_pk_bf16_f32 v150, v180, v181
	v_cvt_pk_bf16_f32 v151, v193, v173
	v_cvt_pk_bf16_f32 v136, v201, v202
	v_cvt_pk_bf16_f32 v137, v203, v204
	s_waitcnt lgkmcnt(0)
	v_mfma_f32_32x32x16_bf16 v[80:95], v[144:147], v[128:131], v[80:95]
	v_cvt_pk_bf16_f32 v138, v205, v206
	v_cvt_pk_bf16_f32 v139, v207, v164
	v_add_f32_e32 v160, v168, v160
	v_add_f32_e32 v160, v161, v160
	v_mfma_f32_32x32x16_bf16 v[32:47], v[132:135], v[128:131], v[32:47]
	ds_read2_b64 v[128:131], v152 offset0:132 offset1:134
	v_add_u32_e32 v152, 0x5000, v156
	v_add_u32_e32 v156, 0x5800, v156
	s_waitcnt lgkmcnt(0)
	v_mfma_f32_32x32x16_bf16 v[64:79], v[148:151], v[128:131], v[64:79]
	v_mfma_f32_32x32x16_bf16 v[48:63], v[136:139], v[128:131], v[48:63]
	ds_read2_b64 v[128:131], v153 offset0:164 offset1:166
	ds_read2_b64 v[140:143], v152 offset0:192 offset1:194
	ds_read2_b64 v[152:155], v152 offset0:196 offset1:198
	s_waitcnt lgkmcnt(2)
	v_mfma_f32_32x32x16_bf16 v[80:95], v[148:151], v[128:131], v[80:95]
	v_mfma_f32_32x32x16_bf16 v[32:47], v[136:139], v[128:131], v[32:47]
	ds_read2_b64 v[128:131], v156 offset0:224 offset1:226
	ds_read2_b64 v[156:159], v156 offset0:228 offset1:230
	s_waitcnt lgkmcnt(0)
	s_barrier
	global_load_dword v208, v165, s[16:17]
	v_and_b32_e32 v209, 31, v167
	v_mfma_f32_32x32x16_bf16 v[96:111], v[144:147], v[140:143], v[96:111]
	v_lshlrev_b32_e32 v210, 2, v209
	global_load_dword v212, v210, s[54:55]
	global_load_dword v213, v210, s[54:55] offset:128
	global_load_dword v215, v210, s[54:55] offset:256
	v_mfma_f32_32x32x16_bf16 v[16:31], v[132:135], v[140:143], v[16:31]
	v_add_f32_e32 v141, v169, v194
	v_add_f32_e32 v141, v195, v141
	v_add_f32_e32 v141, v196, v141
	v_add_f32_e32 v141, v197, v141
	v_add_f32_e32 v140, v162, v160
	v_add_f32_e32 v140, v163, v140
	v_add_f32_e32 v140, v170, v140
	v_mfma_f32_32x32x16_bf16 v[112:127], v[144:147], v[128:131], v[112:127]
	v_add_f32_e32 v140, v171, v140
	v_add_f32_e32 v140, v172, v140
	v_add_f32_e32 v140, v174, v140
	v_add_f32_e32 v140, v176, v140
	v_add_f32_e32 v140, v177, v140
	v_add_f32_e32 v140, v178, v140
	v_add_f32_e32 v140, v179, v140
	v_mfma_f32_32x32x16_bf16 v[0:15], v[132:135], v[128:131], v[0:15]
	v_add_f32_e32 v128, v198, v141
	v_add_f32_e32 v128, v199, v128
	v_add_f32_e32 v128, v175, v128
	v_add_f32_e32 v128, v200, v128
	v_add_f32_e32 v128, v201, v128
	v_add_f32_e32 v128, v202, v128
	v_add_f32_e32 v128, v203, v128
	v_add_f32_e32 v128, v204, v128
	v_add_f32_e32 v128, v205, v128
	v_add_f32_e32 v128, v206, v128
	v_add_f32_e32 v128, v207, v128
	v_add_f32_e32 v128, v164, v128
	ds_bpermute_b32 v129, v192, v128
	v_add_f32_e32 v130, v180, v140
	v_add_f32_e32 v130, v181, v130
	v_add_f32_e32 v130, v193, v130
	v_add_f32_e32 v130, v173, v130
	s_waitcnt lgkmcnt(0)
	v_add_f32_e32 v128, v128, v129
	ds_bpermute_b32 v133, v192, v130
	v_mfma_f32_32x32x16_bf16 v[0:15], v[136:139], v[156:159], v[0:15]
	v_mov_b32_e32 v143, v32
	v_mov_b32_e32 v140, v64
	v_mov_b32_e32 v142, v48
	s_waitcnt lgkmcnt(0)
	v_add_f32_e32 v133, v130, v133
	v_mov_b32_e32 v141, v80
	v_mov_b32_e32 v80, v65
	v_lshlrev_b32_e32 v164, 1, v209
	v_mfma_f32_32x32x16_bf16 v[16:31], v[136:139], v[152:155], v[16:31]
	s_nop 2
	v_mov_b32_e32 v146, v0
	v_xor_b32_e32 v0, 16, v214
	s_waitcnt vmcnt(3)
	v_div_scale_f32 v129, s[0:1], v128, v128, v208
	v_rcp_f32_e32 v131, v129
	v_mfma_f32_32x32x16_bf16 v[96:111], v[148:151], v[152:155], v[96:111]
	s_nop 2
	v_mov_b32_e32 v147, v16
	s_waitcnt vmcnt(1)
	v_mul_f32_e32 v130, 0x3f4ccccd, v213
	v_fma_f32 v132, -v129, v131, 1.0
	v_fmac_f32_e32 v131, v132, v131
	v_div_scale_f32 v132, vcc, v208, v128, v208
	v_mul_f32_e32 v134, v132, v131
	v_fma_f32 v135, -v129, v134, v132
	v_fmac_f32_e32 v134, v135, v131
	v_fma_f32 v129, -v129, v134, v132
	v_div_fmas_f32 v129, v129, v131, v134
	v_div_scale_f32 v134, s[0:1], v133, v133, 1.0
	v_rcp_f32_e32 v135, v134
	v_mfma_f32_32x32x16_bf16 v[112:127], v[148:151], v[156:159], v[112:127]
	v_div_fixup_f32 v132, v129, v128, v208
	v_mov_b32_e32 v145, v96
	v_fma_f32 v136, -v134, v135, 1.0
	v_fmac_f32_e32 v135, v136, v135
	v_div_scale_f32 v136, vcc, 1.0, v133, 1.0
	v_mul_f32_e32 v137, v136, v135
	v_fma_f32 v138, -v134, v137, v136
	v_fmac_f32_e32 v137, v138, v135
	v_fma_f32 v134, -v134, v137, v136
	v_div_fmas_f32 v134, v134, v135, v137
	v_ashrrev_i32_e32 v135, 3, v167
	v_div_fixup_f32 v133, v134, v133, 1.0
	v_and_b32_e32 v134, -4, v135
	v_cmp_lt_i32_e32 vcc, v0, v188
	v_or_b32_e32 v150, 1, v134
	v_and_or_b32 v136, v135, 60, v187
	v_cndmask_b32_e32 v16, v214, v0, vcc
	v_and_or_b32 v0, v150, 61, v187
	v_lshlrev_b32_e32 v137, 2, v136
	v_lshlrev_b32_e32 v32, 2, v0
	ds_bpermute_b32 v138, v137, v132
	ds_bpermute_b32 v0, v32, v132
	ds_bpermute_b32 v136, v137, v133
	ds_bpermute_b32 v64, v32, v133
	v_mov_b32_e32 v32, v49
	s_waitcnt lgkmcnt(3)
	v_pk_mul_f32 v[142:143], v[142:143], v[138:139] op_sel_hi:[1,0]
	v_mov_b32_e32 v144, v112
	v_pk_mul_f32 v[138:139], v[146:147], v[138:139] op_sel_hi:[1,0]
	v_lshlrev_b32_e32 v48, 2, v16
	s_waitcnt lgkmcnt(2)
	v_pk_mul_f32 v[32:33], v[32:33], v[0:1] op_sel_hi:[1,0]
	v_mov_b32_e32 v16, v1
	s_waitcnt lgkmcnt(1)
; DI u16 f2bf(float a) { return (u16)(pk2(a, 0.f) & 0xffffu); }
; DI int crow(int i, int h) { return (i & 3) + 8 * (i >> 2) + 4 * h; }
; __device__ __forceinline__ void attn_item_A(const Params& p, int layer, int head, int q0u, char* lds) {
;     ...
; #pragma unroll
;   for (int e = 0; e < 16; ++e) {
;     const int qq = crow(e, h_e);
;     const float ia = __shfl(iA, qq), ib = __shfl(iB, qq);
;     float ov[4];
;     float ss = 0.f;
; #pragma unroll
;     for (int d = 0; d < 4; ++d) { ov[d] = o1[d][e] * ia - o2[d][e] * ib; ss += ov[d] * ov[d]; }
; #pragma unroll
;     for (int x = 16; x >= 1; x >>= 1) ss += __shfl_xor(ss, x);
;     const float rs = rsqrtf(ss * (1.f / 128.f) + LN_EPS);
;     const size_t rowoff = (size_t)(orow0 + qq) * LDX + ocol + r_e;
; #pragma unroll
;     for (int d = 0; d < 4; ++d) Mx[rowoff + d * 32] = f2bf(ov[d] * rs * sw[d]);
;   }
	v_pk_fma_f32 v[140:141], v[140:141], v[136:137], v[142:143] op_sel_hi:[1,0,1] neg_lo:[0,0,1] neg_hi:[0,0,1]
	v_pk_fma_f32 v[136:137], v[144:145], v[136:137], v[138:139] op_sel_hi:[1,0,1] neg_lo:[0,0,1] neg_hi:[0,0,1]
	s_waitcnt lgkmcnt(0)
	v_pk_fma_f32 v[144:145], v[80:81], v[64:65], v[32:33] op_sel_hi:[1,0,1] neg_lo:[0,0,1] neg_hi:[0,0,1]
	v_mov_b32_e32 v96, v113
	v_pk_mul_f32 v[0:1], v[16:17], v[0:1] op_sel_hi:[1,0]
	v_pk_mul_f32 v[142:143], v[140:141], v[140:141]
	v_pk_mul_f32 v[32:33], v[144:145], v[144:145]
	v_pk_fma_f32 v[96:97], v[96:97], v[64:65], v[0:1] op_sel_hi:[1,0,1] neg_lo:[0,0,1] neg_hi:[0,0,1]
	v_pk_mul_f32 v[138:139], v[136:137], v[136:137]
	v_pk_mul_f32 v[0:1], v[96:97], v[96:97]
	v_mov_b32_e32 v16, v32
	v_mov_b32_e32 v17, v142
	v_mov_b32_e32 v142, v33
	v_pk_add_f32 v[16:17], v[16:17], v[142:143]
	v_mov_b32_e32 v32, v1
	v_mov_b32_e32 v33, v139
	v_pk_add_f32 v[16:17], v[32:33], v[16:17]
	v_mov_b32_e32 v1, v138
	v_pk_add_f32 v[0:1], v[0:1], v[16:17]
	ds_bpermute_b32 v17, v48, v1
	ds_bpermute_b32 v16, v48, v0
	v_xor_b32_e32 v32, 8, v214
	v_cmp_lt_i32_e32 vcc, v32, v188
	s_add_u32 s0, s31, s4
	s_addc_u32 s1, s34, s5
	v_cndmask_b32_e32 v32, v214, v32, vcc
	v_lshlrev_b32_e32 v49, 2, v32
	s_waitcnt lgkmcnt(0)
	v_pk_add_f32 v[0:1], v[0:1], v[16:17]
	ds_bpermute_b32 v17, v49, v1
	ds_bpermute_b32 v16, v49, v0
	v_xor_b32_e32 v32, 4, v214
	v_cmp_lt_i32_e32 vcc, v32, v188
	v_mul_f32_e32 v131, 0x3f4ccccd, v212
	s_waitcnt vmcnt(0)
	v_mul_f32_e32 v129, 0x3f4ccccd, v215
	v_cndmask_b32_e32 v32, v214, v32, vcc
	v_lshlrev_b32_e32 v64, 2, v32
	s_waitcnt lgkmcnt(0)
	v_pk_add_f32 v[0:1], v[0:1], v[16:17]
	ds_bpermute_b32 v17, v64, v1
	ds_bpermute_b32 v16, v64, v0
	v_xor_b32_e32 v32, 2, v214
	v_cmp_lt_i32_e32 vcc, v32, v188
	v_or_b32_e32 v152, 2, v134
	v_or_b32_e32 v135, 3, v135
	v_cndmask_b32_e32 v32, v214, v32, vcc
	v_lshlrev_b32_e32 v65, 2, v32
	s_waitcnt lgkmcnt(0)
	v_pk_add_f32 v[0:1], v[0:1], v[16:17]
	ds_bpermute_b32 v17, v65, v1
	ds_bpermute_b32 v16, v65, v0
	v_xor_b32_e32 v32, 1, v214
	v_cmp_lt_i32_e32 vcc, v32, v188
	v_mov_b32_e32 v148, v2
	v_and_or_b32 v2, v135, 63, v187
	v_cndmask_b32_e32 v32, v214, v32, vcc
	v_lshlrev_b32_e32 v80, 2, v32
	s_waitcnt lgkmcnt(0)
	v_pk_add_f32 v[0:1], v[0:1], v[16:17]
	ds_bpermute_b32 v33, v80, v1
	ds_bpermute_b32 v32, v80, v0
	v_lshl_add_u64 v[16:17], s[0:1], 0, v[164:165]
	v_mov_b32_e32 v149, v18
	v_lshlrev_b32_e32 v18, 2, v2
	ds_bpermute_b32 v2, v18, v132
	s_waitcnt lgkmcnt(1)
	v_pk_add_f32 v[0:1], v[0:1], v[32:33]
	v_mov_b64_e32 v[32:33], s[30:31]
	v_pk_fma_f32 v[112:113], v[0:1], s[28:29], v[32:33] op_sel_hi:[1,0,0]
	v_mov_b32_e32 v142, v50
	v_mul_f32_e32 v0, 0x4b800000, v113
	v_cmp_gt_f32_e32 vcc, s80, v113
	ds_bpermute_b32 v50, v18, v133
	v_mov_b32_e32 v143, v34
	v_cndmask_b32_e32 v0, v113, v0, vcc
	v_rsq_f32_e32 v81, v0
	v_add_u32_e32 v0, v134, v191
	v_mad_i64_i32 v[0:1], s[0:1], v0, s77, v[16:17]
	v_mul_f32_e32 v113, 0x45800000, v81
	v_cndmask_b32_e32 v81, v81, v113, vcc
	v_mul_f32_e32 v113, v140, v81
	v_mul_f32_e32 v113, v131, v113
	v_cvt_pk_bf16_f32 v113, v113, s0
	global_store_short v[0:1], v113, off
	v_mul_f32_e32 v113, v141, v81
	v_mul_f32_e32 v113, v130, v113
	v_cvt_pk_bf16_f32 v113, v113, s0
	global_store_short v[0:1], v113, off offset:64
	v_mul_f32_e32 v113, v137, v81
	v_mul_f32_e32 v113, v129, v113
	v_cvt_pk_bf16_f32 v137, v113, s0
	v_mul_f32_e32 v113, 0x4b800000, v112
	v_cmp_gt_f32_e32 vcc, s80, v112
	v_mov_b32_e32 v34, v51
	v_mov_b32_e32 v140, v66
	v_cndmask_b32_e32 v112, v112, v113, vcc
	v_rsq_f32_e32 v151, v112
	v_and_or_b32 v112, v152, 62, v187
	v_lshlrev_b32_e32 v113, 2, v112
	ds_bpermute_b32 v138, v113, v132
	ds_bpermute_b32 v112, v113, v133
	v_mov_b32_e32 v141, v82
	v_mov_b32_e32 v82, v67
	s_waitcnt lgkmcnt(3)
	v_pk_mul_f32 v[34:35], v[34:35], v[2:3] op_sel_hi:[1,0]
	s_waitcnt lgkmcnt(1)
	v_pk_mul_f32 v[142:143], v[142:143], v[138:139] op_sel_hi:[1,0]
	v_mov_b32_e32 v18, v3
	s_waitcnt lgkmcnt(0)
	v_pk_fma_f32 v[140:141], v[140:141], v[112:113], v[142:143] op_sel_hi:[1,0,1] neg_lo:[0,0,1] neg_hi:[0,0,1]
	v_mov_b32_e32 v146, v114
	v_mov_b32_e32 v147, v98
	v_pk_mul_f32 v[138:139], v[148:149], v[138:139] op_sel_hi:[1,0]
	v_pk_fma_f32 v[66:67], v[82:83], v[50:51], v[34:35] op_sel_hi:[1,0,1] neg_lo:[0,0,1] neg_hi:[0,0,1]
	v_mov_b32_e32 v98, v115
	v_pk_mul_f32 v[2:3], v[18:19], v[2:3] op_sel_hi:[1,0]
	v_pk_mul_f32 v[142:143], v[140:141], v[140:141]
	v_pk_fma_f32 v[112:113], v[146:147], v[112:113], v[138:139] op_sel_hi:[1,0,1] neg_lo:[0,0,1] neg_hi:[0,0,1]
	v_pk_mul_f32 v[34:35], v[66:67], v[66:67]
	v_pk_fma_f32 v[50:51], v[98:99], v[50:51], v[2:3] op_sel_hi:[1,0,1] neg_lo:[0,0,1] neg_hi:[0,0,1]
	v_pk_mul_f32 v[138:139], v[112:113], v[112:113]
	v_pk_mul_f32 v[2:3], v[50:51], v[50:51]
	v_mov_b32_e32 v18, v34
	v_mov_b32_e32 v19, v142
	v_mov_b32_e32 v142, v35
	v_pk_add_f32 v[18:19], v[18:19], v[142:143]
	v_mov_b32_e32 v34, v3
	v_mov_b32_e32 v35, v139
	v_pk_add_f32 v[18:19], v[34:35], v[18:19]
	v_mov_b32_e32 v3, v138
	v_pk_add_f32 v[2:3], v[2:3], v[18:19]
	ds_bpermute_b32 v19, v48, v3
	ds_bpermute_b32 v18, v48, v2
	v_mul_f32_e32 v35, 0x45800000, v151
	v_cndmask_b32_e32 v35, v151, v35, vcc
	v_mul_f32_e32 v34, v136, v81
	v_mul_f32_e32 v81, v144, v35
	s_waitcnt lgkmcnt(0)
	v_pk_add_f32 v[18:19], v[2:3], v[18:19]
	ds_bpermute_b32 v83, v49, v19
	ds_bpermute_b32 v82, v49, v18
	v_add_u32_e32 v2, v150, v191
	v_mad_i64_i32 v[2:3], s[0:1], v2, s77, v[16:17]
	v_mul_f32_e32 v81, v131, v81
	s_waitcnt lgkmcnt(0)
	v_pk_add_f32 v[18:19], v[18:19], v[82:83]
	ds_bpermute_b32 v83, v64, v19
	ds_bpermute_b32 v82, v64, v18
	v_cvt_pk_bf16_f32 v81, v81, s0
	global_store_short v[2:3], v81, off
	v_mul_f32_e32 v81, v145, v35
	v_mul_f32_e32 v81, v130, v81
	s_waitcnt lgkmcnt(0)
; DI u16 f2bf(float a) { return (u16)(pk2(a, 0.f) & 0xffffu); }
; DI int crow(int i, int h) { return (i & 3) + 8 * (i >> 2) + 4 * h; }
; __device__ __forceinline__ void attn_item_A(const Params& p, int layer, int head, int q0u, char* lds) {
;     ...
; #pragma unroll
;   for (int e = 0; e < 16; ++e) {
;     const int qq = crow(e, h_e);
;     const float ia = __shfl(iA, qq), ib = __shfl(iB, qq);
;     float ov[4];
;     float ss = 0.f;
; #pragma unroll
;     for (int d = 0; d < 4; ++d) { ov[d] = o1[d][e] * ia - o2[d][e] * ib; ss += ov[d] * ov[d]; }
; #pragma unroll
;     for (int x = 16; x >= 1; x >>= 1) ss += __shfl_xor(ss, x);
;     const float rs = rsqrtf(ss * (1.f / 128.f) + LN_EPS);
;     const size_t rowoff = (size_t)(orow0 + qq) * LDX + ocol + r_e;
; #pragma unroll
;     for (int d = 0; d < 4; ++d) Mx[rowoff + d * 32] = f2bf(ov[d] * rs * sw[d]);
;   }
	v_pk_add_f32 v[18:19], v[18:19], v[82:83]
	ds_bpermute_b32 v83, v65, v19
	ds_bpermute_b32 v82, v65, v18
	v_cvt_pk_bf16_f32 v81, v81, s0
	global_store_short v[2:3], v81, off offset:64
	v_mul_f32_e32 v81, v97, v35
	v_mul_f32_e32 v81, v129, v81
	s_waitcnt lgkmcnt(0)
	v_pk_add_f32 v[18:19], v[18:19], v[82:83]
	ds_bpermute_b32 v83, v80, v19
	ds_bpermute_b32 v82, v80, v18
	v_cvt_pk_bf16_f32 v81, v81, s0
	global_store_short v[2:3], v81, off offset:128
	v_mov_b32_e32 v136, v116
	v_add_u32_e32 v116, 9, v134
	s_waitcnt lgkmcnt(0)
	v_pk_add_f32 v[18:19], v[18:19], v[82:83]
	v_mov_b32_e32 v138, v4
	v_pk_fma_f32 v[82:83], v[18:19], s[28:29], v[32:33] op_sel_hi:[1,0,0]
	v_and_or_b32 v4, v116, 61, v187
	v_mul_f32_e32 v18, 0x4b800000, v83
	v_cmp_gt_f32_e32 vcc, s80, v83
	v_mov_b32_e32 v139, v20
	v_lshlrev_b32_e32 v20, 2, v4
	v_cndmask_b32_e32 v18, v83, v18, vcc
	v_rsq_f32_e32 v81, v18
	v_add_u32_e32 v18, v152, v191
	v_mad_i64_i32 v[18:19], s[0:1], v18, s77, v[16:17]
	v_mul_f32_e32 v83, 0x45800000, v81
	v_cndmask_b32_e32 v81, v81, v83, vcc
	v_mul_f32_e32 v83, v140, v81
	v_mul_f32_e32 v83, v131, v83
	v_cvt_pk_bf16_f32 v83, v83, s0
	global_store_short v[18:19], v83, off
	v_mul_f32_e32 v83, v141, v81
	v_mul_f32_e32 v83, v130, v83
	v_cvt_pk_bf16_f32 v83, v83, s0
	global_store_short v[18:19], v83, off offset:64
	v_mul_f32_e32 v83, v113, v81
	v_mul_f32_e32 v83, v129, v83
	v_cvt_pk_bf16_f32 v113, v83, s0
	v_mul_f32_e32 v83, 0x4b800000, v82
	v_cmp_gt_f32_e32 vcc, s80, v82
	v_add_u32_e32 v141, 8, v134
	v_mul_f32_e32 v35, v96, v35
	v_cndmask_b32_e32 v82, v82, v83, vcc
	v_rsq_f32_e32 v140, v82
	v_and_or_b32 v82, v141, 60, v187
	v_lshlrev_b32_e32 v83, 2, v82
	ds_bpermute_b32 v96, v83, v132
	ds_bpermute_b32 v4, v20, v132
	ds_bpermute_b32 v82, v83, v133
	v_mov_b32_e32 v114, v52
	ds_bpermute_b32 v52, v20, v133
	v_mov_b32_e32 v115, v36
	v_mov_b32_e32 v36, v53
	v_mov_b32_e32 v98, v68
	v_mov_b32_e32 v99, v84
	s_waitcnt lgkmcnt(3)
	v_pk_mul_f32 v[114:115], v[114:115], v[96:97] op_sel_hi:[1,0]
	v_mov_b32_e32 v84, v69
	s_waitcnt lgkmcnt(2)
	v_pk_mul_f32 v[36:37], v[36:37], v[4:5] op_sel_hi:[1,0]
	v_mov_b32_e32 v20, v5
	global_store_short v[0:1], v137, off offset:128
	s_waitcnt lgkmcnt(1)
	v_pk_fma_f32 v[98:99], v[98:99], v[82:83], v[114:115] op_sel_hi:[1,0,1] neg_lo:[0,0,1] neg_hi:[0,0,1]
	v_mov_b32_e32 v137, v100
	v_pk_mul_f32 v[96:97], v[138:139], v[96:97] op_sel_hi:[1,0]
	s_waitcnt lgkmcnt(0)
	v_pk_fma_f32 v[68:69], v[84:85], v[52:53], v[36:37] op_sel_hi:[1,0,1] neg_lo:[0,0,1] neg_hi:[0,0,1]
	v_mov_b32_e32 v100, v117
	v_pk_mul_f32 v[4:5], v[20:21], v[4:5] op_sel_hi:[1,0]
	v_pk_mul_f32 v[114:115], v[98:99], v[98:99]
	v_pk_fma_f32 v[82:83], v[136:137], v[82:83], v[96:97] op_sel_hi:[1,0,1] neg_lo:[0,0,1] neg_hi:[0,0,1]
	v_pk_mul_f32 v[36:37], v[68:69], v[68:69]
	v_pk_fma_f32 v[52:53], v[100:101], v[52:53], v[4:5] op_sel_hi:[1,0,1] neg_lo:[0,0,1] neg_hi:[0,0,1]
	v_pk_mul_f32 v[96:97], v[82:83], v[82:83]
	v_pk_mul_f32 v[4:5], v[52:53], v[52:53]
	v_mov_b32_e32 v20, v36
	v_mov_b32_e32 v21, v114
	v_mov_b32_e32 v114, v37
	v_pk_add_f32 v[20:21], v[20:21], v[114:115]
	v_mov_b32_e32 v36, v5
	v_mov_b32_e32 v37, v97
	v_pk_add_f32 v[20:21], v[36:37], v[20:21]
	v_mov_b32_e32 v5, v96
	v_pk_add_f32 v[4:5], v[4:5], v[20:21]
	ds_bpermute_b32 v21, v48, v5
	ds_bpermute_b32 v20, v48, v4
	v_mul_f32_e32 v37, 0x45800000, v140
	v_cndmask_b32_e32 v37, v140, v37, vcc
	v_mul_f32_e32 v66, v66, v37
	v_mul_f32_e32 v66, v131, v66
	s_waitcnt lgkmcnt(0)
	v_pk_add_f32 v[20:21], v[4:5], v[20:21]
	ds_bpermute_b32 v85, v49, v21
	ds_bpermute_b32 v84, v49, v20
	v_add_u32_e32 v4, v135, v191
	v_mad_i64_i32 v[4:5], s[0:1], v4, s77, v[16:17]
	v_mul_f32_e32 v36, v112, v81
	s_waitcnt lgkmcnt(0)
	v_pk_add_f32 v[20:21], v[20:21], v[84:85]
	ds_bpermute_b32 v85, v64, v21
	ds_bpermute_b32 v84, v64, v20
	v_cvt_pk_bf16_f32 v66, v66, s0
	global_store_short v[4:5], v66, off
	v_mul_f32_e32 v81, v67, v37
	v_mul_f32_e32 v51, v51, v37
	s_waitcnt lgkmcnt(0)
	v_pk_add_f32 v[20:21], v[20:21], v[84:85]
	ds_bpermute_b32 v67, v65, v21
	ds_bpermute_b32 v66, v65, v20
	v_mul_f32_e32 v51, v129, v51
	v_cvt_pk_bf16_f32 v51, v51, s0
	global_store_short v[4:5], v51, off offset:128
	v_mul_f32_e32 v37, v50, v37
	s_waitcnt lgkmcnt(0)
	v_pk_add_f32 v[20:21], v[20:21], v[66:67]
	ds_bpermute_b32 v67, v80, v21
	ds_bpermute_b32 v66, v80, v20
	v_mul_f32_e32 v81, v130, v81
	v_cvt_pk_bf16_f32 v81, v81, s0
	global_store_short v[4:5], v81, off offset:64
	global_store_short v[18:19], v113, off offset:128
	s_waitcnt lgkmcnt(0)
	v_pk_add_f32 v[20:21], v[20:21], v[66:67]
	v_add_u32_e32 v113, 10, v134
	v_pk_fma_f32 v[50:51], v[20:21], s[28:29], v[32:33] op_sel_hi:[1,0,0]
	v_mov_b32_e32 v96, v54
	v_mul_f32_e32 v20, 0x4b800000, v51
	v_cmp_gt_f32_e32 vcc, s80, v51
	v_mov_b32_e32 v97, v38
	v_mov_b32_e32 v100, v6
	v_cndmask_b32_e32 v20, v51, v20, vcc
	v_rsq_f32_e32 v51, v20
	v_add_u32_e32 v20, v141, v191
	v_mad_i64_i32 v[20:21], s[0:1], v20, s77, v[16:17]
	v_mul_f32_e32 v66, 0x45800000, v51
	v_cndmask_b32_e32 v81, v51, v66, vcc
	v_mul_f32_e32 v51, v98, v81
	v_mul_f32_e32 v51, v131, v51
	v_cvt_pk_bf16_f32 v51, v51, s0
	global_store_short v[20:21], v51, off
	v_mul_f32_e32 v51, v99, v81
	v_mul_f32_e32 v51, v130, v51
	v_cvt_pk_bf16_f32 v51, v51, s0
	global_store_short v[20:21], v51, off offset:64
	v_mul_f32_e32 v51, v83, v81
	v_mul_f32_e32 v51, v129, v51
	v_cvt_pk_bf16_f32 v83, v51, s0
	v_mul_f32_e32 v51, 0x4b800000, v50
	v_cmp_gt_f32_e32 vcc, s80, v50
	v_mov_b32_e32 v101, v22
	v_mov_b32_e32 v84, v70
	v_cndmask_b32_e32 v50, v50, v51, vcc
	v_rsq_f32_e32 v112, v50
	v_and_or_b32 v50, v113, 62, v187
	v_lshlrev_b32_e32 v51, 2, v50
	ds_bpermute_b32 v66, v51, v132
	ds_bpermute_b32 v50, v51, v133
	v_mov_b32_e32 v85, v86
	v_mov_b32_e32 v98, v118
	v_mov_b32_e32 v99, v102
	s_waitcnt lgkmcnt(1)
; DI u16 f2bf(float a) { return (u16)(pk2(a, 0.f) & 0xffffu); }
; DI int crow(int i, int h) { return (i & 3) + 8 * (i >> 2) + 4 * h; }
; __device__ __forceinline__ void attn_item_A(const Params& p, int layer, int head, int q0u, char* lds) {
;     ...
; #pragma unroll
;   for (int e = 0; e < 16; ++e) {
;     const int qq = crow(e, h_e);
;     const float ia = __shfl(iA, qq), ib = __shfl(iB, qq);
;     float ov[4];
;     float ss = 0.f;
; #pragma unroll
;     for (int d = 0; d < 4; ++d) { ov[d] = o1[d][e] * ia - o2[d][e] * ib; ss += ov[d] * ov[d]; }
; #pragma unroll
;     for (int x = 16; x >= 1; x >>= 1) ss += __shfl_xor(ss, x);
;     const float rs = rsqrtf(ss * (1.f / 128.f) + LN_EPS);
;     const size_t rowoff = (size_t)(orow0 + qq) * LDX + ocol + r_e;
; #pragma unroll
;     for (int d = 0; d < 4; ++d) Mx[rowoff + d * 32] = f2bf(ov[d] * rs * sw[d]);
;   }
	v_pk_mul_f32 v[96:97], v[96:97], v[66:67] op_sel_hi:[1,0]
	v_pk_mul_f32 v[66:67], v[100:101], v[66:67] op_sel_hi:[1,0]
	s_waitcnt lgkmcnt(0)
	v_pk_fma_f32 v[84:85], v[84:85], v[50:51], v[96:97] op_sel_hi:[1,0,1] neg_lo:[0,0,1] neg_hi:[0,0,1]
	v_pk_fma_f32 v[50:51], v[98:99], v[50:51], v[66:67] op_sel_hi:[1,0,1] neg_lo:[0,0,1] neg_hi:[0,0,1]
	v_add_u32_e32 v98, 11, v134
	v_and_or_b32 v6, v98, 63, v187
	v_lshlrev_b32_e32 v22, 2, v6
	ds_bpermute_b32 v6, v22, v132
	ds_bpermute_b32 v54, v22, v133
	v_mov_b32_e32 v38, v55
	v_mov_b32_e32 v86, v71
	v_mov_b32_e32 v22, v7
	s_waitcnt lgkmcnt(1)
	v_pk_mul_f32 v[38:39], v[38:39], v[6:7] op_sel_hi:[1,0]
	v_mov_b32_e32 v102, v119
	s_waitcnt lgkmcnt(0)
	v_pk_fma_f32 v[70:71], v[86:87], v[54:55], v[38:39] op_sel_hi:[1,0,1] neg_lo:[0,0,1] neg_hi:[0,0,1]
	v_pk_mul_f32 v[6:7], v[22:23], v[6:7] op_sel_hi:[1,0]
	v_pk_mul_f32 v[96:97], v[84:85], v[84:85]
	v_pk_mul_f32 v[38:39], v[70:71], v[70:71]
	v_pk_fma_f32 v[54:55], v[102:103], v[54:55], v[6:7] op_sel_hi:[1,0,1] neg_lo:[0,0,1] neg_hi:[0,0,1]
	v_pk_mul_f32 v[66:67], v[50:51], v[50:51]
	v_pk_mul_f32 v[6:7], v[54:55], v[54:55]
	v_mov_b32_e32 v22, v38
	v_mov_b32_e32 v23, v96
	v_mov_b32_e32 v96, v39
	v_pk_add_f32 v[22:23], v[22:23], v[96:97]
	v_mov_b32_e32 v38, v7
	v_mov_b32_e32 v39, v67
	v_pk_add_f32 v[22:23], v[38:39], v[22:23]
	v_mov_b32_e32 v7, v66
	v_pk_add_f32 v[6:7], v[6:7], v[22:23]
	ds_bpermute_b32 v23, v48, v7
	ds_bpermute_b32 v22, v48, v6
	v_mul_f32_e32 v39, 0x45800000, v112
	v_cndmask_b32_e32 v39, v112, v39, vcc
	v_mul_f32_e32 v68, v68, v39
	v_mul_f32_e32 v53, v53, v39
	s_waitcnt lgkmcnt(0)
	v_pk_add_f32 v[22:23], v[6:7], v[22:23]
	ds_bpermute_b32 v67, v49, v23
	ds_bpermute_b32 v66, v49, v22
	v_add_u32_e32 v6, v116, v191
	v_mad_i64_i32 v[6:7], s[0:1], v6, s77, v[16:17]
	v_mul_f32_e32 v68, v131, v68
	s_waitcnt lgkmcnt(0)
	v_pk_add_f32 v[22:23], v[22:23], v[66:67]
	ds_bpermute_b32 v67, v64, v23
	ds_bpermute_b32 v66, v64, v22
	v_mul_f32_e32 v53, v129, v53
	v_cvt_pk_bf16_f32 v68, v68, s0
	v_cvt_pk_bf16_f32 v53, v53, s0
	global_store_short v[6:7], v68, off
	s_waitcnt lgkmcnt(0)
	v_pk_add_f32 v[22:23], v[22:23], v[66:67]
	ds_bpermute_b32 v67, v65, v23
	ds_bpermute_b32 v66, v65, v22
	v_mul_f32_e32 v68, v69, v39
	global_store_short v[6:7], v53, off offset:128
	v_mul_f32_e32 v39, v52, v39
	v_mul_f32_e32 v38, v82, v81
	s_waitcnt lgkmcnt(0)
	v_pk_add_f32 v[22:23], v[22:23], v[66:67]
	ds_bpermute_b32 v67, v80, v23
	ds_bpermute_b32 v66, v80, v22
	v_mul_f32_e32 v68, v130, v68
	v_cvt_pk_bf16_f32 v68, v68, s0
	v_add_u32_e32 v97, 16, v134
	global_store_short v[20:21], v83, off offset:128
	s_waitcnt lgkmcnt(0)
	v_pk_add_f32 v[22:23], v[22:23], v[66:67]
	v_mov_b32_e32 v82, v56
	v_pk_fma_f32 v[52:53], v[22:23], s[28:29], v[32:33] op_sel_hi:[1,0,0]
	v_mov_b32_e32 v83, v40
	v_mul_f32_e32 v22, 0x4b800000, v53
	v_cmp_gt_f32_e32 vcc, s80, v53
	v_mov_b32_e32 v86, v8
	v_mov_b32_e32 v87, v24
	v_cndmask_b32_e32 v22, v53, v22, vcc
	v_rsq_f32_e32 v53, v22
	v_add_u32_e32 v22, v113, v191
	v_mad_i64_i32 v[22:23], s[0:1], v22, s77, v[16:17]
	v_mul_f32_e32 v66, 0x45800000, v53
	v_cndmask_b32_e32 v81, v53, v66, vcc
	v_mul_f32_e32 v53, v84, v81
	v_mul_f32_e32 v53, v131, v53
	v_cvt_pk_bf16_f32 v53, v53, s0
	global_store_short v[22:23], v53, off
	v_mul_f32_e32 v53, v85, v81
	v_mul_f32_e32 v53, v130, v53
	v_cvt_pk_bf16_f32 v53, v53, s0
	global_store_short v[22:23], v53, off offset:64
	v_mul_f32_e32 v53, 0x4b800000, v52
	v_cmp_gt_f32_e32 vcc, s80, v52
	global_store_short v[6:7], v68, off offset:64
	v_mov_b32_e32 v68, v72
	v_cndmask_b32_e32 v52, v52, v53, vcc
	v_rsq_f32_e32 v96, v52
	v_and_or_b32 v52, v97, 60, v187
	v_lshlrev_b32_e32 v53, 2, v52
	ds_bpermute_b32 v66, v53, v132
	ds_bpermute_b32 v52, v53, v133
	v_mov_b32_e32 v69, v88
	v_mov_b32_e32 v84, v120
	v_mov_b32_e32 v85, v104
	s_waitcnt lgkmcnt(1)
	v_pk_mul_f32 v[82:83], v[82:83], v[66:67] op_sel_hi:[1,0]
	v_pk_mul_f32 v[66:67], v[86:87], v[66:67] op_sel_hi:[1,0]
	s_waitcnt lgkmcnt(0)
	v_pk_fma_f32 v[68:69], v[68:69], v[52:53], v[82:83] op_sel_hi:[1,0,1] neg_lo:[0,0,1] neg_hi:[0,0,1]
	v_pk_fma_f32 v[52:53], v[84:85], v[52:53], v[66:67] op_sel_hi:[1,0,1] neg_lo:[0,0,1] neg_hi:[0,0,1]
	v_add_u32_e32 v84, 17, v134
	v_and_or_b32 v8, v84, 61, v187
	v_lshlrev_b32_e32 v24, 2, v8
	ds_bpermute_b32 v8, v24, v132
	ds_bpermute_b32 v56, v24, v133
	v_mov_b32_e32 v40, v57
	v_mov_b32_e32 v88, v73
	v_mov_b32_e32 v24, v9
	s_waitcnt lgkmcnt(1)
	v_pk_mul_f32 v[40:41], v[40:41], v[8:9] op_sel_hi:[1,0]
	v_mov_b32_e32 v104, v121
	s_waitcnt lgkmcnt(0)
	v_pk_fma_f32 v[72:73], v[88:89], v[56:57], v[40:41] op_sel_hi:[1,0,1] neg_lo:[0,0,1] neg_hi:[0,0,1]
	v_pk_mul_f32 v[8:9], v[24:25], v[8:9] op_sel_hi:[1,0]
	v_pk_mul_f32 v[82:83], v[68:69], v[68:69]
	v_pk_mul_f32 v[40:41], v[72:73], v[72:73]
	v_pk_fma_f32 v[56:57], v[104:105], v[56:57], v[8:9] op_sel_hi:[1,0,1] neg_lo:[0,0,1] neg_hi:[0,0,1]
	v_pk_mul_f32 v[66:67], v[52:53], v[52:53]
	v_pk_mul_f32 v[8:9], v[56:57], v[56:57]
	v_mov_b32_e32 v24, v40
	v_mov_b32_e32 v25, v82
	v_mov_b32_e32 v82, v41
	v_pk_add_f32 v[24:25], v[24:25], v[82:83]
	v_mov_b32_e32 v40, v9
	v_mov_b32_e32 v41, v67
	v_pk_add_f32 v[24:25], v[40:41], v[24:25]
	v_mov_b32_e32 v9, v66
	v_pk_add_f32 v[8:9], v[8:9], v[24:25]
	ds_bpermute_b32 v25, v48, v9
	ds_bpermute_b32 v24, v48, v8
	v_mul_f32_e32 v51, v51, v81
	v_mul_f32_e32 v51, v129, v51
	v_cvt_pk_bf16_f32 v51, v51, s0
	global_store_short v[22:23], v51, off offset:128
	s_waitcnt lgkmcnt(0)
	v_pk_add_f32 v[24:25], v[8:9], v[24:25]
	v_mul_f32_e32 v40, v50, v81
	ds_bpermute_b32 v51, v49, v25
	ds_bpermute_b32 v50, v49, v24
	v_mul_f32_e32 v41, 0x45800000, v96
	v_cndmask_b32_e32 v41, v96, v41, vcc
	v_add_u32_e32 v8, v98, v191
	v_mul_f32_e32 v66, v70, v41
	s_waitcnt lgkmcnt(0)
; DI u16 f2bf(float a) { return (u16)(pk2(a, 0.f) & 0xffffu); }
; DI int crow(int i, int h) { return (i & 3) + 8 * (i >> 2) + 4 * h; }
; __device__ __forceinline__ void attn_item_A(const Params& p, int layer, int head, int q0u, char* lds) {
;     ...
; #pragma unroll
;   for (int e = 0; e < 16; ++e) {
;     const int qq = crow(e, h_e);
;     const float ia = __shfl(iA, qq), ib = __shfl(iB, qq);
;     float ov[4];
;     float ss = 0.f;
; #pragma unroll
;     for (int d = 0; d < 4; ++d) { ov[d] = o1[d][e] * ia - o2[d][e] * ib; ss += ov[d] * ov[d]; }
; #pragma unroll
;     for (int x = 16; x >= 1; x >>= 1) ss += __shfl_xor(ss, x);
;     const float rs = rsqrtf(ss * (1.f / 128.f) + LN_EPS);
;     const size_t rowoff = (size_t)(orow0 + qq) * LDX + ocol + r_e;
; #pragma unroll
;     for (int d = 0; d < 4; ++d) Mx[rowoff + d * 32] = f2bf(ov[d] * rs * sw[d]);
;   }
	v_pk_add_f32 v[24:25], v[24:25], v[50:51]
	ds_bpermute_b32 v51, v64, v25
	ds_bpermute_b32 v50, v64, v24
	v_mad_i64_i32 v[8:9], s[0:1], v8, s77, v[16:17]
	v_mul_f32_e32 v66, v131, v66
	s_nop 0
	v_cvt_pk_bf16_f32 v66, v66, s0
	s_waitcnt lgkmcnt(0)
	v_pk_add_f32 v[24:25], v[24:25], v[50:51]
	ds_bpermute_b32 v51, v65, v25
	ds_bpermute_b32 v50, v65, v24
	global_store_short v[8:9], v66, off
	v_mul_f32_e32 v66, v71, v41
	v_mul_f32_e32 v55, v55, v41
	v_mul_f32_e32 v41, v54, v41
	s_waitcnt lgkmcnt(0)
	v_pk_add_f32 v[24:25], v[24:25], v[50:51]
	ds_bpermute_b32 v51, v80, v25
	ds_bpermute_b32 v50, v80, v24
	v_mul_f32_e32 v66, v130, v66
	v_mul_f32_e32 v55, v129, v55
	v_cvt_pk_bf16_f32 v66, v66, s0
	v_cvt_pk_bf16_f32 v55, v55, s0
	s_waitcnt lgkmcnt(0)
	v_pk_add_f32 v[24:25], v[24:25], v[50:51]
	v_add_u32_e32 v86, 18, v134
	v_pk_fma_f32 v[50:51], v[24:25], s[28:29], v[32:33] op_sel_hi:[1,0,0]
	global_store_short v[8:9], v66, off offset:64
	v_mul_f32_e32 v24, 0x4b800000, v51
	v_cmp_gt_f32_e32 vcc, s80, v51
	v_mov_b32_e32 v66, v74
	v_add_u32_e32 v74, 19, v134
	v_cndmask_b32_e32 v24, v51, v24, vcc
	v_rsq_f32_e32 v51, v24
	v_add_u32_e32 v24, v97, v191
	v_mad_i64_i32 v[24:25], s[0:1], v24, s77, v[16:17]
	v_mul_f32_e32 v54, 0x45800000, v51
	v_cndmask_b32_e32 v81, v51, v54, vcc
	v_mul_f32_e32 v51, v68, v81
	v_mul_f32_e32 v51, v131, v51
	v_cvt_pk_bf16_f32 v51, v51, s0
	global_store_short v[24:25], v51, off
	v_mul_f32_e32 v51, v69, v81
	v_mul_f32_e32 v51, v130, v51
	v_cvt_pk_bf16_f32 v51, v51, s0
	global_store_short v[24:25], v51, off offset:64
	v_mul_f32_e32 v51, v53, v81
	v_mul_f32_e32 v51, v129, v51
	v_cvt_pk_bf16_f32 v53, v51, s0
	v_mul_f32_e32 v51, 0x4b800000, v50
	v_cmp_gt_f32_e32 vcc, s80, v50
	v_mov_b32_e32 v82, v10
	v_and_or_b32 v10, v74, 63, v187
	v_cndmask_b32_e32 v50, v50, v51, vcc
	v_rsq_f32_e32 v85, v50
	v_and_or_b32 v50, v86, 62, v187
	v_lshlrev_b32_e32 v51, 2, v50
	ds_bpermute_b32 v54, v51, v132
	ds_bpermute_b32 v50, v51, v133
	v_mov_b32_e32 v68, v58
	v_mov_b32_e32 v69, v42
	v_mov_b32_e32 v83, v26
	v_lshlrev_b32_e32 v26, 2, v10
	global_store_short v[8:9], v55, off offset:128
	v_mov_b32_e32 v67, v90
	s_waitcnt lgkmcnt(1)
	v_pk_mul_f32 v[68:69], v[68:69], v[54:55] op_sel_hi:[1,0]
	v_mov_b32_e32 v70, v122
	v_mov_b32_e32 v71, v106
	v_pk_mul_f32 v[54:55], v[82:83], v[54:55] op_sel_hi:[1,0]
	ds_bpermute_b32 v10, v26, v132
	s_waitcnt lgkmcnt(1)
	v_pk_fma_f32 v[66:67], v[66:67], v[50:51], v[68:69] op_sel_hi:[1,0,1] neg_lo:[0,0,1] neg_hi:[0,0,1]
	v_pk_fma_f32 v[50:51], v[70:71], v[50:51], v[54:55] op_sel_hi:[1,0,1] neg_lo:[0,0,1] neg_hi:[0,0,1]
	ds_bpermute_b32 v54, v26, v133
	v_mov_b32_e32 v42, v59
	v_mov_b32_e32 v90, v75
	s_waitcnt lgkmcnt(1)
	v_pk_mul_f32 v[42:43], v[42:43], v[10:11] op_sel_hi:[1,0]
	v_mov_b32_e32 v26, v11
	s_waitcnt lgkmcnt(0)
	v_pk_fma_f32 v[42:43], v[90:91], v[54:55], v[42:43] op_sel_hi:[1,0,1] neg_lo:[0,0,1] neg_hi:[0,0,1]
	v_mov_b32_e32 v106, v123
	v_pk_mul_f32 v[10:11], v[26:27], v[10:11] op_sel_hi:[1,0]
	v_pk_mul_f32 v[68:69], v[66:67], v[66:67]
	v_pk_mul_f32 v[58:59], v[42:43], v[42:43]
	v_pk_fma_f32 v[54:55], v[106:107], v[54:55], v[10:11] op_sel_hi:[1,0,1] neg_lo:[0,0,1] neg_hi:[0,0,1]
	v_pk_mul_f32 v[70:71], v[50:51], v[50:51]
	v_pk_mul_f32 v[10:11], v[54:55], v[54:55]
	v_mov_b32_e32 v26, v58
	v_mov_b32_e32 v27, v68
	v_mov_b32_e32 v68, v59
	v_pk_add_f32 v[26:27], v[26:27], v[68:69]
	v_mov_b32_e32 v58, v11
	v_mov_b32_e32 v59, v71
	v_pk_add_f32 v[26:27], v[58:59], v[26:27]
	v_mov_b32_e32 v11, v70
	v_pk_add_f32 v[10:11], v[10:11], v[26:27]
	ds_bpermute_b32 v27, v48, v11
	ds_bpermute_b32 v26, v48, v10
	v_mul_f32_e32 v75, v52, v81
	v_mul_f32_e32 v52, 0x45800000, v85
	global_store_short v[24:25], v53, off offset:128
	v_cndmask_b32_e32 v58, v85, v52, vcc
	s_waitcnt lgkmcnt(0)
	v_pk_add_f32 v[26:27], v[10:11], v[26:27]
	ds_bpermute_b32 v53, v49, v27
	ds_bpermute_b32 v52, v49, v26
	v_add_u32_e32 v10, v84, v191
	v_mul_f32_e32 v59, v72, v58
	v_mad_i64_i32 v[10:11], s[0:1], v10, s77, v[16:17]
	s_waitcnt lgkmcnt(0)
	v_pk_add_f32 v[26:27], v[26:27], v[52:53]
	ds_bpermute_b32 v53, v64, v27
	ds_bpermute_b32 v52, v64, v26
	v_mul_f32_e32 v59, v131, v59
	v_cvt_pk_bf16_f32 v59, v59, s0
	v_mul_f32_e32 v72, v56, v58
	global_store_short v[10:11], v59, off
	s_waitcnt lgkmcnt(0)
	v_pk_add_f32 v[26:27], v[26:27], v[52:53]
	ds_bpermute_b32 v53, v65, v27
	ds_bpermute_b32 v52, v65, v26
	v_mul_f32_e32 v59, v73, v58
	v_mul_f32_e32 v57, v57, v58
	v_mul_f32_e32 v59, v130, v59
	v_mul_f32_e32 v57, v129, v57
	s_waitcnt lgkmcnt(0)
	v_pk_add_f32 v[26:27], v[26:27], v[52:53]
	ds_bpermute_b32 v53, v80, v27
	ds_bpermute_b32 v52, v80, v26
	v_cvt_pk_bf16_f32 v59, v59, s0
	v_cvt_pk_bf16_f32 v57, v57, s0
	v_add_u32_e32 v82, 24, v134
	v_mov_b32_e32 v70, v12
	s_waitcnt lgkmcnt(0)
	v_pk_add_f32 v[26:27], v[26:27], v[52:53]
	v_mov_b32_e32 v71, v28
	v_pk_fma_f32 v[52:53], v[26:27], s[28:29], v[32:33] op_sel_hi:[1,0,0]
	global_store_short v[10:11], v57, off offset:128
	v_mul_f32_e32 v26, 0x4b800000, v53
	v_cmp_gt_f32_e32 vcc, s80, v53
	global_store_short v[10:11], v59, off offset:64
	v_mov_b32_e32 v58, v76
	v_cndmask_b32_e32 v26, v53, v26, vcc
	v_rsq_f32_e32 v53, v26
	v_add_u32_e32 v26, v86, v191
	v_mad_i64_i32 v[26:27], s[0:1], v26, s77, v[16:17]
	v_mul_f32_e32 v56, 0x45800000, v53
	v_cndmask_b32_e32 v73, v53, v56, vcc
	v_mul_f32_e32 v53, v66, v73
	v_mul_f32_e32 v53, v131, v53
	v_cvt_pk_bf16_f32 v53, v53, s0
	global_store_short v[26:27], v53, off
	v_mul_f32_e32 v53, v67, v73
	v_mul_f32_e32 v53, v130, v53
	v_cvt_pk_bf16_f32 v53, v53, s0
	global_store_short v[26:27], v53, off offset:64
	v_mul_f32_e32 v53, 0x4b800000, v52
	v_cmp_gt_f32_e32 vcc, s80, v52
	v_mov_b32_e32 v66, v60
	v_mov_b32_e32 v67, v44
	v_cndmask_b32_e32 v52, v52, v53, vcc
	v_rsq_f32_e32 v81, v52
	v_and_or_b32 v52, v82, 60, v187
	v_lshlrev_b32_e32 v53, 2, v52
	ds_bpermute_b32 v56, v53, v132
	ds_bpermute_b32 v52, v53, v133
	v_mov_b32_e32 v59, v92
	v_mov_b32_e32 v68, v124
	v_mov_b32_e32 v69, v108
	s_waitcnt lgkmcnt(1)
; DI u16 f2bf(float a) { return (u16)(pk2(a, 0.f) & 0xffffu); }
; DI int crow(int i, int h) { return (i & 3) + 8 * (i >> 2) + 4 * h; }
; __device__ __forceinline__ void attn_item_A(const Params& p, int layer, int head, int q0u, char* lds) {
;     ...
; #pragma unroll
;   for (int e = 0; e < 16; ++e) {
;     const int qq = crow(e, h_e);
;     const float ia = __shfl(iA, qq), ib = __shfl(iB, qq);
;     float ov[4];
;     float ss = 0.f;
; #pragma unroll
;     for (int d = 0; d < 4; ++d) { ov[d] = o1[d][e] * ia - o2[d][e] * ib; ss += ov[d] * ov[d]; }
; #pragma unroll
;     for (int x = 16; x >= 1; x >>= 1) ss += __shfl_xor(ss, x);
;     const float rs = rsqrtf(ss * (1.f / 128.f) + LN_EPS);
;     const size_t rowoff = (size_t)(orow0 + qq) * LDX + ocol + r_e;
; #pragma unroll
;     for (int d = 0; d < 4; ++d) Mx[rowoff + d * 32] = f2bf(ov[d] * rs * sw[d]);
;   }
	v_pk_mul_f32 v[66:67], v[66:67], v[56:57] op_sel_hi:[1,0]
	v_pk_mul_f32 v[56:57], v[70:71], v[56:57] op_sel_hi:[1,0]
	v_add_u32_e32 v70, 25, v134
	v_and_or_b32 v12, v70, 61, v187
	v_lshlrev_b32_e32 v28, 2, v12
	ds_bpermute_b32 v12, v28, v132
	s_waitcnt lgkmcnt(1)
	v_pk_fma_f32 v[58:59], v[58:59], v[52:53], v[66:67] op_sel_hi:[1,0,1] neg_lo:[0,0,1] neg_hi:[0,0,1]
	v_pk_fma_f32 v[52:53], v[68:69], v[52:53], v[56:57] op_sel_hi:[1,0,1] neg_lo:[0,0,1] neg_hi:[0,0,1]
	ds_bpermute_b32 v56, v28, v133
	v_mov_b32_e32 v44, v61
	v_mov_b32_e32 v92, v77
	s_waitcnt lgkmcnt(1)
	v_pk_mul_f32 v[44:45], v[44:45], v[12:13] op_sel_hi:[1,0]
	v_mov_b32_e32 v28, v13
	s_waitcnt lgkmcnt(0)
	v_pk_fma_f32 v[44:45], v[92:93], v[56:57], v[44:45] op_sel_hi:[1,0,1] neg_lo:[0,0,1] neg_hi:[0,0,1]
	v_mov_b32_e32 v108, v125
	v_pk_mul_f32 v[12:13], v[28:29], v[12:13] op_sel_hi:[1,0]
	v_pk_mul_f32 v[66:67], v[58:59], v[58:59]
	v_pk_mul_f32 v[60:61], v[44:45], v[44:45]
	v_pk_fma_f32 v[28:29], v[108:109], v[56:57], v[12:13] op_sel_hi:[1,0,1] neg_lo:[0,0,1] neg_hi:[0,0,1]
	v_pk_mul_f32 v[68:69], v[52:53], v[52:53]
	v_pk_mul_f32 v[12:13], v[28:29], v[28:29]
	v_mov_b32_e32 v56, v60
	v_mov_b32_e32 v57, v66
	v_mov_b32_e32 v66, v61
	v_pk_add_f32 v[56:57], v[56:57], v[66:67]
	v_mov_b32_e32 v60, v13
	v_mov_b32_e32 v61, v69
	v_pk_add_f32 v[56:57], v[60:61], v[56:57]
	v_mov_b32_e32 v13, v68
	v_pk_add_f32 v[12:13], v[12:13], v[56:57]
	ds_bpermute_b32 v57, v48, v13
	ds_bpermute_b32 v56, v48, v12
	v_mul_f32_e32 v51, v51, v73
	v_mul_f32_e32 v51, v129, v51
	v_cvt_pk_bf16_f32 v51, v51, s0
	v_mul_f32_e32 v68, v50, v73
	v_mul_f32_e32 v50, 0x45800000, v81
	global_store_short v[26:27], v51, off offset:128
	v_cndmask_b32_e32 v60, v81, v50, vcc
	s_waitcnt lgkmcnt(0)
	v_pk_add_f32 v[50:51], v[12:13], v[56:57]
	ds_bpermute_b32 v57, v49, v51
	ds_bpermute_b32 v56, v49, v50
	v_add_u32_e32 v12, v74, v191
	v_mul_f32_e32 v42, v42, v60
	v_mad_i64_i32 v[12:13], s[0:1], v12, s77, v[16:17]
	s_waitcnt lgkmcnt(0)
	v_pk_add_f32 v[50:51], v[50:51], v[56:57]
	ds_bpermute_b32 v57, v64, v51
	ds_bpermute_b32 v56, v64, v50
	v_mul_f32_e32 v42, v131, v42
	v_cvt_pk_bf16_f32 v42, v42, s0
	global_store_short v[12:13], v42, off
	v_mul_f32_e32 v61, v43, v60
	s_waitcnt lgkmcnt(0)
	v_pk_add_f32 v[42:43], v[50:51], v[56:57]
	ds_bpermute_b32 v51, v65, v43
	ds_bpermute_b32 v50, v65, v42
	v_mul_f32_e32 v69, v54, v60
	v_mul_f32_e32 v55, v55, v60
	v_mul_f32_e32 v56, v130, v61
	v_mul_f32_e32 v55, v129, v55
	s_waitcnt lgkmcnt(0)
	v_pk_add_f32 v[42:43], v[42:43], v[50:51]
	ds_bpermute_b32 v51, v80, v43
	ds_bpermute_b32 v50, v80, v42
	v_cvt_pk_bf16_f32 v56, v56, s0
	v_cvt_pk_bf16_f32 v55, v55, s0
	global_load_dword v128, v210, s[54:55] offset:384
	v_add_u32_e32 v74, 26, v134
	s_waitcnt lgkmcnt(0)
	v_pk_add_f32 v[42:43], v[42:43], v[50:51]
	v_add_u32_e32 v76, 27, v134
	v_pk_fma_f32 v[42:43], v[42:43], s[28:29], v[32:33] op_sel_hi:[1,0,0]
	v_mov_b32_e32 v66, v14
	v_mul_f32_e32 v50, 0x4b800000, v43
	v_cmp_gt_f32_e32 vcc, s80, v43
	v_mov_b32_e32 v67, v30
	v_and_or_b32 v14, v76, 63, v187
	v_cndmask_b32_e32 v43, v43, v50, vcc
	v_rsq_f32_e32 v43, v43
	v_add_u32_e32 v50, v82, v191
	v_mad_i64_i32 v[50:51], s[0:1], v50, s77, v[16:17]
	v_mul_f32_e32 v54, 0x45800000, v43
	v_cndmask_b32_e32 v71, v43, v54, vcc
	v_mul_f32_e32 v43, v58, v71
	v_mul_f32_e32 v43, v131, v43
	v_cvt_pk_bf16_f32 v43, v43, s0
	global_store_short v[50:51], v43, off
	v_mul_f32_e32 v43, v59, v71
	v_mul_f32_e32 v43, v130, v43
	v_cvt_pk_bf16_f32 v43, v43, s0
	global_store_short v[50:51], v43, off offset:64
	v_mul_f32_e32 v43, v53, v71
	v_mul_f32_e32 v43, v129, v43
	v_cvt_pk_bf16_f32 v53, v43, s0
	v_mul_f32_e32 v43, 0x4b800000, v42
	v_cmp_gt_f32_e32 vcc, s80, v42
	v_mov_b32_e32 v58, v62
	v_mov_b32_e32 v59, v46
	v_cndmask_b32_e32 v42, v42, v43, vcc
	v_rsq_f32_e32 v73, v42
	v_and_or_b32 v42, v74, 62, v187
	v_lshlrev_b32_e32 v43, 2, v42
	ds_bpermute_b32 v54, v43, v132
	ds_bpermute_b32 v42, v43, v133
	global_store_short v[12:13], v56, off offset:64
	global_store_short v[12:13], v55, off offset:128
	v_mov_b32_e32 v56, v78
	v_mov_b32_e32 v57, v94
	s_waitcnt lgkmcnt(1)
	v_pk_mul_f32 v[58:59], v[58:59], v[54:55] op_sel_hi:[1,0]
	v_mov_b32_e32 v60, v126
	v_mov_b32_e32 v61, v110
	v_pk_mul_f32 v[54:55], v[66:67], v[54:55] op_sel_hi:[1,0]
	v_lshlrev_b32_e32 v14, 2, v14
	s_waitcnt lgkmcnt(0)
	v_pk_fma_f32 v[56:57], v[56:57], v[42:43], v[58:59] op_sel_hi:[1,0,1] neg_lo:[0,0,1] neg_hi:[0,0,1]
	v_pk_fma_f32 v[42:43], v[60:61], v[42:43], v[54:55] op_sel_hi:[1,0,1] neg_lo:[0,0,1] neg_hi:[0,0,1]
	ds_bpermute_b32 v55, v14, v132
	ds_bpermute_b32 v54, v14, v133
	v_mov_b32_e32 v46, v63
	v_mov_b32_e32 v94, v79
	v_pk_mul_f32 v[58:59], v[56:57], v[56:57]
	s_waitcnt lgkmcnt(1)
	v_mov_b32_e32 v14, v55
	v_pk_mul_f32 v[46:47], v[46:47], v[14:15] op_sel_hi:[1,0]
	v_mov_b32_e32 v14, v127
	s_waitcnt lgkmcnt(0)
; DI u16 f2bf(float a) { return (u16)(pk2(a, 0.f) & 0xffffu); }
; DI int crow(int i, int h) { return (i & 3) + 8 * (i >> 2) + 4 * h; }
; __device__ __forceinline__ void attn_item_A(const Params& p, int layer, int head, int q0u, char* lds) {
;     ...
; #pragma unroll
;   for (int e = 0; e < 16; ++e) {
;     const int qq = crow(e, h_e);
;     const float ia = __shfl(iA, qq), ib = __shfl(iB, qq);
;     float ov[4];
;     float ss = 0.f;
; #pragma unroll
;     for (int d = 0; d < 4; ++d) { ov[d] = o1[d][e] * ia - o2[d][e] * ib; ss += ov[d] * ov[d]; }
; #pragma unroll
;     for (int x = 16; x >= 1; x >>= 1) ss += __shfl_xor(ss, x);
;     const float rs = rsqrtf(ss * (1.f / 128.f) + LN_EPS);
;     const size_t rowoff = (size_t)(orow0 + qq) * LDX + ocol + r_e;
; #pragma unroll
;     for (int d = 0; d < 4; ++d) Mx[rowoff + d * 32] = f2bf(ov[d] * rs * sw[d]);
;   }
	v_pk_mul_f32 v[14:15], v[14:15], v[54:55]
	v_pk_fma_f32 v[46:47], v[94:95], v[54:55], v[46:47] op_sel_hi:[1,0,1] neg_lo:[0,0,1] neg_hi:[0,0,1]
	v_mul_f32_e32 v67, v111, v54
	v_mul_f32_e32 v31, v31, v55
	v_mov_b32_e32 v66, v14
	v_mov_b32_e32 v30, v15
	v_pk_mul_f32 v[62:63], v[46:47], v[46:47]
	v_pk_add_f32 v[14:15], v[66:67], v[30:31] neg_lo:[0,1] neg_hi:[0,1]
	v_pk_mul_f32 v[60:61], v[42:43], v[42:43]
	v_pk_mul_f32 v[30:31], v[14:15], v[14:15]
	v_mov_b32_e32 v54, v62
	v_mov_b32_e32 v55, v58
	v_mov_b32_e32 v58, v63
	v_pk_add_f32 v[54:55], v[54:55], v[58:59]
	v_mov_b32_e32 v58, v31
	v_mov_b32_e32 v59, v61
	v_pk_add_f32 v[54:55], v[58:59], v[54:55]
	v_mov_b32_e32 v31, v60
	v_pk_add_f32 v[30:31], v[30:31], v[54:55]
	ds_bpermute_b32 v55, v48, v31
	ds_bpermute_b32 v54, v48, v30
	global_store_short v[50:51], v53, off offset:128
	v_mul_f32_e32 v58, v52, v71
	v_mul_f32_e32 v48, 0x45800000, v73
	v_cndmask_b32_e32 v59, v73, v48, vcc
	s_waitcnt lgkmcnt(0)
	v_pk_add_f32 v[30:31], v[30:31], v[54:55]
	ds_bpermute_b32 v53, v49, v31
	ds_bpermute_b32 v52, v49, v30
	v_add_u32_e32 v48, v70, v191
	v_mul_f32_e32 v44, v44, v59
	v_mad_i64_i32 v[48:49], s[0:1], v48, s77, v[16:17]
	s_waitcnt lgkmcnt(0)
	v_pk_add_f32 v[30:31], v[30:31], v[52:53]
	ds_bpermute_b32 v53, v64, v31
	ds_bpermute_b32 v52, v64, v30
	v_mul_f32_e32 v44, v131, v44
	v_cvt_pk_bf16_f32 v44, v44, s0
	global_store_short v[48:49], v44, off
	v_mul_f32_e32 v54, v45, v59
	s_waitcnt lgkmcnt(0)
	v_pk_add_f32 v[30:31], v[30:31], v[52:53]
	ds_bpermute_b32 v45, v65, v31
	ds_bpermute_b32 v44, v65, v30
	v_mul_f32_e32 v29, v29, v59
	v_mul_f32_e32 v52, v130, v54
	v_mul_f32_e32 v29, v129, v29
	v_cvt_pk_bf16_f32 v52, v52, s0
	s_waitcnt lgkmcnt(0)
	v_pk_add_f32 v[30:31], v[30:31], v[44:45]
	ds_bpermute_b32 v45, v80, v31
	ds_bpermute_b32 v44, v80, v30
	v_cvt_pk_bf16_f32 v29, v29, s0
	global_store_short v[48:49], v52, off offset:64
	global_store_short v[48:49], v29, off offset:128
	v_mul_f32_e32 v52, v28, v59
	s_waitcnt lgkmcnt(0)
	v_pk_add_f32 v[28:29], v[30:31], v[44:45]
	s_nop 0
	v_pk_fma_f32 v[28:29], v[28:29], s[28:29], v[32:33] op_sel_hi:[1,0,0]
	s_nop 0
	v_mul_f32_e32 v30, 0x4b800000, v29
	v_cmp_gt_f32_e32 vcc, s80, v29
	v_mul_f32_e32 v33, 0x4b800000, v28
	s_nop 0
	v_cndmask_b32_e32 v29, v29, v30, vcc
	v_rsq_f32_e32 v29, v29
	v_add_u32_e32 v30, v74, v191
	v_mad_i64_i32 v[30:31], s[0:1], v30, s77, v[16:17]
	v_mul_f32_e32 v32, 0x45800000, v29
	v_cndmask_b32_e32 v29, v29, v32, vcc
	v_mul_f32_e32 v32, v56, v29
	v_mul_f32_e32 v32, v131, v32
	v_cvt_pk_bf16_f32 v32, v32, s0
	global_store_short v[30:31], v32, off
	v_mul_f32_e32 v32, v57, v29
	v_cmp_gt_f32_e32 vcc, s80, v28
	v_mul_f32_e32 v32, v130, v32
	v_cvt_pk_bf16_f32 v32, v32, s0
	v_cndmask_b32_e32 v28, v28, v33, vcc
	v_rsq_f32_e32 v28, v28
	global_store_short v[30:31], v32, off offset:64
	v_mul_f32_e32 v32, v43, v29
	v_mul_f32_e32 v32, v129, v32
	v_cvt_pk_bf16_f32 v32, v32, s0
	global_store_short v[30:31], v32, off offset:128
	v_mul_f32_e32 v32, 0x45800000, v28
	v_cndmask_b32_e32 v167, v28, v32, vcc
	v_add_u32_e32 v28, v76, v191
	v_mad_i64_i32 v[16:17], s[0:1], v28, s77, v[16:17]
	v_mul_f32_e32 v28, v46, v167
	v_mul_f32_e32 v28, v131, v28
	v_cvt_pk_bf16_f32 v28, v28, s0
	v_mul_f32_e32 v15, v15, v167
	global_store_short v[16:17], v28, off
	v_mul_f32_e32 v28, v47, v167
	v_mul_f32_e32 v15, v129, v15
	v_mul_f32_e32 v28, v130, v28
	v_cvt_pk_bf16_f32 v15, v15, s0
	v_mov_b32_e32 v129, v14
	v_cvt_pk_bf16_f32 v28, v28, s0
	global_store_short v[16:17], v15, off offset:128
	s_waitcnt vmcnt(13)
	v_pk_mul_f32 v[14:15], v[128:129], v[166:167]
	global_store_short v[16:17], v28, off offset:64
	v_mul_f32_e32 v28, v14, v34
	v_cvt_pk_bf16_f32 v28, v28, s0
	global_store_short v[0:1], v28, off offset:192
	v_mul_f32_e32 v0, v14, v35
	v_cvt_pk_bf16_f32 v0, v0, s0
	global_store_short v[2:3], v0, off offset:192
	v_mul_f32_e32 v0, v14, v36
	v_cvt_pk_bf16_f32 v0, v0, s0
	global_store_short v[18:19], v0, off offset:192
	v_mul_f32_e32 v0, v14, v37
	v_cvt_pk_bf16_f32 v0, v0, s0
	global_store_short v[4:5], v0, off offset:192
	v_mul_f32_e32 v0, v14, v38
	v_cvt_pk_bf16_f32 v0, v0, s0
	global_store_short v[20:21], v0, off offset:192
	v_mul_f32_e32 v0, v14, v39
	v_cvt_pk_bf16_f32 v0, v0, s0
	global_store_short v[6:7], v0, off offset:192
	v_mul_f32_e32 v0, v14, v40
	v_cvt_pk_bf16_f32 v0, v0, s0
	global_store_short v[22:23], v0, off offset:192
	v_mul_f32_e32 v0, v14, v41
	v_cvt_pk_bf16_f32 v0, v0, s0
	global_store_short v[8:9], v0, off offset:192
	v_mul_f32_e32 v0, v14, v75
	v_cvt_pk_bf16_f32 v0, v0, s0
	global_store_short v[24:25], v0, off offset:192
	v_mul_f32_e32 v0, v14, v72
	v_cvt_pk_bf16_f32 v0, v0, s0
	global_store_short v[10:11], v0, off offset:192
	v_mul_f32_e32 v0, v14, v68
	v_cvt_pk_bf16_f32 v0, v0, s0
	global_store_short v[26:27], v0, off offset:192
	v_mul_f32_e32 v0, v14, v69
	v_cvt_pk_bf16_f32 v0, v0, s0
	global_store_short v[12:13], v0, off offset:192
	v_mul_f32_e32 v0, v14, v58
	v_cvt_pk_bf16_f32 v0, v0, s0
	global_store_short v[50:51], v0, off offset:192
	v_mul_f32_e32 v0, v14, v52
	v_mul_f32_e32 v29, v42, v29
	v_cvt_pk_bf16_f32 v0, v0, s0
	global_store_short v[48:49], v0, off offset:192
	v_mul_f32_e32 v0, v14, v29
	v_cvt_pk_bf16_f32 v0, v0, s0
	global_store_short v[30:31], v0, off offset:192
	v_mul_f32_e32 v0, v14, v15
	s_branch .LBB0_1476

; #define MFMA32(a, b, c) __builtin_amdgcn_mfma_f32_32x32x16_bf16((a), (b), (c), 0, 0, 0)
; __device__ __forceinline__ void attn_item_A(const Params& p, int layer, int head, int q0u, char* lds) {
;     ...
;   for (int t = 0; t < ntiles; ++t) {
;     const int buf = t & 1;
;     const bool more = (t + 1 < ntiles);
;     if (more) { ATT_LOADK(t + 1); ATT_LOADV(t + 1); }
;     const u16* kt_ = Ks + buf * 32 * KLD + r * KLD + 8 * h;
;     bf16x8 a0, a1, b0, b1;
;     {
;       f32x16 sx, sy;
; #pragma unroll
;       for (int e = 0; e < 16; ++e) { sx[e] = 0.f; sy[e] = 0.f; }
; #pragma unroll
;       for (int s = 0; s < 4; ++s) {
;         const bf16x8 kf = *(const bf16x8*)(kt_ + 16 * s);
;         const bf16x8 qf = *(const bf16x8*)(Qs + s * 1024);
;         sx = MFMA32(kf, qf, sx);
;       }
; #pragma unroll
;       for (int s = 4; s < 8; ++s) {
;         const bf16x8 kf = *(const bf16x8*)(kt_ + 16 * s);
;         const bf16x8 qf = *(const bf16x8*)(Qs + s * 1024);
;         sy = MFMA32(kf, qf, sy);
;       }
;       {
;         float w[16];
; #pragma unroll
;         for (int e = 0; e < 16; ++e) { w[e] = __builtin_amdgcn_exp2f(fmaf(sx[e], CS, -bA)); lA += w[e]; }
;         const u32x4 p0 = {pk2(w[0], w[1]), pk2(w[2], w[3]), pk2(w[4], w[5]), pk2(w[6], w[7])};
;         const u32x4 p1 = {pk2(w[8], w[9]), pk2(w[10], w[11]), pk2(w[12], w[13]), pk2(w[14], w[15])};
;         a0 = __builtin_bit_cast(bf16x8, p0); a1 = __builtin_bit_cast(bf16x8, p1);
;       }
;       {
;         float w[16];
; #pragma unroll
;         for (int e = 0; e < 16; ++e) { w[e] = __builtin_amdgcn_exp2f(fmaf(sy[e], CS, -bB)); lB += w[e]; }
;         const u32x4 p0 = {pk2(w[0], w[1]), pk2(w[2], w[3]), pk2(w[4], w[5]), pk2(w[6], w[7])};
;         const u32x4 p1 = {pk2(w[8], w[9]), pk2(w[10], w[11]), pk2(w[12], w[13]), pk2(w[14], w[15])};
;         b0 = __builtin_bit_cast(bf16x8, p0); b1 = __builtin_bit_cast(bf16x8, p1);
;       }
;     }
;     const u16* vt = Vt + buf * 128 * VLD + r * VLD + 4 * h;
; #pragma unroll
;     for (int d = 0; d < 4; d += 2) {
;       const s16x4 l0 = *(const s16x4*)(vt + d * 32 * VLD), h0 = *(const s16x4*)(vt + d * 32 * VLD + 8);
;       const s16x4 l1 = *(const s16x4*)(vt + d * 32 * VLD + 16), h1 = *(const s16x4*)(vt + d * 32 * VLD + 24);
;       const s16x4 m0 = *(const s16x4*)(vt + (d + 1) * 32 * VLD), n0 = *(const s16x4*)(vt + (d + 1) * 32 * VLD + 8);
.LBB0_2327:
	s_setprio 1
	s_and_b32 s0, s8, 1
	s_mul_i32 s1, s0, 0x2200
	v_add_u32_e32 v196, v192, v193
	v_add_u32_e32 v197, s1, v195
	ds_read_b128 v[128:131], v196 offset:37888
	ds_read_b128 v[160:163], v196 offset:38912
	ds_read_b128 v[144:147], v196 offset:41984
	ds_read_b128 v[178:181], v196 offset:43008
	ds_read_b128 v[132:135], v197
	ds_read_b128 v[198:201], v197 offset:32
	ds_read_b128 v[148:151], v197 offset:128
	ds_read_b128 v[202:205], v197 offset:160
	ds_read_b128 v[206:209], v197 offset:64
	ds_read_b128 v[216:219], v197 offset:96
	ds_read_b128 v[220:223], v197 offset:192
	ds_read_b128 v[224:227], v197 offset:224
	s_waitcnt lgkmcnt(7)
	v_mfma_f32_32x32x16_bf16 v[128:143], v[132:135], v[128:131], 0
	s_mul_i32 s1, s0, 0x2400
	s_ashr_i32 s7, s6, 31
	s_xor_b32 s0, s0, 1
	s_add_i32 s8, s8, 1
	s_waitcnt lgkmcnt(5)
	v_mfma_f32_32x32x16_bf16 v[144:159], v[148:151], v[144:147], 0
	v_mfma_f32_32x32x16_bf16 v[128:143], v[198:201], v[160:163], v[128:143]
	s_waitcnt lgkmcnt(4)
	v_mfma_f32_32x32x16_bf16 v[144:159], v[202:205], v[178:181], v[144:159]
	s_waitcnt lgkmcnt(3)
	v_mfma_f32_32x32x16_bf16 v[128:143], v[206:209], v[240:243], v[128:143]
	v_add_u32_e32 v197, s1, v164
	v_add_u32_e32 v210, 0x4000, v197
	v_add_u32_e32 v215, 0x4800, v197
	v_add_u32_e32 v238, 0x5000, v197
	v_add_u32_e32 v197, 0x5800, v197
	v_lshl_add_u64 v[178:179], s[6:7], 1, v[170:171]
	s_waitcnt lgkmcnt(1)
	v_mfma_f32_32x32x16_bf16 v[144:159], v[220:223], v[248:251], v[144:159]
	v_add_u32_e32 v160, s6, v194
	v_mad_i64_i32 v[180:181], s[10:11], v160, s68, v[176:177]
	global_load_dwordx4 v[160:163], v[180:181], off offset:1040
	s_add_i32 s6, s6, 32
	s_mul_i32 s1, s0, 0x2200
	s_mulk_i32 s0, 0x2400
	v_mfma_f32_32x32x16_bf16 v[128:143], v[216:219], v[244:247], v[128:143]
	ds_read2_b64 v[198:201], v210 offset0:128 offset1:130
	s_cmpk_eq_i32 s6, 0x4100
	s_waitcnt lgkmcnt(1)
	v_mfma_f32_32x32x16_bf16 v[144:159], v[224:227], v[252:255], v[144:159]
	s_setprio 0
	s_nop 7
	v_fmamk_f32 v128, v128, 0x3e38aa3b, v175
	v_fmamk_f32 v129, v129, 0x3e38aa3b, v175
	v_fmamk_f32 v130, v130, 0x3e38aa3b, v175
	v_fmamk_f32 v131, v131, 0x3e38aa3b, v175
	v_fmamk_f32 v132, v132, 0x3e38aa3b, v175
	v_fmamk_f32 v133, v133, 0x3e38aa3b, v175
	v_fmamk_f32 v202, v134, 0x3e38aa3b, v175
	v_fmamk_f32 v135, v135, 0x3e38aa3b, v175
	v_fmamk_f32 v203, v144, 0x3e38aa3b, v173
	v_fmamk_f32 v145, v145, 0x3e38aa3b, v173
	v_fmamk_f32 v204, v146, 0x3e38aa3b, v173
	v_fmamk_f32 v205, v147, 0x3e38aa3b, v173
	v_fmamk_f32 v206, v148, 0x3e38aa3b, v173
	v_fmamk_f32 v207, v149, 0x3e38aa3b, v173
	v_fmamk_f32 v208, v150, 0x3e38aa3b, v173
	v_fmamk_f32 v209, v151, 0x3e38aa3b, v173
	v_exp_f32_e32 v150, v128
	v_exp_f32_e32 v148, v129
	v_exp_f32_e32 v146, v130
	v_exp_f32_e32 v144, v131
	v_exp_f32_e32 v134, v132
	v_exp_f32_e32 v130, v133
	v_exp_f32_e32 v132, v202
	v_exp_f32_e32 v128, v135
	v_exp_f32_e32 v151, v203
	v_exp_f32_e32 v149, v145
	v_exp_f32_e32 v147, v204
	v_exp_f32_e32 v145, v205
	v_exp_f32_e32 v135, v206
	v_exp_f32_e32 v131, v207
	v_exp_f32_e32 v133, v208
	v_exp_f32_e32 v129, v209
	v_cvt_pk_bf16_f32 v202, v150, v148
	v_cvt_pk_bf16_f32 v203, v146, v144
	v_cvt_pk_bf16_f32 v204, v134, v130
	v_cvt_pk_bf16_f32 v205, v132, v128
	v_cvt_pk_bf16_f32 v206, v151, v149
	v_cvt_pk_bf16_f32 v207, v147, v145
	v_cvt_pk_bf16_f32 v208, v135, v131
	v_cvt_pk_bf16_f32 v209, v133, v129
	s_setprio 1
	s_waitcnt lgkmcnt(0)
	v_mfma_f32_32x32x16_bf16 v[64:79], v[202:205], v[198:201], v[64:79]
	v_fmamk_f32 v152, v152, 0x3e38aa3b, v173
	v_fmamk_f32 v153, v153, 0x3e38aa3b, v173
	v_fmamk_f32 v154, v154, 0x3e38aa3b, v173
	v_fmamk_f32 v155, v155, 0x3e38aa3b, v173
	v_fmamk_f32 v156, v156, 0x3e38aa3b, v173
	v_fmamk_f32 v157, v157, 0x3e38aa3b, v173
	v_fmamk_f32 v158, v158, 0x3e38aa3b, v173
	v_mfma_f32_32x32x16_bf16 v[48:63], v[206:209], v[198:201], v[48:63]
	ds_read2_b64 v[198:201], v215 offset0:160 offset1:162
	ds_read2_b64 v[216:219], v210 offset0:132 offset1:134
	ds_read2_b64 v[220:223], v238 offset0:192 offset1:194
	ds_read2_b64 v[224:227], v197 offset0:224 offset1:226
	v_fmamk_f32 v159, v159, 0x3e38aa3b, v173
	v_exp_f32_e32 v213, v152
	v_exp_f32_e32 v229, v153
	v_exp_f32_e32 v231, v154
	v_exp_f32_e32 v233, v157
	s_waitcnt lgkmcnt(1)
	v_mfma_f32_32x32x16_bf16 v[96:111], v[202:205], v[220:223], v[96:111]
	v_exp_f32_e32 v235, v158
	v_exp_f32_e32 v237, v159
	v_fmamk_f32 v136, v136, 0x3e38aa3b, v175
	v_fmamk_f32 v137, v137, 0x3e38aa3b, v175
	v_fmamk_f32 v138, v138, 0x3e38aa3b, v175
	v_fmamk_f32 v139, v139, 0x3e38aa3b, v175
	v_fmamk_f32 v140, v140, 0x3e38aa3b, v175
	v_mfma_f32_32x32x16_bf16 v[16:31], v[206:209], v[220:223], v[16:31]
	v_exp_f32_e32 v221, v155
	v_exp_f32_e32 v223, v156
	global_load_dwordx4 v[152:155], v[180:181], off offset:1024
	global_load_dwordx4 v[156:159], v[178:179], off
	v_fmamk_f32 v141, v141, 0x3e38aa3b, v175
	global_load_dwordx4 v[178:181], v[178:179], off offset:16
	v_fmamk_f32 v142, v142, 0x3e38aa3b, v175
	v_fmamk_f32 v143, v143, 0x3e38aa3b, v175
	v_exp_f32_e32 v212, v136
	v_exp_f32_e32 v228, v137
	v_exp_f32_e32 v230, v138
	v_exp_f32_e32 v220, v139
	v_exp_f32_e32 v222, v140
	v_exp_f32_e32 v232, v141
	v_exp_f32_e32 v234, v142
	v_exp_f32_e32 v236, v143
	v_mfma_f32_32x32x16_bf16 v[80:95], v[202:205], v[198:201], v[80:95]
	v_cvt_pk_bf16_f32 v136, v212, v228
	v_cvt_pk_bf16_f32 v137, v230, v220
	v_cvt_pk_bf16_f32 v138, v222, v232
	v_cvt_pk_bf16_f32 v139, v234, v236
	v_cvt_pk_bf16_f32 v140, v213, v229
	v_cvt_pk_bf16_f32 v141, v231, v221
	v_cvt_pk_bf16_f32 v142, v223, v233
	v_mfma_f32_32x32x16_bf16 v[32:47], v[206:209], v[198:201], v[32:47]
	v_cvt_pk_bf16_f32 v143, v235, v237
	ds_read2_b64 v[198:201], v215 offset0:164 offset1:166
	v_add_f32_e64 v150, v168, v150
	v_add_f32_e64 v151, v169, v151
	v_add_f32_e64 v148, v148, v150
	v_add_f32_e64 v149, v149, v151
	v_pk_add_f32 v[146:147], v[146:147], v[148:149]
	s_waitcnt lgkmcnt(1)
; #define MFMA32(a, b, c) __builtin_amdgcn_mfma_f32_32x32x16_bf16((a), (b), (c), 0, 0, 0)
; __device__ __forceinline__ void attn_item_A(const Params& p, int layer, int head, int q0u, char* lds) {
;     ...
;   for (int t = 0; t < ntiles; ++t) {
;     const int buf = t & 1;
;     const bool more = (t + 1 < ntiles);
;     if (more) { ATT_LOADK(t + 1); ATT_LOADV(t + 1); }
;     const u16* kt_ = Ks + buf * 32 * KLD + r * KLD + 8 * h;
;     bf16x8 a0, a1, b0, b1;
;     {
;       f32x16 sx, sy;
; #pragma unroll
;       for (int e = 0; e < 16; ++e) { sx[e] = 0.f; sy[e] = 0.f; }
; #pragma unroll
;       for (int s = 0; s < 4; ++s) {
;         const bf16x8 kf = *(const bf16x8*)(kt_ + 16 * s);
;         const bf16x8 qf = *(const bf16x8*)(Qs + s * 1024);
;         sx = MFMA32(kf, qf, sx);
;       }
; #pragma unroll
;       for (int s = 4; s < 8; ++s) {
;         const bf16x8 kf = *(const bf16x8*)(kt_ + 16 * s);
;         const bf16x8 qf = *(const bf16x8*)(Qs + s * 1024);
;         sy = MFMA32(kf, qf, sy);
;       }
;       {
;         float w[16];
; #pragma unroll
;         for (int e = 0; e < 16; ++e) { w[e] = __builtin_amdgcn_exp2f(fmaf(sx[e], CS, -bA)); lA += w[e]; }
;         const u32x4 p0 = {pk2(w[0], w[1]), pk2(w[2], w[3]), pk2(w[4], w[5]), pk2(w[6], w[7])};
;         const u32x4 p1 = {pk2(w[8], w[9]), pk2(w[10], w[11]), pk2(w[12], w[13]), pk2(w[14], w[15])};
;         a0 = __builtin_bit_cast(bf16x8, p0); a1 = __builtin_bit_cast(bf16x8, p1);
;       }
;       {
;         float w[16];
; #pragma unroll
;         for (int e = 0; e < 16; ++e) { w[e] = __builtin_amdgcn_exp2f(fmaf(sy[e], CS, -bB)); lB += w[e]; }
;         const u32x4 p0 = {pk2(w[0], w[1]), pk2(w[2], w[3]), pk2(w[4], w[5]), pk2(w[6], w[7])};
;         const u32x4 p1 = {pk2(w[8], w[9]), pk2(w[10], w[11]), pk2(w[12], w[13]), pk2(w[14], w[15])};
;         b0 = __builtin_bit_cast(bf16x8, p0); b1 = __builtin_bit_cast(bf16x8, p1);
;       }
;     }
;     const u16* vt = Vt + buf * 128 * VLD + r * VLD + 4 * h;
; #pragma unroll
;     for (int d = 0; d < 4; d += 2) {
;       const s16x4 l0 = *(const s16x4*)(vt + d * 32 * VLD), h0 = *(const s16x4*)(vt + d * 32 * VLD + 8);
;       const s16x4 l1 = *(const s16x4*)(vt + d * 32 * VLD + 16), h1 = *(const s16x4*)(vt + d * 32 * VLD + 24);
;       const s16x4 m0 = *(const s16x4*)(vt + (d + 1) * 32 * VLD), n0 = *(const s16x4*)(vt + (d + 1) * 32 * VLD + 8);
	v_mfma_f32_32x32x16_bf16 v[112:127], v[202:205], v[224:227], v[112:127]
	ds_read2_b64 v[202:205], v197 offset0:228 offset1:230
	v_add_f32_e64 v144, v144, v146
	v_add_f32_e64 v145, v145, v147
	v_add_f32_e64 v134, v134, v144
	v_add_f32_e64 v135, v135, v145
	v_pk_add_f32 v[130:131], v[130:131], v[134:135]
	v_mfma_f32_32x32x16_bf16 v[0:15], v[206:209], v[224:227], v[0:15]
	v_add_f32_e64 v130, v132, v130
	v_add_f32_e64 v131, v133, v131
	v_add_u32_e32 v206, s1, v172
	v_add_f32_e64 v128, v128, v130
	v_add_f32_e64 v129, v129, v131
	v_add_u32_e32 v207, s0, v174
	v_pk_add_f32 v[128:129], v[212:213], v[128:129]
	v_add_u32_e32 v197, 0x4400, v207
	v_pk_add_f32 v[128:129], v[228:229], v[128:129]
	s_waitcnt lgkmcnt(1)
	v_mfma_f32_32x32x16_bf16 v[80:95], v[136:139], v[198:201], v[80:95]
	v_add_f32_e64 v128, v230, v128
	v_add_f32_e64 v129, v231, v129
	v_add_u32_e32 v207, 0x4410, v207
	v_add_f32_e64 v128, v220, v128
	v_add_f32_e64 v129, v221, v129
	v_pk_add_f32 v[128:129], v[222:223], v[128:129]
	s_nop 0
	v_pk_add_f32 v[128:129], v[232:233], v[128:129]
	v_mfma_f32_32x32x16_bf16 v[32:47], v[140:143], v[198:201], v[32:47]
	ds_read2_b64 v[198:201], v238 offset0:196 offset1:198
	v_add_f32_e64 v128, v234, v128
	v_add_f32_e64 v129, v235, v129
	s_setprio 0
	s_waitcnt vmcnt(2)
	ds_write_b128 v206, v[152:155]
	ds_write_b128 v206, v[160:163] offset:16
	s_waitcnt vmcnt(1)
	ds_write2_b64 v197, v[156:157], v[158:159] offset1:1
	s_waitcnt vmcnt(0)
	ds_write2_b64 v207, v[178:179], v[180:181] offset1:1
	v_mfma_f32_32x32x16_bf16 v[64:79], v[136:139], v[216:219], v[64:79]
	v_add_f32_e64 v168, v236, v128
	v_add_f32_e64 v169, v237, v129
	s_waitcnt lgkmcnt(0)
	s_barrier
	v_mfma_f32_32x32x16_bf16 v[48:63], v[140:143], v[216:219], v[48:63]
	v_mfma_f32_32x32x16_bf16 v[96:111], v[136:139], v[198:201], v[96:111]
	v_mfma_f32_32x32x16_bf16 v[16:31], v[140:143], v[198:201], v[16:31]
	v_mfma_f32_32x32x16_bf16 v[112:127], v[136:139], v[202:205], v[112:127]
	v_mfma_f32_32x32x16_bf16 v[0:15], v[140:143], v[202:205], v[0:15]
	s_cbranch_scc0 .LBB0_2327
	ds_read_b128 v[128:131], v195 offset:8704
	ds_read_b128 v[132:135], v196 offset:37888
	ds_read_b128 v[136:139], v195 offset:8736
	ds_read_b128 v[140:143], v196 offset:38912
	s_waitcnt lgkmcnt(2)
	v_mfma_f32_32x32x16_bf16 v[144:159], v[128:131], v[132:135], 0
	ds_read_b128 v[128:131], v195 offset:8768
	ds_read_b128 v[132:135], v196 offset:39936
	ds_read_b128 v[160:163], v195 offset:8800
	ds_read_b128 v[176:179], v196 offset:40960
	s_waitcnt lgkmcnt(4)
	v_mfma_f32_32x32x16_bf16 v[144:159], v[136:139], v[140:143], v[144:159]
	s_waitcnt lgkmcnt(2)
	v_mfma_f32_32x32x16_bf16 v[144:159], v[128:131], v[132:135], v[144:159]
	ds_read_b128 v[128:131], v195 offset:8832
	ds_read_b128 v[132:135], v196 offset:41984
	ds_read_b128 v[198:201], v195 offset:8864
	ds_read_b128 v[202:205], v196 offset:43008
	ds_read_b128 v[206:209], v195 offset:8896
	ds_read_b128 v[192:195], v195 offset:8928
	ds_read_b128 v[216:219], v196 offset:44032
	ds_read_b128 v[220:223], v196 offset:45056
	s_waitcnt lgkmcnt(6)
	v_mfma_f32_32x32x16_bf16 v[128:143], v[128:131], v[132:135], 0
	s_waitcnt lgkmcnt(4)
	v_mfma_f32_32x32x16_bf16 v[128:143], v[198:201], v[202:205], v[128:143]
	s_waitcnt lgkmcnt(1)
	v_mfma_f32_32x32x16_bf16 v[128:143], v[206:209], v[216:219], v[128:143]
	s_waitcnt lgkmcnt(0)
	v_mfma_f32_32x32x16_bf16 v[128:143], v[192:195], v[220:223], v[128:143]
	v_mfma_f32_32x32x16_bf16 v[144:159], v[160:163], v[176:179], v[144:159]
	s_nop 10
	v_fmamk_f32 v128, v128, 0x3e38aa3b, v173
	v_exp_f32_e32 v192, v128
	v_fmamk_f32 v128, v129, 0x3e38aa3b, v173
	v_exp_f32_e32 v193, v128
	v_fmamk_f32 v128, v130, 0x3e38aa3b, v173
	v_exp_f32_e32 v194, v128
	v_fmamk_f32 v128, v131, 0x3e38aa3b, v173
	v_exp_f32_e32 v195, v128
	v_fmamk_f32 v128, v132, 0x3e38aa3b, v173
	v_fmamk_f32 v132, v134, 0x3e38aa3b, v173
	v_fmamk_f32 v144, v144, 0x3e38aa3b, v175
	v_fmamk_f32 v145, v145, 0x3e38aa3b, v175
	v_fmamk_f32 v146, v146, 0x3e38aa3b, v175
	v_fmamk_f32 v147, v147, 0x3e38aa3b, v175
	v_fmamk_f32 v148, v148, 0x3e38aa3b, v175
	v_fmamk_f32 v149, v149, 0x3e38aa3b, v175
	v_fmamk_f32 v150, v150, 0x3e38aa3b, v175
	v_fmamk_f32 v151, v151, 0x3e38aa3b, v175
	v_exp_f32_e32 v201, v128
	v_fmamk_f32 v128, v133, 0x3e38aa3b, v173
	v_exp_f32_e32 v203, v132
	v_fmamk_f32 v132, v135, 0x3e38aa3b, v173
	v_exp_f32_e32 v170, v144
	v_exp_f32_e32 v171, v145
	v_exp_f32_e32 v172, v146
	v_exp_f32_e32 v174, v147
	v_exp_f32_e32 v176, v148
	v_exp_f32_e32 v177, v149
	v_exp_f32_e32 v178, v150
	v_exp_f32_e32 v179, v151
	v_fmamk_f32 v144, v155, 0x3e38aa3b, v175
	v_exp_f32_e32 v202, v128
	v_exp_f32_e32 v204, v132
	v_exp_f32_e32 v197, v144
	v_fmamk_f32 v144, v156, 0x3e38aa3b, v175
	v_fmamk_f32 v152, v152, 0x3e38aa3b, v175
	v_exp_f32_e32 v198, v144
	v_fmamk_f32 v144, v157, 0x3e38aa3b, v175
	v_exp_f32_e32 v180, v152
	v_exp_f32_e32 v199, v144
	v_fmamk_f32 v144, v158, 0x3e38aa3b, v175
	v_add_u32_e32 v152, 0x6800, v164
	v_fmamk_f32 v136, v136, 0x3e38aa3b, v173
	v_exp_f32_e32 v200, v144
	v_cvt_pk_bf16_f32 v144, v170, v171
	v_cvt_pk_bf16_f32 v145, v172, v174
	v_cvt_pk_bf16_f32 v146, v176, v177
	v_cvt_pk_bf16_f32 v147, v178, v179
	ds_read2_b64 v[128:131], v152 offset1:2
	v_cvt_pk_bf16_f32 v132, v192, v193
	v_cvt_pk_bf16_f32 v133, v194, v195
	v_cvt_pk_bf16_f32 v134, v201, v202
	v_cvt_pk_bf16_f32 v135, v203, v204
	v_exp_f32_e32 v205, v136
	v_fmamk_f32 v136, v137, 0x3e38aa3b, v173
	v_exp_f32_e32 v206, v136
	v_fmamk_f32 v136, v138, 0x3e38aa3b, v173
	v_exp_f32_e32 v207, v136
	v_fmamk_f32 v136, v139, 0x3e38aa3b, v173
	v_fmamk_f32 v153, v153, 0x3e38aa3b, v175
	v_exp_f32_e32 v208, v136
	v_fmamk_f32 v136, v140, 0x3e38aa3b, v173
	v_exp_f32_e32 v181, v153
	v_add_u32_e32 v153, 0x7000, v164
	v_exp_f32_e32 v209, v136
	v_fmamk_f32 v136, v141, 0x3e38aa3b, v173
	v_fmamk_f32 v154, v154, 0x3e38aa3b, v175
	v_fmac_f32_e32 v175, 0x3e38aa3b, v159
	s_waitcnt lgkmcnt(0)
; __device__ __forceinline__ void attn_item_A(const Params& p, int layer, int head, int q0u, char* lds) {
;     ...
;     const u16* vt = Vt + buf * 128 * VLD + r * VLD + 4 * h;
; #pragma unroll
;     for (int d = 0; d < 4; d += 2) {
;       const s16x4 l0 = *(const s16x4*)(vt + d * 32 * VLD), h0 = *(const s16x4*)(vt + d * 32 * VLD + 8);
;       const s16x4 l1 = *(const s16x4*)(vt + d * 32 * VLD + 16), h1 = *(const s16x4*)(vt + d * 32 * VLD + 24);
;       const s16x4 m0 = *(const s16x4*)(vt + (d + 1) * 32 * VLD), n0 = *(const s16x4*)(vt + (d + 1) * 32 * VLD + 8);
;       const s16x4 m1 = *(const s16x4*)(vt + (d + 1) * 32 * VLD + 16), n1 = *(const s16x4*)(vt + (d + 1) * 32 * VLD + 24);
;       const bf16x8 v0 = {l0[0], l0[1], l0[2], l0[3], h0[0], h0[1], h0[2], h0[3]};
;       const bf16x8 v1 = {l1[0], l1[1], l1[2], l1[3], h1[0], h1[1], h1[2], h1[3]};
;       const bf16x8 u0 = {m0[0], m0[1], m0[2], m0[3], n0[0], n0[1], n0[2], n0[3]};
;       const bf16x8 u1 = {m1[0], m1[1], m1[2], m1[3], n1[0], n1[1], n1[2], n1[3]};
;       o1[d] = MFMA32(a0, v0, o1[d]);
;       o2[d] = MFMA32(b0, v0, o2[d]);
;       o1[d + 1] = MFMA32(a0, u0, o1[d + 1]);
;       o2[d + 1] = MFMA32(b0, u0, o2[d + 1]);
;       o1[d] = MFMA32(a1, v1, o1[d]);
;       o2[d] = MFMA32(b1, v1, o2[d]);
;       o1[d + 1] = MFMA32(a1, u1, o1[d + 1]);
;       o2[d + 1] = MFMA32(b1, u1, o2[d + 1]);
;     }
;     if (more) { ATT_STOREK(buf ^ 1); ATT_STOREV(buf ^ 1); }
;     __syncthreads();
;   }
;   int lane_e = lane; asm volatile("" : "+v"(lane_e));
;   const int r_e = lane_e & 31, h_e = lane_e >> 5;
;   lA += __shfl_xor(lA, 32); lB += __shfl_xor(lB, 32);
;   const float lam = ((const float*)(p.ws + OFF_LAM))[layer];
;   const float iA = 1.f / lA, iB = lam / lB;
;   u16* Mx = (u16*)(p.ws + OFF_M);
;   const int orow0 = q0u + wid * 32;
;   const float lam_init = 0.8f - 0.6f * expf(-0.3f * (float)layer);
;   float sw[4];
; #pragma unroll
;   for (int d = 0; d < 4; ++d) sw[d] = p.subln[layer * 128 + d * 32 + r_e] * (1.f - lam_init);
; #pragma unroll
;   for (int e = 0; e < 16; ++e) {
;     const int qq = crow(e, h_e);
;     const float ia = __shfl(iA, qq), ib = __shfl(iB, qq);
;     float ov[4];
;     float ss = 0.f;
; #pragma unroll
;     for (int d = 0; d < 4; ++d) { ov[d] = o1[d][e] * ia - o2[d][e] * ib; ss += ov[d] * ov[d]; }
; #pragma unroll
;     for (int x = 16; x >= 1; x >>= 1) ss += __shfl_xor(ss, x);
	v_mfma_f32_32x32x16_bf16 v[64:79], v[144:147], v[128:131], v[64:79]
	v_exp_f32_e32 v210, v136
	v_fmamk_f32 v136, v142, 0x3e38aa3b, v173
	v_fmac_f32_e32 v173, 0x3e38aa3b, v143
	v_exp_f32_e32 v196, v154
	v_exp_f32_e32 v175, v175
	v_exp_f32_e32 v212, v136
	v_exp_f32_e32 v173, v173
	v_mfma_f32_32x32x16_bf16 v[48:63], v[132:135], v[128:131], v[48:63]
	ds_read2_b64 v[128:131], v153 offset0:32 offset1:34
	v_cvt_pk_bf16_f32 v148, v180, v181
	v_cvt_pk_bf16_f32 v149, v196, v197
	v_cvt_pk_bf16_f32 v150, v198, v199
	v_cvt_pk_bf16_f32 v151, v200, v175
	v_cvt_pk_bf16_f32 v136, v205, v206
	v_cvt_pk_bf16_f32 v137, v207, v208
	s_waitcnt lgkmcnt(0)
	v_mfma_f32_32x32x16_bf16 v[80:95], v[144:147], v[128:131], v[80:95]
	v_cvt_pk_bf16_f32 v138, v209, v210
	v_cvt_pk_bf16_f32 v139, v212, v173
	v_add_u32_e32 v160, 0x8000, v164
	v_mfma_f32_32x32x16_bf16 v[32:47], v[132:135], v[128:131], v[32:47]
	ds_read2_b64 v[128:131], v152 offset0:4 offset1:6
	v_add_u32_e32 v152, 0x7800, v164
	ds_read2_b64 v[140:143], v152 offset0:64 offset1:66
	s_waitcnt lgkmcnt(1)
	v_mfma_f32_32x32x16_bf16 v[64:79], v[148:151], v[128:131], v[64:79]
	v_mfma_f32_32x32x16_bf16 v[48:63], v[136:139], v[128:131], v[48:63]
	ds_read2_b64 v[128:131], v153 offset0:36 offset1:38
	ds_read2_b64 v[152:155], v152 offset0:68 offset1:70
	ds_read2_b64 v[156:159], v160 offset0:96 offset1:98
	ds_read2_b64 v[160:163], v160 offset0:100 offset1:102
	s_waitcnt lgkmcnt(0)
	s_barrier
	global_load_dword v164, v165, s[18:19]
	v_mfma_f32_32x32x16_bf16 v[96:111], v[144:147], v[140:143], v[96:111]
	v_and_b32_e32 v213, 31, v167
	v_mfma_f32_32x32x16_bf16 v[16:31], v[132:135], v[140:143], v[16:31]
	v_add_f32_e32 v140, v169, v192
	v_add_f32_e32 v140, v193, v140
	v_add_f32_e32 v140, v194, v140
	v_add_f32_e32 v140, v195, v140
	v_add_f32_e32 v140, v201, v140
	v_add_f32_e32 v140, v202, v140
	v_add_f32_e32 v140, v203, v140
	v_add_f32_e32 v140, v204, v140
	v_add_f32_e32 v140, v205, v140
	v_add_f32_e32 v140, v206, v140
	v_mfma_f32_32x32x16_bf16 v[0:15], v[132:135], v[156:159], v[0:15]
	v_add_f32_e32 v132, v207, v140
	v_add_f32_e32 v132, v208, v132
	v_add_f32_e32 v132, v209, v132
	v_add_f32_e32 v132, v210, v132
	v_add_f32_e32 v132, v212, v132
	v_add_f32_e32 v132, v173, v132
	ds_bpermute_b32 v133, v191, v132
	v_mfma_f32_32x32x16_bf16 v[80:95], v[148:151], v[128:131], v[80:95]
	s_waitcnt lgkmcnt(0)
	v_add_f32_e32 v132, v132, v133
	s_waitcnt vmcnt(0)
	v_div_scale_f32 v133, s[0:1], v132, v132, v164
	v_mfma_f32_32x32x16_bf16 v[32:47], v[136:139], v[128:131], v[32:47]
	v_add_f32_e32 v131, v168, v170
	v_add_f32_e32 v131, v171, v131
	v_add_f32_e32 v131, v172, v131
	v_add_f32_e32 v131, v174, v131
	v_add_f32_e32 v131, v176, v131
	v_add_f32_e32 v131, v177, v131
	v_add_f32_e32 v131, v178, v131
	v_add_f32_e32 v131, v179, v131
	v_add_f32_e32 v131, v180, v131
	v_add_f32_e32 v131, v181, v131
	v_lshlrev_b32_e32 v128, 2, v213
	v_add_f32_e32 v131, v196, v131
	v_rcp_f32_e32 v134, v133
	global_load_dword v129, v128, s[54:55] offset:512
	global_load_dword v130, v128, s[54:55] offset:640
	global_load_dword v215, v128, s[54:55] offset:768
	v_add_f32_e32 v131, v197, v131
	v_add_f32_e32 v131, v198, v131
	v_add_f32_e32 v131, v199, v131
	v_add_f32_e32 v131, v200, v131
	v_fma_f32 v140, -v133, v134, 1.0
	v_add_f32_e32 v131, v175, v131
	v_fmac_f32_e32 v134, v140, v134
	v_div_scale_f32 v140, vcc, v164, v132, v164
	ds_bpermute_b32 v135, v191, v131
	v_mul_f32_e32 v141, v140, v134
	v_fma_f32 v142, -v133, v141, v140
	v_fmac_f32_e32 v141, v142, v134
	v_fma_f32 v133, -v133, v141, v140
	v_div_fmas_f32 v133, v133, v134, v141
	v_div_fixup_f32 v132, v133, v132, v164
	s_waitcnt lgkmcnt(0)
	v_add_f32_e32 v133, v131, v135
	v_div_scale_f32 v134, s[0:1], v133, v133, 1.0
	v_rcp_f32_e32 v135, v134
	v_mfma_f32_32x32x16_bf16 v[0:15], v[136:139], v[160:163], v[0:15]
	v_mov_b32_e32 v143, v32
	v_mov_b32_e32 v140, v64
	v_mov_b32_e32 v142, v48
	v_mov_b32_e32 v141, v80
	v_mov_b32_e32 v80, v65
	s_add_u32 s0, s34, s4
	s_addc_u32 s1, s35, s5
	v_mfma_f32_32x32x16_bf16 v[112:127], v[144:147], v[156:159], v[112:127]
	s_nop 3
	v_mov_b32_e32 v146, v0
	v_xor_b32_e32 v0, 16, v214
	v_lshlrev_b32_e32 v164, 1, v213
	global_load_dword v128, v128, s[54:55] offset:896
	s_waitcnt vmcnt(3)
	v_mul_f32_e32 v131, 0x3f24fd5c, v129
	v_mfma_f32_32x32x16_bf16 v[16:31], v[136:139], v[152:155], v[16:31]
	v_fma_f32 v136, -v134, v135, 1.0
	v_fmac_f32_e32 v135, v136, v135
	v_div_scale_f32 v136, vcc, 1.0, v133, 1.0
	v_mul_f32_e32 v137, v136, v135
	v_fma_f32 v138, -v134, v137, v136
	v_fmac_f32_e32 v137, v138, v135
	v_fma_f32 v134, -v134, v137, v136
	v_div_fmas_f32 v134, v134, v135, v137
	v_ashrrev_i32_e32 v135, 3, v167
	v_div_fixup_f32 v133, v134, v133, 1.0
	v_and_b32_e32 v134, -4, v135
	v_mfma_f32_32x32x16_bf16 v[96:111], v[148:151], v[152:155], v[96:111]
	v_cmp_lt_i32_e32 vcc, v0, v187
	v_and_or_b32 v136, v135, 60, v186
	v_mov_b32_e32 v147, v16
	v_cndmask_b32_e32 v16, v214, v0, vcc
	v_lshlrev_b32_e32 v137, 2, v136
	ds_bpermute_b32 v138, v137, v132
	ds_bpermute_b32 v136, v137, v133
	v_mfma_f32_32x32x16_bf16 v[112:127], v[148:151], v[160:163], v[112:127]
	v_or_b32_e32 v150, 1, v134
	v_and_or_b32 v0, v150, 61, v186
	v_lshlrev_b32_e32 v32, 2, v0
	ds_bpermute_b32 v0, v32, v132
	ds_bpermute_b32 v64, v32, v133
	v_mov_b32_e32 v32, v49
	s_waitcnt lgkmcnt(3)
	v_pk_mul_f32 v[142:143], v[142:143], v[138:139] op_sel_hi:[1,0]
	s_nop 3
	v_mov_b32_e32 v144, v112
	v_mov_b32_e32 v145, v96
	v_pk_mul_f32 v[138:139], v[146:147], v[138:139] op_sel_hi:[1,0]
	v_lshlrev_b32_e32 v48, 2, v16
	s_waitcnt lgkmcnt(1)
; DI u16 f2bf(float a) { return (u16)(pk2(a, 0.f) & 0xffffu); }
; DI int crow(int i, int h) { return (i & 3) + 8 * (i >> 2) + 4 * h; }
; __device__ __forceinline__ void attn_item_A(const Params& p, int layer, int head, int q0u, char* lds) {
;     ...
; #pragma unroll
;   for (int e = 0; e < 16; ++e) {
;     const int qq = crow(e, h_e);
;     const float ia = __shfl(iA, qq), ib = __shfl(iB, qq);
;     float ov[4];
;     float ss = 0.f;
; #pragma unroll
;     for (int d = 0; d < 4; ++d) { ov[d] = o1[d][e] * ia - o2[d][e] * ib; ss += ov[d] * ov[d]; }
; #pragma unroll
;     for (int x = 16; x >= 1; x >>= 1) ss += __shfl_xor(ss, x);
;     const float rs = rsqrtf(ss * (1.f / 128.f) + LN_EPS);
;     const size_t rowoff = (size_t)(orow0 + qq) * LDX + ocol + r_e;
; #pragma unroll
;     for (int d = 0; d < 4; ++d) Mx[rowoff + d * 32] = f2bf(ov[d] * rs * sw[d]);
;   }
	v_pk_mul_f32 v[32:33], v[32:33], v[0:1] op_sel_hi:[1,0]
	v_mov_b32_e32 v16, v1
	v_pk_fma_f32 v[140:141], v[140:141], v[136:137], v[142:143] op_sel_hi:[1,0,1] neg_lo:[0,0,1] neg_hi:[0,0,1]
	v_pk_fma_f32 v[136:137], v[144:145], v[136:137], v[138:139] op_sel_hi:[1,0,1] neg_lo:[0,0,1] neg_hi:[0,0,1]
	s_waitcnt lgkmcnt(0)
	v_pk_fma_f32 v[144:145], v[80:81], v[64:65], v[32:33] op_sel_hi:[1,0,1] neg_lo:[0,0,1] neg_hi:[0,0,1]
	v_mov_b32_e32 v96, v113
	v_pk_mul_f32 v[0:1], v[16:17], v[0:1] op_sel_hi:[1,0]
	v_pk_mul_f32 v[142:143], v[140:141], v[140:141]
	v_pk_mul_f32 v[32:33], v[144:145], v[144:145]
	v_pk_fma_f32 v[96:97], v[96:97], v[64:65], v[0:1] op_sel_hi:[1,0,1] neg_lo:[0,0,1] neg_hi:[0,0,1]
	v_pk_mul_f32 v[138:139], v[136:137], v[136:137]
	v_pk_mul_f32 v[0:1], v[96:97], v[96:97]
	v_mov_b32_e32 v16, v32
	v_mov_b32_e32 v17, v142
	v_mov_b32_e32 v142, v33
	v_pk_add_f32 v[16:17], v[16:17], v[142:143]
	v_mov_b32_e32 v32, v1
	v_mov_b32_e32 v33, v139
	v_pk_add_f32 v[16:17], v[32:33], v[16:17]
	v_mov_b32_e32 v1, v138
	v_pk_add_f32 v[0:1], v[0:1], v[16:17]
	ds_bpermute_b32 v17, v48, v1
	ds_bpermute_b32 v16, v48, v0
	v_xor_b32_e32 v32, 8, v214
	v_cmp_lt_i32_e32 vcc, v32, v187
	s_waitcnt vmcnt(2)
	v_mul_f32_e32 v130, 0x3f24fd5c, v130
	s_waitcnt vmcnt(1)
	v_mul_f32_e32 v129, 0x3f24fd5c, v215
	v_cndmask_b32_e32 v32, v214, v32, vcc
	v_lshlrev_b32_e32 v49, 2, v32
	s_waitcnt lgkmcnt(0)
	v_pk_add_f32 v[0:1], v[0:1], v[16:17]
	ds_bpermute_b32 v17, v49, v1
	ds_bpermute_b32 v16, v49, v0
	v_xor_b32_e32 v32, 4, v214
	v_cmp_lt_i32_e32 vcc, v32, v187
	v_or_b32_e32 v152, 2, v134
	v_or_b32_e32 v135, 3, v135
	v_cndmask_b32_e32 v32, v214, v32, vcc
	v_lshlrev_b32_e32 v64, 2, v32
	s_waitcnt lgkmcnt(0)
	v_pk_add_f32 v[0:1], v[0:1], v[16:17]
	ds_bpermute_b32 v17, v64, v1
	ds_bpermute_b32 v16, v64, v0
	v_xor_b32_e32 v32, 2, v214
	v_cmp_lt_i32_e32 vcc, v32, v187
	v_mov_b32_e32 v148, v2
	v_and_or_b32 v2, v135, 63, v186
	v_cndmask_b32_e32 v32, v214, v32, vcc
	v_lshlrev_b32_e32 v65, 2, v32
	s_waitcnt lgkmcnt(0)
	v_pk_add_f32 v[0:1], v[0:1], v[16:17]
	ds_bpermute_b32 v17, v65, v1
	ds_bpermute_b32 v16, v65, v0
	v_xor_b32_e32 v32, 1, v214
	v_cmp_lt_i32_e32 vcc, v32, v187
	v_mov_b32_e32 v149, v18
	v_lshlrev_b32_e32 v18, 2, v2
	v_cndmask_b32_e32 v32, v214, v32, vcc
	v_lshlrev_b32_e32 v80, 2, v32
	s_waitcnt lgkmcnt(0)
	v_pk_add_f32 v[0:1], v[0:1], v[16:17]
	ds_bpermute_b32 v33, v80, v1
	ds_bpermute_b32 v32, v80, v0
	v_lshl_add_u64 v[16:17], s[0:1], 0, v[164:165]
	ds_bpermute_b32 v2, v18, v132
	v_mov_b32_e32 v142, v50
	ds_bpermute_b32 v50, v18, v133
	s_waitcnt lgkmcnt(2)
	v_pk_add_f32 v[0:1], v[0:1], v[32:33]
	v_mov_b64_e32 v[32:33], s[36:37]
	v_pk_fma_f32 v[112:113], v[0:1], s[30:31], v[32:33] op_sel_hi:[1,0,0]
	v_mov_b32_e32 v143, v34
	v_mul_f32_e32 v0, 0x4b800000, v113
	v_cmp_gt_f32_e32 vcc, s81, v113
	v_mov_b32_e32 v34, v51
	s_waitcnt lgkmcnt(1)
	v_pk_mul_f32 v[34:35], v[34:35], v[2:3] op_sel_hi:[1,0]
	v_cndmask_b32_e32 v0, v113, v0, vcc
	v_rsq_f32_e32 v81, v0
	v_add_u32_e32 v0, v134, v190
	v_mad_i64_i32 v[0:1], s[0:1], v0, s78, v[16:17]
	v_mul_f32_e32 v113, 0x45800000, v81
	v_cndmask_b32_e32 v81, v81, v113, vcc
	v_mul_f32_e32 v113, v140, v81
	v_mul_f32_e32 v113, v131, v113
	v_cvt_pk_bf16_f32 v113, v113, s0
	global_store_short v[0:1], v113, off
	v_mul_f32_e32 v113, v141, v81
	v_mul_f32_e32 v113, v130, v113
	v_cvt_pk_bf16_f32 v113, v113, s0
	global_store_short v[0:1], v113, off offset:64
	v_mul_f32_e32 v113, v137, v81
	v_mul_f32_e32 v113, v129, v113
	v_cvt_pk_bf16_f32 v137, v113, s0
	v_mul_f32_e32 v113, 0x4b800000, v112
	v_cmp_gt_f32_e32 vcc, s81, v112
	v_mov_b32_e32 v140, v66
	v_mov_b32_e32 v141, v82
	v_cndmask_b32_e32 v112, v112, v113, vcc
	v_rsq_f32_e32 v151, v112
	v_and_or_b32 v112, v152, 62, v186
	v_lshlrev_b32_e32 v113, 2, v112
	ds_bpermute_b32 v138, v113, v132
	ds_bpermute_b32 v112, v113, v133
	v_mov_b32_e32 v82, v67
	v_mov_b32_e32 v18, v3
	v_mov_b32_e32 v146, v114
	s_waitcnt lgkmcnt(1)
	v_pk_mul_f32 v[142:143], v[142:143], v[138:139] op_sel_hi:[1,0]
	v_mov_b32_e32 v147, v98
	s_waitcnt lgkmcnt(0)
	v_pk_fma_f32 v[140:141], v[140:141], v[112:113], v[142:143] op_sel_hi:[1,0,1] neg_lo:[0,0,1] neg_hi:[0,0,1]
	v_pk_mul_f32 v[138:139], v[148:149], v[138:139] op_sel_hi:[1,0]
	v_pk_fma_f32 v[66:67], v[82:83], v[50:51], v[34:35] op_sel_hi:[1,0,1] neg_lo:[0,0,1] neg_hi:[0,0,1]
	v_mov_b32_e32 v98, v115
	v_pk_mul_f32 v[2:3], v[18:19], v[2:3] op_sel_hi:[1,0]
	v_pk_mul_f32 v[142:143], v[140:141], v[140:141]
	v_pk_fma_f32 v[112:113], v[146:147], v[112:113], v[138:139] op_sel_hi:[1,0,1] neg_lo:[0,0,1] neg_hi:[0,0,1]
	v_pk_mul_f32 v[34:35], v[66:67], v[66:67]
	v_pk_fma_f32 v[50:51], v[98:99], v[50:51], v[2:3] op_sel_hi:[1,0,1] neg_lo:[0,0,1] neg_hi:[0,0,1]
	v_pk_mul_f32 v[138:139], v[112:113], v[112:113]
	v_pk_mul_f32 v[2:3], v[50:51], v[50:51]
	v_mov_b32_e32 v18, v34
	v_mov_b32_e32 v19, v142
	v_mov_b32_e32 v142, v35
	v_pk_add_f32 v[18:19], v[18:19], v[142:143]
	v_mov_b32_e32 v34, v3
	v_mov_b32_e32 v35, v139
	v_pk_add_f32 v[18:19], v[34:35], v[18:19]
	v_mov_b32_e32 v3, v138
	v_pk_add_f32 v[2:3], v[2:3], v[18:19]
	ds_bpermute_b32 v19, v48, v3
	ds_bpermute_b32 v18, v48, v2
	v_mul_f32_e32 v35, 0x45800000, v151
	v_cndmask_b32_e32 v35, v151, v35, vcc
	v_mul_f32_e32 v34, v136, v81
	v_mul_f32_e32 v81, v144, v35
	s_waitcnt lgkmcnt(0)
	v_pk_add_f32 v[18:19], v[2:3], v[18:19]
	ds_bpermute_b32 v83, v49, v19
	ds_bpermute_b32 v82, v49, v18
	v_add_u32_e32 v2, v150, v190
	v_mad_i64_i32 v[2:3], s[0:1], v2, s78, v[16:17]
	v_mul_f32_e32 v81, v131, v81
	s_waitcnt lgkmcnt(0)
	v_pk_add_f32 v[18:19], v[18:19], v[82:83]
	ds_bpermute_b32 v83, v64, v19
	ds_bpermute_b32 v82, v64, v18
	v_cvt_pk_bf16_f32 v81, v81, s0
	global_store_short v[2:3], v81, off
	v_mul_f32_e32 v81, v145, v35
	v_mul_f32_e32 v81, v130, v81
	s_waitcnt lgkmcnt(0)
; DI u16 f2bf(float a) { return (u16)(pk2(a, 0.f) & 0xffffu); }
; DI int crow(int i, int h) { return (i & 3) + 8 * (i >> 2) + 4 * h; }
; __device__ __forceinline__ void attn_item_A(const Params& p, int layer, int head, int q0u, char* lds) {
;     ...
; #pragma unroll
;   for (int e = 0; e < 16; ++e) {
;     const int qq = crow(e, h_e);
;     const float ia = __shfl(iA, qq), ib = __shfl(iB, qq);
;     float ov[4];
;     float ss = 0.f;
; #pragma unroll
;     for (int d = 0; d < 4; ++d) { ov[d] = o1[d][e] * ia - o2[d][e] * ib; ss += ov[d] * ov[d]; }
; #pragma unroll
;     for (int x = 16; x >= 1; x >>= 1) ss += __shfl_xor(ss, x);
;     const float rs = rsqrtf(ss * (1.f / 128.f) + LN_EPS);
;     const size_t rowoff = (size_t)(orow0 + qq) * LDX + ocol + r_e;
; #pragma unroll
;     for (int d = 0; d < 4; ++d) Mx[rowoff + d * 32] = f2bf(ov[d] * rs * sw[d]);
;   }
	v_pk_add_f32 v[18:19], v[18:19], v[82:83]
	ds_bpermute_b32 v83, v65, v19
	ds_bpermute_b32 v82, v65, v18
	v_cvt_pk_bf16_f32 v81, v81, s0
	global_store_short v[2:3], v81, off offset:64
	v_mul_f32_e32 v81, v97, v35
	v_mul_f32_e32 v81, v129, v81
	s_waitcnt lgkmcnt(0)
	v_pk_add_f32 v[18:19], v[18:19], v[82:83]
	ds_bpermute_b32 v83, v80, v19
	ds_bpermute_b32 v82, v80, v18
	v_cvt_pk_bf16_f32 v81, v81, s0
	global_store_short v[2:3], v81, off offset:128
	v_mov_b32_e32 v136, v116
	v_add_u32_e32 v116, 9, v134
	s_waitcnt lgkmcnt(0)
	v_pk_add_f32 v[18:19], v[18:19], v[82:83]
	v_mov_b32_e32 v138, v4
	v_pk_fma_f32 v[82:83], v[18:19], s[30:31], v[32:33] op_sel_hi:[1,0,0]
	v_and_or_b32 v4, v116, 61, v186
	v_mul_f32_e32 v18, 0x4b800000, v83
	v_cmp_gt_f32_e32 vcc, s81, v83
	v_mov_b32_e32 v139, v20
	v_lshlrev_b32_e32 v20, 2, v4
	v_cndmask_b32_e32 v18, v83, v18, vcc
	v_rsq_f32_e32 v81, v18
	v_add_u32_e32 v18, v152, v190
	v_mad_i64_i32 v[18:19], s[0:1], v18, s78, v[16:17]
	v_mul_f32_e32 v83, 0x45800000, v81
	v_cndmask_b32_e32 v81, v81, v83, vcc
	v_mul_f32_e32 v83, v140, v81
	v_mul_f32_e32 v83, v131, v83
	v_cvt_pk_bf16_f32 v83, v83, s0
	global_store_short v[18:19], v83, off
	v_mul_f32_e32 v83, v141, v81
	v_mul_f32_e32 v83, v130, v83
	v_cvt_pk_bf16_f32 v83, v83, s0
	global_store_short v[18:19], v83, off offset:64
	v_mul_f32_e32 v83, v113, v81
	v_mul_f32_e32 v83, v129, v83
	v_cvt_pk_bf16_f32 v113, v83, s0
	v_mul_f32_e32 v83, 0x4b800000, v82
	v_cmp_gt_f32_e32 vcc, s81, v82
	v_add_u32_e32 v141, 8, v134
	v_mul_f32_e32 v35, v96, v35
	v_cndmask_b32_e32 v82, v82, v83, vcc
	v_rsq_f32_e32 v140, v82
	v_and_or_b32 v82, v141, 60, v186
	v_lshlrev_b32_e32 v83, 2, v82
	ds_bpermute_b32 v96, v83, v132
	ds_bpermute_b32 v4, v20, v132
	ds_bpermute_b32 v82, v83, v133
	v_mov_b32_e32 v114, v52
	ds_bpermute_b32 v52, v20, v133
	v_mov_b32_e32 v115, v36
	v_mov_b32_e32 v36, v53
	v_mov_b32_e32 v98, v68
	v_mov_b32_e32 v99, v84
	s_waitcnt lgkmcnt(3)
	v_pk_mul_f32 v[114:115], v[114:115], v[96:97] op_sel_hi:[1,0]
	v_mov_b32_e32 v84, v69
	s_waitcnt lgkmcnt(2)
	v_pk_mul_f32 v[36:37], v[36:37], v[4:5] op_sel_hi:[1,0]
	v_mov_b32_e32 v20, v5
	global_store_short v[0:1], v137, off offset:128
	s_waitcnt lgkmcnt(1)
	v_pk_fma_f32 v[98:99], v[98:99], v[82:83], v[114:115] op_sel_hi:[1,0,1] neg_lo:[0,0,1] neg_hi:[0,0,1]
	v_mov_b32_e32 v137, v100
	v_pk_mul_f32 v[96:97], v[138:139], v[96:97] op_sel_hi:[1,0]
	s_waitcnt lgkmcnt(0)
	v_pk_fma_f32 v[68:69], v[84:85], v[52:53], v[36:37] op_sel_hi:[1,0,1] neg_lo:[0,0,1] neg_hi:[0,0,1]
	v_mov_b32_e32 v100, v117
	v_pk_mul_f32 v[4:5], v[20:21], v[4:5] op_sel_hi:[1,0]
	v_pk_mul_f32 v[114:115], v[98:99], v[98:99]
	v_pk_fma_f32 v[82:83], v[136:137], v[82:83], v[96:97] op_sel_hi:[1,0,1] neg_lo:[0,0,1] neg_hi:[0,0,1]
	v_pk_mul_f32 v[36:37], v[68:69], v[68:69]
	v_pk_fma_f32 v[52:53], v[100:101], v[52:53], v[4:5] op_sel_hi:[1,0,1] neg_lo:[0,0,1] neg_hi:[0,0,1]
	v_pk_mul_f32 v[96:97], v[82:83], v[82:83]
	v_pk_mul_f32 v[4:5], v[52:53], v[52:53]
	v_mov_b32_e32 v20, v36
	v_mov_b32_e32 v21, v114
	v_mov_b32_e32 v114, v37
	v_pk_add_f32 v[20:21], v[20:21], v[114:115]
	v_mov_b32_e32 v36, v5
	v_mov_b32_e32 v37, v97
	v_pk_add_f32 v[20:21], v[36:37], v[20:21]
	v_mov_b32_e32 v5, v96
	v_pk_add_f32 v[4:5], v[4:5], v[20:21]
	ds_bpermute_b32 v21, v48, v5
	ds_bpermute_b32 v20, v48, v4
	v_mul_f32_e32 v37, 0x45800000, v140
	v_cndmask_b32_e32 v37, v140, v37, vcc
	v_mul_f32_e32 v66, v66, v37
	v_mul_f32_e32 v66, v131, v66
	s_waitcnt lgkmcnt(0)
	v_pk_add_f32 v[20:21], v[4:5], v[20:21]
	ds_bpermute_b32 v85, v49, v21
	ds_bpermute_b32 v84, v49, v20
	v_add_u32_e32 v4, v135, v190
	v_mad_i64_i32 v[4:5], s[0:1], v4, s78, v[16:17]
	v_mul_f32_e32 v36, v112, v81
	s_waitcnt lgkmcnt(0)
	v_pk_add_f32 v[20:21], v[20:21], v[84:85]
	ds_bpermute_b32 v85, v64, v21
	ds_bpermute_b32 v84, v64, v20
	v_cvt_pk_bf16_f32 v66, v66, s0
	global_store_short v[4:5], v66, off
	v_mul_f32_e32 v81, v67, v37
	v_mul_f32_e32 v51, v51, v37
	s_waitcnt lgkmcnt(0)
	v_pk_add_f32 v[20:21], v[20:21], v[84:85]
	ds_bpermute_b32 v67, v65, v21
	ds_bpermute_b32 v66, v65, v20
	v_mul_f32_e32 v51, v129, v51
	v_cvt_pk_bf16_f32 v51, v51, s0
	global_store_short v[4:5], v51, off offset:128
	v_mul_f32_e32 v37, v50, v37
	s_waitcnt lgkmcnt(0)
	v_pk_add_f32 v[20:21], v[20:21], v[66:67]
	ds_bpermute_b32 v67, v80, v21
	ds_bpermute_b32 v66, v80, v20
	v_mul_f32_e32 v81, v130, v81
	v_cvt_pk_bf16_f32 v81, v81, s0
	global_store_short v[4:5], v81, off offset:64
	global_store_short v[18:19], v113, off offset:128
	s_waitcnt lgkmcnt(0)
	v_pk_add_f32 v[20:21], v[20:21], v[66:67]
	v_add_u32_e32 v113, 10, v134
	v_pk_fma_f32 v[50:51], v[20:21], s[30:31], v[32:33] op_sel_hi:[1,0,0]
	v_mov_b32_e32 v96, v54
	v_mul_f32_e32 v20, 0x4b800000, v51
	v_cmp_gt_f32_e32 vcc, s81, v51
	v_mov_b32_e32 v97, v38
	v_mov_b32_e32 v100, v6
	v_cndmask_b32_e32 v20, v51, v20, vcc
	v_rsq_f32_e32 v51, v20
	v_add_u32_e32 v20, v141, v190
	v_mad_i64_i32 v[20:21], s[0:1], v20, s78, v[16:17]
	v_mul_f32_e32 v66, 0x45800000, v51
	v_cndmask_b32_e32 v81, v51, v66, vcc
	v_mul_f32_e32 v51, v98, v81
	v_mul_f32_e32 v51, v131, v51
	v_cvt_pk_bf16_f32 v51, v51, s0
	global_store_short v[20:21], v51, off
	v_mul_f32_e32 v51, v99, v81
	v_mul_f32_e32 v51, v130, v51
	v_cvt_pk_bf16_f32 v51, v51, s0
	global_store_short v[20:21], v51, off offset:64
	v_mul_f32_e32 v51, v83, v81
	v_mul_f32_e32 v51, v129, v51
	v_cvt_pk_bf16_f32 v83, v51, s0
	v_mul_f32_e32 v51, 0x4b800000, v50
	v_cmp_gt_f32_e32 vcc, s81, v50
	v_mov_b32_e32 v101, v22
	v_mov_b32_e32 v84, v70
	v_cndmask_b32_e32 v50, v50, v51, vcc
	v_rsq_f32_e32 v112, v50
	v_and_or_b32 v50, v113, 62, v186
	v_lshlrev_b32_e32 v51, 2, v50
	ds_bpermute_b32 v66, v51, v132
	ds_bpermute_b32 v50, v51, v133
	v_mov_b32_e32 v85, v86
	v_mov_b32_e32 v98, v118
	v_mov_b32_e32 v99, v102
	s_waitcnt lgkmcnt(1)
; DI u16 f2bf(float a) { return (u16)(pk2(a, 0.f) & 0xffffu); }
; DI int crow(int i, int h) { return (i & 3) + 8 * (i >> 2) + 4 * h; }
; __device__ __forceinline__ void attn_item_A(const Params& p, int layer, int head, int q0u, char* lds) {
;     ...
; #pragma unroll
;   for (int e = 0; e < 16; ++e) {
;     const int qq = crow(e, h_e);
;     const float ia = __shfl(iA, qq), ib = __shfl(iB, qq);
;     float ov[4];
;     float ss = 0.f;
; #pragma unroll
;     for (int d = 0; d < 4; ++d) { ov[d] = o1[d][e] * ia - o2[d][e] * ib; ss += ov[d] * ov[d]; }
; #pragma unroll
;     for (int x = 16; x >= 1; x >>= 1) ss += __shfl_xor(ss, x);
;     const float rs = rsqrtf(ss * (1.f / 128.f) + LN_EPS);
;     const size_t rowoff = (size_t)(orow0 + qq) * LDX + ocol + r_e;
; #pragma unroll
;     for (int d = 0; d < 4; ++d) Mx[rowoff + d * 32] = f2bf(ov[d] * rs * sw[d]);
;   }
	v_pk_mul_f32 v[96:97], v[96:97], v[66:67] op_sel_hi:[1,0]
	v_pk_mul_f32 v[66:67], v[100:101], v[66:67] op_sel_hi:[1,0]
	s_waitcnt lgkmcnt(0)
	v_pk_fma_f32 v[84:85], v[84:85], v[50:51], v[96:97] op_sel_hi:[1,0,1] neg_lo:[0,0,1] neg_hi:[0,0,1]
	v_pk_fma_f32 v[50:51], v[98:99], v[50:51], v[66:67] op_sel_hi:[1,0,1] neg_lo:[0,0,1] neg_hi:[0,0,1]
	v_add_u32_e32 v98, 11, v134
	v_and_or_b32 v6, v98, 63, v186
	v_lshlrev_b32_e32 v22, 2, v6
	ds_bpermute_b32 v6, v22, v132
	ds_bpermute_b32 v54, v22, v133
	v_mov_b32_e32 v38, v55
	v_mov_b32_e32 v86, v71
	v_mov_b32_e32 v22, v7
	s_waitcnt lgkmcnt(1)
	v_pk_mul_f32 v[38:39], v[38:39], v[6:7] op_sel_hi:[1,0]
	v_mov_b32_e32 v102, v119
	s_waitcnt lgkmcnt(0)
	v_pk_fma_f32 v[70:71], v[86:87], v[54:55], v[38:39] op_sel_hi:[1,0,1] neg_lo:[0,0,1] neg_hi:[0,0,1]
	v_pk_mul_f32 v[6:7], v[22:23], v[6:7] op_sel_hi:[1,0]
	v_pk_mul_f32 v[96:97], v[84:85], v[84:85]
	v_pk_mul_f32 v[38:39], v[70:71], v[70:71]
	v_pk_fma_f32 v[54:55], v[102:103], v[54:55], v[6:7] op_sel_hi:[1,0,1] neg_lo:[0,0,1] neg_hi:[0,0,1]
	v_pk_mul_f32 v[66:67], v[50:51], v[50:51]
	v_pk_mul_f32 v[6:7], v[54:55], v[54:55]
	v_mov_b32_e32 v22, v38
	v_mov_b32_e32 v23, v96
	v_mov_b32_e32 v96, v39
	v_pk_add_f32 v[22:23], v[22:23], v[96:97]
	v_mov_b32_e32 v38, v7
	v_mov_b32_e32 v39, v67
	v_pk_add_f32 v[22:23], v[38:39], v[22:23]
	v_mov_b32_e32 v7, v66
	v_pk_add_f32 v[6:7], v[6:7], v[22:23]
	ds_bpermute_b32 v23, v48, v7
	ds_bpermute_b32 v22, v48, v6
	v_mul_f32_e32 v39, 0x45800000, v112
	v_cndmask_b32_e32 v39, v112, v39, vcc
	v_mul_f32_e32 v68, v68, v39
	v_mul_f32_e32 v53, v53, v39
	s_waitcnt lgkmcnt(0)
	v_pk_add_f32 v[22:23], v[6:7], v[22:23]
	ds_bpermute_b32 v67, v49, v23
	ds_bpermute_b32 v66, v49, v22
	v_add_u32_e32 v6, v116, v190
	v_mad_i64_i32 v[6:7], s[0:1], v6, s78, v[16:17]
	v_mul_f32_e32 v68, v131, v68
	s_waitcnt lgkmcnt(0)
	v_pk_add_f32 v[22:23], v[22:23], v[66:67]
	ds_bpermute_b32 v67, v64, v23
	ds_bpermute_b32 v66, v64, v22
	v_mul_f32_e32 v53, v129, v53
	v_cvt_pk_bf16_f32 v68, v68, s0
	v_cvt_pk_bf16_f32 v53, v53, s0
	global_store_short v[6:7], v68, off
	s_waitcnt lgkmcnt(0)
	v_pk_add_f32 v[22:23], v[22:23], v[66:67]
	ds_bpermute_b32 v67, v65, v23
	ds_bpermute_b32 v66, v65, v22
	v_mul_f32_e32 v68, v69, v39
	global_store_short v[6:7], v53, off offset:128
	v_mul_f32_e32 v39, v52, v39
	v_mul_f32_e32 v38, v82, v81
	s_waitcnt lgkmcnt(0)
	v_pk_add_f32 v[22:23], v[22:23], v[66:67]
	ds_bpermute_b32 v67, v80, v23
	ds_bpermute_b32 v66, v80, v22
	v_mul_f32_e32 v68, v130, v68
	v_cvt_pk_bf16_f32 v68, v68, s0
	v_add_u32_e32 v97, 16, v134
	global_store_short v[20:21], v83, off offset:128
	s_waitcnt lgkmcnt(0)
	v_pk_add_f32 v[22:23], v[22:23], v[66:67]
	v_mov_b32_e32 v82, v56
	v_pk_fma_f32 v[52:53], v[22:23], s[30:31], v[32:33] op_sel_hi:[1,0,0]
	v_mov_b32_e32 v83, v40
	v_mul_f32_e32 v22, 0x4b800000, v53
	v_cmp_gt_f32_e32 vcc, s81, v53
	v_mov_b32_e32 v86, v8
	v_mov_b32_e32 v87, v24
	v_cndmask_b32_e32 v22, v53, v22, vcc
	v_rsq_f32_e32 v53, v22
	v_add_u32_e32 v22, v113, v190
	v_mad_i64_i32 v[22:23], s[0:1], v22, s78, v[16:17]
	v_mul_f32_e32 v66, 0x45800000, v53
	v_cndmask_b32_e32 v81, v53, v66, vcc
	v_mul_f32_e32 v53, v84, v81
	v_mul_f32_e32 v53, v131, v53
	v_cvt_pk_bf16_f32 v53, v53, s0
	global_store_short v[22:23], v53, off
	v_mul_f32_e32 v53, v85, v81
	v_mul_f32_e32 v53, v130, v53
	v_cvt_pk_bf16_f32 v53, v53, s0
	global_store_short v[22:23], v53, off offset:64
	v_mul_f32_e32 v53, 0x4b800000, v52
	v_cmp_gt_f32_e32 vcc, s81, v52
	global_store_short v[6:7], v68, off offset:64
	v_mov_b32_e32 v68, v72
	v_cndmask_b32_e32 v52, v52, v53, vcc
	v_rsq_f32_e32 v96, v52
	v_and_or_b32 v52, v97, 60, v186
	v_lshlrev_b32_e32 v53, 2, v52
	ds_bpermute_b32 v66, v53, v132
	ds_bpermute_b32 v52, v53, v133
	v_mov_b32_e32 v69, v88
	v_mov_b32_e32 v84, v120
	v_mov_b32_e32 v85, v104
	s_waitcnt lgkmcnt(1)
	v_pk_mul_f32 v[82:83], v[82:83], v[66:67] op_sel_hi:[1,0]
	v_pk_mul_f32 v[66:67], v[86:87], v[66:67] op_sel_hi:[1,0]
	s_waitcnt lgkmcnt(0)
	v_pk_fma_f32 v[68:69], v[68:69], v[52:53], v[82:83] op_sel_hi:[1,0,1] neg_lo:[0,0,1] neg_hi:[0,0,1]
	v_pk_fma_f32 v[52:53], v[84:85], v[52:53], v[66:67] op_sel_hi:[1,0,1] neg_lo:[0,0,1] neg_hi:[0,0,1]
	v_add_u32_e32 v84, 17, v134
	v_and_or_b32 v8, v84, 61, v186
	v_lshlrev_b32_e32 v24, 2, v8
	ds_bpermute_b32 v8, v24, v132
	ds_bpermute_b32 v56, v24, v133
	v_mov_b32_e32 v40, v57
	v_mov_b32_e32 v88, v73
	v_mov_b32_e32 v24, v9
	s_waitcnt lgkmcnt(1)
	v_pk_mul_f32 v[40:41], v[40:41], v[8:9] op_sel_hi:[1,0]
	v_mov_b32_e32 v104, v121
	s_waitcnt lgkmcnt(0)
	v_pk_fma_f32 v[72:73], v[88:89], v[56:57], v[40:41] op_sel_hi:[1,0,1] neg_lo:[0,0,1] neg_hi:[0,0,1]
	v_pk_mul_f32 v[8:9], v[24:25], v[8:9] op_sel_hi:[1,0]
	v_pk_mul_f32 v[82:83], v[68:69], v[68:69]
	v_pk_mul_f32 v[40:41], v[72:73], v[72:73]
	v_pk_fma_f32 v[56:57], v[104:105], v[56:57], v[8:9] op_sel_hi:[1,0,1] neg_lo:[0,0,1] neg_hi:[0,0,1]
	v_pk_mul_f32 v[66:67], v[52:53], v[52:53]
	v_pk_mul_f32 v[8:9], v[56:57], v[56:57]
	v_mov_b32_e32 v24, v40
	v_mov_b32_e32 v25, v82
	v_mov_b32_e32 v82, v41
	v_pk_add_f32 v[24:25], v[24:25], v[82:83]
	v_mov_b32_e32 v40, v9
	v_mov_b32_e32 v41, v67
	v_pk_add_f32 v[24:25], v[40:41], v[24:25]
	v_mov_b32_e32 v9, v66
	v_pk_add_f32 v[8:9], v[8:9], v[24:25]
	ds_bpermute_b32 v25, v48, v9
	ds_bpermute_b32 v24, v48, v8
	v_mul_f32_e32 v51, v51, v81
	v_mul_f32_e32 v51, v129, v51
	v_cvt_pk_bf16_f32 v51, v51, s0
	global_store_short v[22:23], v51, off offset:128
	s_waitcnt lgkmcnt(0)
	v_pk_add_f32 v[24:25], v[8:9], v[24:25]
	v_mul_f32_e32 v40, v50, v81
	ds_bpermute_b32 v51, v49, v25
	ds_bpermute_b32 v50, v49, v24
	v_mul_f32_e32 v41, 0x45800000, v96
	v_cndmask_b32_e32 v41, v96, v41, vcc
	v_add_u32_e32 v8, v98, v190
	v_mul_f32_e32 v66, v70, v41
	s_waitcnt lgkmcnt(0)
; DI u16 f2bf(float a) { return (u16)(pk2(a, 0.f) & 0xffffu); }
; DI int crow(int i, int h) { return (i & 3) + 8 * (i >> 2) + 4 * h; }
; __device__ __forceinline__ void attn_item_A(const Params& p, int layer, int head, int q0u, char* lds) {
;     ...
; #pragma unroll
;   for (int e = 0; e < 16; ++e) {
;     const int qq = crow(e, h_e);
;     const float ia = __shfl(iA, qq), ib = __shfl(iB, qq);
;     float ov[4];
;     float ss = 0.f;
; #pragma unroll
;     for (int d = 0; d < 4; ++d) { ov[d] = o1[d][e] * ia - o2[d][e] * ib; ss += ov[d] * ov[d]; }
; #pragma unroll
;     for (int x = 16; x >= 1; x >>= 1) ss += __shfl_xor(ss, x);
;     const float rs = rsqrtf(ss * (1.f / 128.f) + LN_EPS);
;     const size_t rowoff = (size_t)(orow0 + qq) * LDX + ocol + r_e;
; #pragma unroll
;     for (int d = 0; d < 4; ++d) Mx[rowoff + d * 32] = f2bf(ov[d] * rs * sw[d]);
;   }
	v_pk_add_f32 v[24:25], v[24:25], v[50:51]
	ds_bpermute_b32 v51, v64, v25
	ds_bpermute_b32 v50, v64, v24
	v_mad_i64_i32 v[8:9], s[0:1], v8, s78, v[16:17]
	v_mul_f32_e32 v66, v131, v66
	s_nop 0
	v_cvt_pk_bf16_f32 v66, v66, s0
	s_waitcnt lgkmcnt(0)
	v_pk_add_f32 v[24:25], v[24:25], v[50:51]
	ds_bpermute_b32 v51, v65, v25
	ds_bpermute_b32 v50, v65, v24
	global_store_short v[8:9], v66, off
	v_mul_f32_e32 v66, v71, v41
	v_mul_f32_e32 v55, v55, v41
	v_mul_f32_e32 v41, v54, v41
	s_waitcnt lgkmcnt(0)
	v_pk_add_f32 v[24:25], v[24:25], v[50:51]
	ds_bpermute_b32 v51, v80, v25
	ds_bpermute_b32 v50, v80, v24
	v_mul_f32_e32 v66, v130, v66
	v_mul_f32_e32 v55, v129, v55
	v_cvt_pk_bf16_f32 v66, v66, s0
	v_cvt_pk_bf16_f32 v55, v55, s0
	s_waitcnt lgkmcnt(0)
	v_pk_add_f32 v[24:25], v[24:25], v[50:51]
	v_add_u32_e32 v86, 18, v134
	v_pk_fma_f32 v[50:51], v[24:25], s[30:31], v[32:33] op_sel_hi:[1,0,0]
	global_store_short v[8:9], v66, off offset:64
	v_mul_f32_e32 v24, 0x4b800000, v51
	v_cmp_gt_f32_e32 vcc, s81, v51
	v_mov_b32_e32 v66, v74
	v_add_u32_e32 v74, 19, v134
	v_cndmask_b32_e32 v24, v51, v24, vcc
	v_rsq_f32_e32 v51, v24
	v_add_u32_e32 v24, v97, v190
	v_mad_i64_i32 v[24:25], s[0:1], v24, s78, v[16:17]
	v_mul_f32_e32 v54, 0x45800000, v51
	v_cndmask_b32_e32 v81, v51, v54, vcc
	v_mul_f32_e32 v51, v68, v81
	v_mul_f32_e32 v51, v131, v51
	v_cvt_pk_bf16_f32 v51, v51, s0
	global_store_short v[24:25], v51, off
	v_mul_f32_e32 v51, v69, v81
	v_mul_f32_e32 v51, v130, v51
	v_cvt_pk_bf16_f32 v51, v51, s0
	global_store_short v[24:25], v51, off offset:64
	v_mul_f32_e32 v51, v53, v81
	v_mul_f32_e32 v51, v129, v51
	v_cvt_pk_bf16_f32 v53, v51, s0
	v_mul_f32_e32 v51, 0x4b800000, v50
	v_cmp_gt_f32_e32 vcc, s81, v50
	v_mov_b32_e32 v82, v10
	v_and_or_b32 v10, v74, 63, v186
	v_cndmask_b32_e32 v50, v50, v51, vcc
	v_rsq_f32_e32 v85, v50
	v_and_or_b32 v50, v86, 62, v186
	v_lshlrev_b32_e32 v51, 2, v50
	ds_bpermute_b32 v54, v51, v132
	ds_bpermute_b32 v50, v51, v133
	v_mov_b32_e32 v68, v58
	v_mov_b32_e32 v69, v42
	v_mov_b32_e32 v83, v26
	v_lshlrev_b32_e32 v26, 2, v10
	global_store_short v[8:9], v55, off offset:128
	v_mov_b32_e32 v67, v90
	s_waitcnt lgkmcnt(1)
	v_pk_mul_f32 v[68:69], v[68:69], v[54:55] op_sel_hi:[1,0]
	v_mov_b32_e32 v70, v122
	v_mov_b32_e32 v71, v106
	v_pk_mul_f32 v[54:55], v[82:83], v[54:55] op_sel_hi:[1,0]
	ds_bpermute_b32 v10, v26, v132
	s_waitcnt lgkmcnt(1)
	v_pk_fma_f32 v[66:67], v[66:67], v[50:51], v[68:69] op_sel_hi:[1,0,1] neg_lo:[0,0,1] neg_hi:[0,0,1]
	v_pk_fma_f32 v[50:51], v[70:71], v[50:51], v[54:55] op_sel_hi:[1,0,1] neg_lo:[0,0,1] neg_hi:[0,0,1]
	ds_bpermute_b32 v54, v26, v133
	v_mov_b32_e32 v42, v59
	v_mov_b32_e32 v90, v75
	s_waitcnt lgkmcnt(1)
	v_pk_mul_f32 v[42:43], v[42:43], v[10:11] op_sel_hi:[1,0]
	v_mov_b32_e32 v26, v11
	s_waitcnt lgkmcnt(0)
	v_pk_fma_f32 v[42:43], v[90:91], v[54:55], v[42:43] op_sel_hi:[1,0,1] neg_lo:[0,0,1] neg_hi:[0,0,1]
	v_mov_b32_e32 v106, v123
	v_pk_mul_f32 v[10:11], v[26:27], v[10:11] op_sel_hi:[1,0]
	v_pk_mul_f32 v[68:69], v[66:67], v[66:67]
	v_pk_mul_f32 v[58:59], v[42:43], v[42:43]
	v_pk_fma_f32 v[54:55], v[106:107], v[54:55], v[10:11] op_sel_hi:[1,0,1] neg_lo:[0,0,1] neg_hi:[0,0,1]
	v_pk_mul_f32 v[70:71], v[50:51], v[50:51]
	v_pk_mul_f32 v[10:11], v[54:55], v[54:55]
	v_mov_b32_e32 v26, v58
	v_mov_b32_e32 v27, v68
	v_mov_b32_e32 v68, v59
	v_pk_add_f32 v[26:27], v[26:27], v[68:69]
	v_mov_b32_e32 v58, v11
	v_mov_b32_e32 v59, v71
	v_pk_add_f32 v[26:27], v[58:59], v[26:27]
	v_mov_b32_e32 v11, v70
	v_pk_add_f32 v[10:11], v[10:11], v[26:27]
	ds_bpermute_b32 v27, v48, v11
	ds_bpermute_b32 v26, v48, v10
	v_mul_f32_e32 v75, v52, v81
	v_mul_f32_e32 v52, 0x45800000, v85
	global_store_short v[24:25], v53, off offset:128
	v_cndmask_b32_e32 v58, v85, v52, vcc
	s_waitcnt lgkmcnt(0)
	v_pk_add_f32 v[26:27], v[10:11], v[26:27]
	ds_bpermute_b32 v53, v49, v27
	ds_bpermute_b32 v52, v49, v26
	v_add_u32_e32 v10, v84, v190
	v_mul_f32_e32 v59, v72, v58
	v_mad_i64_i32 v[10:11], s[0:1], v10, s78, v[16:17]
	s_waitcnt lgkmcnt(0)
	v_pk_add_f32 v[26:27], v[26:27], v[52:53]
	ds_bpermute_b32 v53, v64, v27
	ds_bpermute_b32 v52, v64, v26
	v_mul_f32_e32 v59, v131, v59
	v_cvt_pk_bf16_f32 v59, v59, s0
	v_mul_f32_e32 v72, v56, v58
	global_store_short v[10:11], v59, off
	s_waitcnt lgkmcnt(0)
	v_pk_add_f32 v[26:27], v[26:27], v[52:53]
	ds_bpermute_b32 v53, v65, v27
	ds_bpermute_b32 v52, v65, v26
	v_mul_f32_e32 v59, v73, v58
	v_mul_f32_e32 v57, v57, v58
	v_mul_f32_e32 v59, v130, v59
	v_mul_f32_e32 v57, v129, v57
	s_waitcnt lgkmcnt(0)
	v_pk_add_f32 v[26:27], v[26:27], v[52:53]
	ds_bpermute_b32 v53, v80, v27
	ds_bpermute_b32 v52, v80, v26
	v_cvt_pk_bf16_f32 v59, v59, s0
	v_cvt_pk_bf16_f32 v57, v57, s0
	v_add_u32_e32 v82, 24, v134
	v_mov_b32_e32 v70, v12
	s_waitcnt lgkmcnt(0)
	v_pk_add_f32 v[26:27], v[26:27], v[52:53]
	v_mov_b32_e32 v71, v28
	v_pk_fma_f32 v[52:53], v[26:27], s[30:31], v[32:33] op_sel_hi:[1,0,0]
	global_store_short v[10:11], v57, off offset:128
	v_mul_f32_e32 v26, 0x4b800000, v53
	v_cmp_gt_f32_e32 vcc, s81, v53
	global_store_short v[10:11], v59, off offset:64
	v_mov_b32_e32 v58, v76
	v_cndmask_b32_e32 v26, v53, v26, vcc
	v_rsq_f32_e32 v53, v26
	v_add_u32_e32 v26, v86, v190
	v_mad_i64_i32 v[26:27], s[0:1], v26, s78, v[16:17]
	v_mul_f32_e32 v56, 0x45800000, v53
	v_cndmask_b32_e32 v73, v53, v56, vcc
	v_mul_f32_e32 v53, v66, v73
	v_mul_f32_e32 v53, v131, v53
	v_cvt_pk_bf16_f32 v53, v53, s0
	global_store_short v[26:27], v53, off
	v_mul_f32_e32 v53, v67, v73
	v_mul_f32_e32 v53, v130, v53
	v_cvt_pk_bf16_f32 v53, v53, s0
	global_store_short v[26:27], v53, off offset:64
	v_mul_f32_e32 v53, 0x4b800000, v52
	v_cmp_gt_f32_e32 vcc, s81, v52
	v_mov_b32_e32 v66, v60
	v_mov_b32_e32 v67, v44
	v_cndmask_b32_e32 v52, v52, v53, vcc
	v_rsq_f32_e32 v81, v52
	v_and_or_b32 v52, v82, 60, v186
	v_lshlrev_b32_e32 v53, 2, v52
	ds_bpermute_b32 v56, v53, v132
	ds_bpermute_b32 v52, v53, v133
	v_mov_b32_e32 v59, v92
	v_mov_b32_e32 v68, v124
	v_mov_b32_e32 v69, v108
	s_waitcnt lgkmcnt(1)
; DI u16 f2bf(float a) { return (u16)(pk2(a, 0.f) & 0xffffu); }
; DI int crow(int i, int h) { return (i & 3) + 8 * (i >> 2) + 4 * h; }
; __device__ __forceinline__ void attn_item_A(const Params& p, int layer, int head, int q0u, char* lds) {
;     ...
; #pragma unroll
;   for (int e = 0; e < 16; ++e) {
;     const int qq = crow(e, h_e);
;     const float ia = __shfl(iA, qq), ib = __shfl(iB, qq);
;     float ov[4];
;     float ss = 0.f;
; #pragma unroll
;     for (int d = 0; d < 4; ++d) { ov[d] = o1[d][e] * ia - o2[d][e] * ib; ss += ov[d] * ov[d]; }
; #pragma unroll
;     for (int x = 16; x >= 1; x >>= 1) ss += __shfl_xor(ss, x);
;     const float rs = rsqrtf(ss * (1.f / 128.f) + LN_EPS);
;     const size_t rowoff = (size_t)(orow0 + qq) * LDX + ocol + r_e;
; #pragma unroll
;     for (int d = 0; d < 4; ++d) Mx[rowoff + d * 32] = f2bf(ov[d] * rs * sw[d]);
;   }
	v_pk_mul_f32 v[66:67], v[66:67], v[56:57] op_sel_hi:[1,0]
	v_pk_mul_f32 v[56:57], v[70:71], v[56:57] op_sel_hi:[1,0]
	v_add_u32_e32 v70, 25, v134
	v_and_or_b32 v12, v70, 61, v186
	v_lshlrev_b32_e32 v28, 2, v12
	ds_bpermute_b32 v12, v28, v132
	s_waitcnt lgkmcnt(1)
	v_pk_fma_f32 v[58:59], v[58:59], v[52:53], v[66:67] op_sel_hi:[1,0,1] neg_lo:[0,0,1] neg_hi:[0,0,1]
	v_pk_fma_f32 v[52:53], v[68:69], v[52:53], v[56:57] op_sel_hi:[1,0,1] neg_lo:[0,0,1] neg_hi:[0,0,1]
	ds_bpermute_b32 v56, v28, v133
	v_mov_b32_e32 v44, v61
	v_mov_b32_e32 v92, v77
	s_waitcnt lgkmcnt(1)
	v_pk_mul_f32 v[44:45], v[44:45], v[12:13] op_sel_hi:[1,0]
	v_mov_b32_e32 v28, v13
	s_waitcnt lgkmcnt(0)
	v_pk_fma_f32 v[44:45], v[92:93], v[56:57], v[44:45] op_sel_hi:[1,0,1] neg_lo:[0,0,1] neg_hi:[0,0,1]
	v_mov_b32_e32 v108, v125
	v_pk_mul_f32 v[12:13], v[28:29], v[12:13] op_sel_hi:[1,0]
	v_pk_mul_f32 v[66:67], v[58:59], v[58:59]
	v_pk_mul_f32 v[60:61], v[44:45], v[44:45]
	v_pk_fma_f32 v[28:29], v[108:109], v[56:57], v[12:13] op_sel_hi:[1,0,1] neg_lo:[0,0,1] neg_hi:[0,0,1]
	v_pk_mul_f32 v[68:69], v[52:53], v[52:53]
	v_pk_mul_f32 v[12:13], v[28:29], v[28:29]
	v_mov_b32_e32 v56, v60
	v_mov_b32_e32 v57, v66
	v_mov_b32_e32 v66, v61
	v_pk_add_f32 v[56:57], v[56:57], v[66:67]
	v_mov_b32_e32 v60, v13
	v_mov_b32_e32 v61, v69
	v_pk_add_f32 v[56:57], v[60:61], v[56:57]
	v_mov_b32_e32 v13, v68
	v_pk_add_f32 v[12:13], v[12:13], v[56:57]
	ds_bpermute_b32 v57, v48, v13
	ds_bpermute_b32 v56, v48, v12
	v_mul_f32_e32 v51, v51, v73
	v_mul_f32_e32 v51, v129, v51
	v_cvt_pk_bf16_f32 v51, v51, s0
	v_mul_f32_e32 v68, v50, v73
	v_mul_f32_e32 v50, 0x45800000, v81
	global_store_short v[26:27], v51, off offset:128
	v_cndmask_b32_e32 v60, v81, v50, vcc
	s_waitcnt lgkmcnt(0)
	v_pk_add_f32 v[50:51], v[12:13], v[56:57]
	ds_bpermute_b32 v57, v49, v51
	ds_bpermute_b32 v56, v49, v50
	v_add_u32_e32 v12, v74, v190
	v_mul_f32_e32 v42, v42, v60
	v_mad_i64_i32 v[12:13], s[0:1], v12, s78, v[16:17]
	s_waitcnt lgkmcnt(0)
	v_pk_add_f32 v[50:51], v[50:51], v[56:57]
	ds_bpermute_b32 v57, v64, v51
	ds_bpermute_b32 v56, v64, v50
	v_mul_f32_e32 v42, v131, v42
	v_cvt_pk_bf16_f32 v42, v42, s0
	global_store_short v[12:13], v42, off
	v_mul_f32_e32 v61, v43, v60
	s_waitcnt lgkmcnt(0)
	v_pk_add_f32 v[42:43], v[50:51], v[56:57]
	ds_bpermute_b32 v51, v65, v43
	ds_bpermute_b32 v50, v65, v42
	v_mul_f32_e32 v69, v54, v60
	v_mul_f32_e32 v55, v55, v60
	v_mul_f32_e32 v56, v130, v61
	v_mul_f32_e32 v55, v129, v55
	s_waitcnt lgkmcnt(0)
	v_pk_add_f32 v[42:43], v[42:43], v[50:51]
	ds_bpermute_b32 v51, v80, v43
	ds_bpermute_b32 v50, v80, v42
	v_cvt_pk_bf16_f32 v56, v56, s0
	v_cvt_pk_bf16_f32 v55, v55, s0
	v_add_u32_e32 v74, 26, v134
	v_add_u32_e32 v76, 27, v134
	s_waitcnt lgkmcnt(0)
	v_pk_add_f32 v[42:43], v[42:43], v[50:51]
	v_mov_b32_e32 v66, v14
	v_pk_fma_f32 v[42:43], v[42:43], s[30:31], v[32:33] op_sel_hi:[1,0,0]
	v_mov_b32_e32 v67, v30
	v_mul_f32_e32 v50, 0x4b800000, v43
	v_cmp_gt_f32_e32 vcc, s81, v43
	v_and_or_b32 v14, v76, 63, v186
	global_store_short v[12:13], v56, off offset:64
	v_cndmask_b32_e32 v43, v43, v50, vcc
	v_rsq_f32_e32 v43, v43
	v_add_u32_e32 v50, v82, v190
	v_mad_i64_i32 v[50:51], s[0:1], v50, s78, v[16:17]
	v_mul_f32_e32 v54, 0x45800000, v43
	v_cndmask_b32_e32 v71, v43, v54, vcc
	v_mul_f32_e32 v43, v58, v71
	v_mul_f32_e32 v43, v131, v43
	v_cvt_pk_bf16_f32 v43, v43, s0
	global_store_short v[50:51], v43, off
	v_mul_f32_e32 v43, v59, v71
	v_mul_f32_e32 v43, v130, v43
	v_cvt_pk_bf16_f32 v43, v43, s0
	global_store_short v[50:51], v43, off offset:64
	v_mul_f32_e32 v43, v53, v71
	v_mul_f32_e32 v43, v129, v43
	v_cvt_pk_bf16_f32 v53, v43, s0
	v_mul_f32_e32 v43, 0x4b800000, v42
	v_cmp_gt_f32_e32 vcc, s81, v42
	v_mov_b32_e32 v58, v62
	v_mov_b32_e32 v59, v46
	v_cndmask_b32_e32 v42, v42, v43, vcc
	v_rsq_f32_e32 v73, v42
	v_and_or_b32 v42, v74, 62, v186
	v_lshlrev_b32_e32 v43, 2, v42
	ds_bpermute_b32 v54, v43, v132
	ds_bpermute_b32 v42, v43, v133
	global_store_short v[12:13], v55, off offset:128
	v_mov_b32_e32 v56, v78
	v_mov_b32_e32 v57, v94
	s_waitcnt lgkmcnt(1)
	v_pk_mul_f32 v[58:59], v[58:59], v[54:55] op_sel_hi:[1,0]
	v_mov_b32_e32 v60, v126
	v_mov_b32_e32 v61, v110
	v_pk_mul_f32 v[54:55], v[66:67], v[54:55] op_sel_hi:[1,0]
	v_lshlrev_b32_e32 v14, 2, v14
	s_waitcnt lgkmcnt(0)
	v_pk_fma_f32 v[56:57], v[56:57], v[42:43], v[58:59] op_sel_hi:[1,0,1] neg_lo:[0,0,1] neg_hi:[0,0,1]
	v_pk_fma_f32 v[42:43], v[60:61], v[42:43], v[54:55] op_sel_hi:[1,0,1] neg_lo:[0,0,1] neg_hi:[0,0,1]
	ds_bpermute_b32 v55, v14, v132
	ds_bpermute_b32 v54, v14, v133
	v_mov_b32_e32 v46, v63
	v_mov_b32_e32 v94, v79
	v_pk_mul_f32 v[58:59], v[56:57], v[56:57]
	s_waitcnt lgkmcnt(1)
	v_mov_b32_e32 v14, v55
	v_pk_mul_f32 v[46:47], v[46:47], v[14:15] op_sel_hi:[1,0]
	v_mov_b32_e32 v14, v127
	s_waitcnt lgkmcnt(0)
; DI u16 f2bf(float a) { return (u16)(pk2(a, 0.f) & 0xffffu); }
; DI int crow(int i, int h) { return (i & 3) + 8 * (i >> 2) + 4 * h; }
; __device__ __forceinline__ void attn_item_A(const Params& p, int layer, int head, int q0u, char* lds) {
;     ...
; #pragma unroll
;   for (int e = 0; e < 16; ++e) {
;     const int qq = crow(e, h_e);
;     const float ia = __shfl(iA, qq), ib = __shfl(iB, qq);
;     float ov[4];
;     float ss = 0.f;
; #pragma unroll
;     for (int d = 0; d < 4; ++d) { ov[d] = o1[d][e] * ia - o2[d][e] * ib; ss += ov[d] * ov[d]; }
; #pragma unroll
;     for (int x = 16; x >= 1; x >>= 1) ss += __shfl_xor(ss, x);
;     const float rs = rsqrtf(ss * (1.f / 128.f) + LN_EPS);
;     const size_t rowoff = (size_t)(orow0 + qq) * LDX + ocol + r_e;
; #pragma unroll
;     for (int d = 0; d < 4; ++d) Mx[rowoff + d * 32] = f2bf(ov[d] * rs * sw[d]);
;   }
	v_pk_mul_f32 v[14:15], v[14:15], v[54:55]
	v_pk_fma_f32 v[46:47], v[94:95], v[54:55], v[46:47] op_sel_hi:[1,0,1] neg_lo:[0,0,1] neg_hi:[0,0,1]
	v_mul_f32_e32 v67, v111, v54
	v_mul_f32_e32 v31, v31, v55
	v_mov_b32_e32 v66, v14
	v_mov_b32_e32 v30, v15
	v_pk_mul_f32 v[62:63], v[46:47], v[46:47]
	v_pk_add_f32 v[14:15], v[66:67], v[30:31] neg_lo:[0,1] neg_hi:[0,1]
	v_pk_mul_f32 v[60:61], v[42:43], v[42:43]
	v_pk_mul_f32 v[30:31], v[14:15], v[14:15]
	v_mov_b32_e32 v54, v62
	v_mov_b32_e32 v55, v58
	v_mov_b32_e32 v58, v63
	v_pk_add_f32 v[54:55], v[54:55], v[58:59]
	v_mov_b32_e32 v58, v31
	v_mov_b32_e32 v59, v61
	v_pk_add_f32 v[54:55], v[58:59], v[54:55]
	v_mov_b32_e32 v31, v60
	v_pk_add_f32 v[30:31], v[30:31], v[54:55]
	ds_bpermute_b32 v55, v48, v31
	ds_bpermute_b32 v54, v48, v30
	global_store_short v[50:51], v53, off offset:128
	v_mul_f32_e32 v58, v52, v71
	v_mul_f32_e32 v48, 0x45800000, v73
	v_cndmask_b32_e32 v59, v73, v48, vcc
	s_waitcnt lgkmcnt(0)
	v_pk_add_f32 v[30:31], v[30:31], v[54:55]
	ds_bpermute_b32 v53, v49, v31
	ds_bpermute_b32 v52, v49, v30
	v_add_u32_e32 v48, v70, v190
	v_mul_f32_e32 v44, v44, v59
	v_mad_i64_i32 v[48:49], s[0:1], v48, s78, v[16:17]
	s_waitcnt lgkmcnt(0)
	v_pk_add_f32 v[30:31], v[30:31], v[52:53]
	ds_bpermute_b32 v53, v64, v31
	ds_bpermute_b32 v52, v64, v30
	v_mul_f32_e32 v44, v131, v44
	v_cvt_pk_bf16_f32 v44, v44, s0
	global_store_short v[48:49], v44, off
	v_mul_f32_e32 v54, v45, v59
	s_waitcnt lgkmcnt(0)
	v_pk_add_f32 v[30:31], v[30:31], v[52:53]
	ds_bpermute_b32 v45, v65, v31
	ds_bpermute_b32 v44, v65, v30
	v_mul_f32_e32 v29, v29, v59
	v_mul_f32_e32 v52, v130, v54
	v_mul_f32_e32 v29, v129, v29
	v_cvt_pk_bf16_f32 v52, v52, s0
	s_waitcnt lgkmcnt(0)
	v_pk_add_f32 v[30:31], v[30:31], v[44:45]
	ds_bpermute_b32 v45, v80, v31
	ds_bpermute_b32 v44, v80, v30
	v_cvt_pk_bf16_f32 v29, v29, s0
	global_store_short v[48:49], v52, off offset:64
	global_store_short v[48:49], v29, off offset:128
	v_mul_f32_e32 v52, v28, v59
	s_waitcnt lgkmcnt(0)
	v_pk_add_f32 v[28:29], v[30:31], v[44:45]
	s_nop 0
	v_pk_fma_f32 v[28:29], v[28:29], s[30:31], v[32:33] op_sel_hi:[1,0,0]
	s_nop 0
	v_mul_f32_e32 v30, 0x4b800000, v29
	v_cmp_gt_f32_e32 vcc, s81, v29
	v_mul_f32_e32 v33, 0x4b800000, v28
	s_nop 0
	v_cndmask_b32_e32 v29, v29, v30, vcc
	v_rsq_f32_e32 v29, v29
	v_add_u32_e32 v30, v74, v190
	v_mad_i64_i32 v[30:31], s[0:1], v30, s78, v[16:17]
	v_mul_f32_e32 v32, 0x45800000, v29
	v_cndmask_b32_e32 v29, v29, v32, vcc
	v_mul_f32_e32 v32, v56, v29
	v_mul_f32_e32 v32, v131, v32
	v_cvt_pk_bf16_f32 v32, v32, s0
	global_store_short v[30:31], v32, off
	v_mul_f32_e32 v32, v57, v29
	v_cmp_gt_f32_e32 vcc, s81, v28
	v_mul_f32_e32 v32, v130, v32
	v_cvt_pk_bf16_f32 v32, v32, s0
	v_cndmask_b32_e32 v28, v28, v33, vcc
	v_rsq_f32_e32 v28, v28
	global_store_short v[30:31], v32, off offset:64
	v_mul_f32_e32 v32, v43, v29
	v_mul_f32_e32 v32, v129, v32
	v_cvt_pk_bf16_f32 v32, v32, s0
	global_store_short v[30:31], v32, off offset:128
	v_mul_f32_e32 v32, 0x45800000, v28
	v_cndmask_b32_e32 v167, v28, v32, vcc
	v_add_u32_e32 v28, v76, v190
	v_mad_i64_i32 v[16:17], s[0:1], v28, s78, v[16:17]
	v_mul_f32_e32 v28, v46, v167
	v_mul_f32_e32 v28, v131, v28
	v_cvt_pk_bf16_f32 v28, v28, s0
	v_mul_f32_e32 v15, v15, v167
	global_store_short v[16:17], v28, off
	v_mul_f32_e32 v28, v47, v167
	v_mul_f32_e32 v15, v129, v15
	v_mul_f32_e32 v28, v130, v28
	v_cvt_pk_bf16_f32 v15, v15, s0
	v_mov_b32_e32 v129, v14
	v_cvt_pk_bf16_f32 v28, v28, s0
	global_store_short v[16:17], v15, off offset:128
	s_waitcnt vmcnt(47)
	v_pk_mul_f32 v[14:15], v[128:129], v[166:167]
	global_store_short v[16:17], v28, off offset:64
	v_mul_f32_e32 v28, v14, v34
	v_cvt_pk_bf16_f32 v28, v28, s0
	global_store_short v[0:1], v28, off offset:192
	v_mul_f32_e32 v0, v14, v35
	v_cvt_pk_bf16_f32 v0, v0, s0
	global_store_short v[2:3], v0, off offset:192
	v_mul_f32_e32 v0, v14, v36
	v_cvt_pk_bf16_f32 v0, v0, s0
	global_store_short v[18:19], v0, off offset:192
	v_mul_f32_e32 v0, v14, v37
	v_cvt_pk_bf16_f32 v0, v0, s0
	global_store_short v[4:5], v0, off offset:192
	v_mul_f32_e32 v0, v14, v38
	v_cvt_pk_bf16_f32 v0, v0, s0
	global_store_short v[20:21], v0, off offset:192
	v_mul_f32_e32 v0, v14, v39
	v_cvt_pk_bf16_f32 v0, v0, s0
	global_store_short v[6:7], v0, off offset:192
	v_mul_f32_e32 v0, v14, v40
	v_cvt_pk_bf16_f32 v0, v0, s0
	global_store_short v[22:23], v0, off offset:192
	v_mul_f32_e32 v0, v14, v41
	v_cvt_pk_bf16_f32 v0, v0, s0
	global_store_short v[8:9], v0, off offset:192
	v_mul_f32_e32 v0, v14, v75
	v_cvt_pk_bf16_f32 v0, v0, s0
	global_store_short v[24:25], v0, off offset:192
	v_mul_f32_e32 v0, v14, v72
	v_cvt_pk_bf16_f32 v0, v0, s0
	global_store_short v[10:11], v0, off offset:192
	v_mul_f32_e32 v0, v14, v68
	v_cvt_pk_bf16_f32 v0, v0, s0
	global_store_short v[26:27], v0, off offset:192
	v_mul_f32_e32 v0, v14, v69
	v_cvt_pk_bf16_f32 v0, v0, s0
	global_store_short v[12:13], v0, off offset:192
	v_mul_f32_e32 v0, v14, v58
	v_cvt_pk_bf16_f32 v0, v0, s0
	global_store_short v[50:51], v0, off offset:192
	v_mul_f32_e32 v0, v14, v52
	v_mul_f32_e32 v29, v42, v29
	v_cvt_pk_bf16_f32 v0, v0, s0
	global_store_short v[48:49], v0, off offset:192
	v_mul_f32_e32 v0, v14, v29
	v_cvt_pk_bf16_f32 v0, v0, s0
	global_store_short v[30:31], v0, off offset:192
	v_mul_f32_e32 v0, v14, v15
	s_branch .LBB0_2240
